# v52 with the softmax-phase priority raise moved down to the P pack/permute block (exp/add at the lower level)
# speedup vs baseline: 1.0064x; 1.0032x over previous
.LBB0_1922:
	s_add_i32 s3, s0, -1
	s_add_i32 s2, s22, 0xffffa000
	s_and_b32 s2, s2, 0x6000
	v_add_u32_e32 v121, s2, v114
	v_add_u32_e32 v122, v121, v115
	v_add_u32_e32 v126, v121, v116
	ds_read_b128 v[122:125], v122 offset:4096
	ds_read_b128 v[132:135], v126 offset:4096
	v_add_u32_e32 v126, v121, v117
	v_add_u32_e32 v121, v121, v118
	s_lshl_b32 s2, s1, 14
	ds_read_b128 v[136:139], v126 offset:4096
	ds_read_b128 v[140:143], v121 offset:4096
	v_add_u32_e32 v121, s2, v106
	ds_read_b64_tr_b16 v[144:145], v121 offset:0
	ds_read_b64_tr_b16 v[146:147], v121 offset:0x800
	ds_read_b64_tr_b16 v[148:149], v121 offset:0x1000
	ds_read_b64_tr_b16 v[150:151], v121 offset:0x1800
	ds_read_b64_tr_b16 v[152:153], v121 offset:0x200
	ds_read_b64_tr_b16 v[154:155], v121 offset:0xa00
	ds_read_b64_tr_b16 v[156:157], v121 offset:0x1200
	ds_read_b64_tr_b16 v[158:159], v121 offset:0x1a00
	ds_read_b64_tr_b16 v[162:163], v121 offset:0x400
	ds_read_b64_tr_b16 v[164:165], v121 offset:0xc00
	ds_read_b64_tr_b16 v[166:167], v121 offset:0x1400
	ds_read_b64_tr_b16 v[168:169], v121 offset:0x1c00
	ds_read_b64_tr_b16 v[170:171], v121 offset:0x600
	ds_read_b64_tr_b16 v[172:173], v121 offset:0xe00
	ds_read_b64_tr_b16 v[174:175], v121 offset:0x1600
	ds_read_b64_tr_b16 v[176:177], v121 offset:0x1e00
	v_exp_f32_e32 v64, v64
	v_exp_f32_e32 v65, v65
	v_exp_f32_e32 v66, v66
	v_exp_f32_e32 v67, v67
	v_exp_f32_e32 v68, v68
	v_exp_f32_e32 v69, v69
	v_add_f32_e32 v126, v65, v64
	v_exp_f32_e32 v70, v70
	v_add_f32_e32 v126, v66, v126
	v_exp_f32_e32 v71, v71
	v_add_f32_e32 v126, v67, v126
	v_exp_f32_e32 v72, v72
	v_add_f32_e32 v126, v68, v126
	v_exp_f32_e32 v73, v73
	v_add_f32_e32 v126, v69, v126
	v_exp_f32_e32 v74, v74
	v_add_f32_e32 v126, v70, v126
	v_exp_f32_e32 v75, v75
	v_add_f32_e32 v126, v71, v126
	v_exp_f32_e32 v76, v76
	v_add_f32_e32 v126, v72, v126
	v_exp_f32_e32 v77, v77
	v_add_f32_e32 v126, v73, v126
	v_exp_f32_e32 v78, v78
	v_add_f32_e32 v126, v74, v126
	v_exp_f32_e32 v79, v79
	v_add_f32_e32 v126, v75, v126
	v_add_f32_e32 v126, v76, v126
	v_add_f32_e32 v126, v77, v126
	v_add_f32_e32 v126, v78, v126
	v_add_f32_e32 v126, v79, v126
	v_add_f32_e32 v120, v126, v120
	s_setprio 2
	v_cvt_pk_bf16_f32 v64, v64, v65
	v_cvt_pk_bf16_f32 v65, v66, v67
	v_cvt_pk_bf16_f32 v66, v68, v69
	v_cvt_pk_bf16_f32 v67, v70, v71
	v_cvt_pk_bf16_f32 v68, v72, v73
	v_cvt_pk_bf16_f32 v69, v74, v75
	v_cvt_pk_bf16_f32 v70, v76, v77
	v_cvt_pk_bf16_f32 v71, v78, v79
	s_nop 0
	v_permlane32_swap_b32_e32 v64, v66
	v_permlane32_swap_b32_e32 v65, v67
	v_permlane32_swap_b32_e32 v68, v70
	v_permlane32_swap_b32_e32 v69, v71
	s_waitcnt lgkmcnt(0)
	s_setprio 1
	v_mfma_f32_32x32x16_bf16 v[0:15], v[64:67], v[144:147], v[0:15]
	s_cmp_lt_i32 s3, s55
	s_cselect_b64 vcc, -1, 0
	s_cmp_ge_i32 s3, s97
	s_cselect_b64 s[74:75], -1, 0
	s_or_b64 s[74:75], vcc, s[74:75]
	s_and_b64 vcc, exec, s[74:75]
	v_mfma_f32_32x32x16_bf16 v[48:63], v[64:67], v[152:155], v[48:63]
	v_mfma_f32_32x32x16_bf16 v[32:47], v[64:67], v[162:165], v[32:47]
	v_mfma_f32_32x32x16_bf16 v[16:31], v[64:67], v[170:173], v[16:31]
	v_mfma_f32_32x32x16_bf16 v[0:15], v[68:71], v[148:151], v[0:15]
	v_mfma_f32_32x32x16_bf16 v[48:63], v[68:71], v[156:159], v[48:63]
	v_mfma_f32_32x32x16_bf16 v[32:47], v[68:71], v[166:169], v[32:47]
	v_mfma_f32_32x32x16_bf16 v[16:31], v[68:71], v[174:177], v[16:31]
	v_mfma_f32_32x32x16_bf16 v[64:79], v[122:125], v[92:95], 0
	v_mfma_f32_32x32x16_bf16 v[64:79], v[132:135], v[88:91], v[64:79]
	v_mfma_f32_32x32x16_bf16 v[64:79], v[136:139], v[84:87], v[64:79]
	v_mfma_f32_32x32x16_bf16 v[64:79], v[140:143], v[80:83], v[64:79]
	s_setprio 0
	v_add_u32_e32 v122, s7, v119
	s_cbranch_vccnz .LBB0_1924
	v_add_u32_e32 v138, 0x28908, v122
	v_add_u32_e32 v140, 0x28920, v122
	v_add_u32_e32 v142, 0x28928, v122
	v_add_u32_e32 v124, 0x28940, v122
	v_add_u32_e32 v126, 0x28948, v122
	v_add_u32_e32 v132, 0x28960, v122
	v_add_u32_e32 v134, 0x28968, v122
	v_add_u32_e32 v123, 0x28900, v122
	ds_read2_b32 v[124:125], v124 offset1:1
	ds_read2_b32 v[126:127], v126 offset1:1
	ds_read2_b32 v[132:133], v132 offset1:1
	ds_read2_b32 v[134:135], v134 offset1:1
	ds_read2_b32 v[136:137], v123 offset1:1
	ds_read2_b32 v[138:139], v138 offset1:1
	ds_read2_b32 v[140:141], v140 offset1:1
	ds_read2_b32 v[142:143], v142 offset1:1
	s_waitcnt lgkmcnt(0)
	v_pk_add_f32 v[78:79], v[78:79], v[134:135]
	v_pk_add_f32 v[76:77], v[76:77], v[132:133]
	v_pk_add_f32 v[74:75], v[74:75], v[126:127]
	v_pk_add_f32 v[72:73], v[72:73], v[124:125]
	v_pk_add_f32 v[70:71], v[70:71], v[142:143]
	v_pk_add_f32 v[68:69], v[68:69], v[140:141]
	v_pk_add_f32 v[66:67], v[66:67], v[138:139]
	v_pk_add_f32 v[64:65], v[64:65], v[136:137]
.LBB0_1924:
	s_add_i32 s3, s22, 0xffffc000
	s_and_b32 s3, s3, 0x6000
	v_add_u32_e32 v123, s3, v114
	v_add_u32_e32 v140, v123, v118
	v_add_u32_e32 v136, v123, v117
	v_add_u32_e32 v132, v123, v116
	v_add_u32_e32 v123, v123, v115
	ds_read_b128 v[124:127], v123
	ds_read_b128 v[132:135], v132
	ds_read_b128 v[136:139], v136
	ds_read_b128 v[140:143], v140
	ds_read_b64_tr_b16 v[144:145], v121 offset:0x2000
	ds_read_b64_tr_b16 v[146:147], v121 offset:0x2800
	ds_read_b64_tr_b16 v[148:149], v121 offset:0x3000
	ds_read_b64_tr_b16 v[150:151], v121 offset:0x3800
	ds_read_b64_tr_b16 v[152:153], v121 offset:0x2200
	ds_read_b64_tr_b16 v[154:155], v121 offset:0x2a00
	ds_read_b64_tr_b16 v[156:157], v121 offset:0x3200
	ds_read_b64_tr_b16 v[158:159], v121 offset:0x3a00
	ds_read_b64_tr_b16 v[162:163], v121 offset:0x2400
	ds_read_b64_tr_b16 v[164:165], v121 offset:0x2c00
	ds_read_b64_tr_b16 v[166:167], v121 offset:0x3400
	ds_read_b64_tr_b16 v[168:169], v121 offset:0x3c00
	ds_read_b64_tr_b16 v[170:171], v121 offset:0x2600
	ds_read_b64_tr_b16 v[172:173], v121 offset:0x2e00
	ds_read_b64_tr_b16 v[174:175], v121 offset:0x3600
	ds_read_b64_tr_b16 v[176:177], v121 offset:0x3e00
	v_exp_f32_e32 v64, v64
	v_exp_f32_e32 v65, v65
	v_exp_f32_e32 v66, v66
	v_exp_f32_e32 v67, v67
	v_exp_f32_e32 v68, v68
	v_exp_f32_e32 v69, v69
	v_add_f32_e32 v121, v65, v64
	v_exp_f32_e32 v70, v70
	v_add_f32_e32 v121, v66, v121
	v_exp_f32_e32 v71, v71
	v_add_f32_e32 v121, v67, v121
	v_exp_f32_e32 v72, v72
	v_add_f32_e32 v121, v68, v121
	v_exp_f32_e32 v73, v73
	v_add_f32_e32 v121, v69, v121
	v_exp_f32_e32 v74, v74
	v_add_f32_e32 v121, v70, v121
	v_exp_f32_e32 v75, v75
	v_add_f32_e32 v121, v71, v121
	v_exp_f32_e32 v76, v76
	v_add_f32_e32 v121, v72, v121
	v_exp_f32_e32 v77, v77
	v_add_f32_e32 v121, v73, v121
	v_exp_f32_e32 v78, v78
	v_add_f32_e32 v121, v74, v121
	v_exp_f32_e32 v79, v79
	v_add_f32_e32 v121, v75, v121
	v_add_f32_e32 v121, v76, v121
	v_add_f32_e32 v121, v77, v121
	v_add_f32_e32 v121, v78, v121
	v_add_f32_e32 v121, v79, v121
	v_add_f32_e32 v120, v120, v121
	s_setprio 2
	v_cvt_pk_bf16_f32 v64, v64, v65
	v_cvt_pk_bf16_f32 v65, v66, v67
	v_cvt_pk_bf16_f32 v66, v68, v69
	v_cvt_pk_bf16_f32 v67, v70, v71
	v_cvt_pk_bf16_f32 v68, v72, v73
	v_cvt_pk_bf16_f32 v69, v74, v75
	v_cvt_pk_bf16_f32 v70, v76, v77
	v_cvt_pk_bf16_f32 v71, v78, v79
	s_nop 0
	v_permlane32_swap_b32_e32 v64, v66
	v_permlane32_swap_b32_e32 v65, v67
	v_permlane32_swap_b32_e32 v68, v70
	v_permlane32_swap_b32_e32 v69, v71
	s_waitcnt lgkmcnt(0)
	s_setprio 1
	s_cmp_lt_u32 s33, 0x100
	s_cbranch_scc1 .Lstg_d0_mid_11
	s_waitcnt vmcnt(3)
	s_barrier

.LBB0_1930:
	s_mov_b64 s[96:97], 0xc00
	ds_read_b128 v[98:101], v107 offset:12288
	ds_read_b128 v[102:105], v108 offset:12288
	ds_read_b128 v[114:117], v109 offset:12288
	ds_read_b128 v[122:125], v110 offset:12288
	v_lshl_add_u32 v96, s64, 14, v106
	ds_read_b64_tr_b16 v[132:133], v96 offset:0
	ds_read_b64_tr_b16 v[134:135], v96 offset:0x800
	ds_read_b64_tr_b16 v[136:137], v96 offset:0x1000
	ds_read_b64_tr_b16 v[138:139], v96 offset:0x1800
	ds_read_b64_tr_b16 v[140:141], v96 offset:0x200
	ds_read_b64_tr_b16 v[142:143], v96 offset:0xa00
	ds_read_b64_tr_b16 v[144:145], v96 offset:0x1200
	ds_read_b64_tr_b16 v[146:147], v96 offset:0x1a00
	ds_read_b64_tr_b16 v[148:149], v96 offset:0x400
	ds_read_b64_tr_b16 v[150:151], v96 offset:0xc00
	ds_read_b64_tr_b16 v[152:153], v96 offset:0x1400
	ds_read_b64_tr_b16 v[154:155], v96 offset:0x1c00
	ds_read_b64_tr_b16 v[156:157], v96 offset:0x600
	ds_read_b64_tr_b16 v[158:159], v96 offset:0xe00
	ds_read_b64_tr_b16 v[162:163], v96 offset:0x1600
	ds_read_b64_tr_b16 v[164:165], v96 offset:0x1e00
	v_exp_f32_e32 v64, v64
	v_exp_f32_e32 v65, v65
	v_exp_f32_e32 v66, v66
	v_exp_f32_e32 v67, v67
	v_exp_f32_e32 v68, v68
	v_exp_f32_e32 v69, v69
	v_add_f32_e32 v97, v65, v64
	v_exp_f32_e32 v70, v70
	v_add_f32_e32 v97, v66, v97
	v_exp_f32_e32 v71, v71
	v_add_f32_e32 v97, v67, v97
	v_exp_f32_e32 v72, v72
	v_add_f32_e32 v97, v68, v97
	v_exp_f32_e32 v73, v73
	v_add_f32_e32 v97, v69, v97
	v_exp_f32_e32 v74, v74
	v_add_f32_e32 v97, v70, v97
	v_exp_f32_e32 v75, v75
	v_add_f32_e32 v97, v71, v97
	v_exp_f32_e32 v76, v76
	v_add_f32_e32 v97, v72, v97
	v_exp_f32_e32 v77, v77
	v_add_f32_e32 v97, v73, v97
	v_exp_f32_e32 v78, v78
	v_add_f32_e32 v97, v74, v97
	v_exp_f32_e32 v79, v79
	v_add_f32_e32 v97, v75, v97
	v_add_f32_e32 v97, v76, v97
	v_add_f32_e32 v97, v77, v97
	v_add_f32_e32 v97, v78, v97
	v_add_f32_e32 v97, v79, v97
	v_add_f32_e32 v97, v97, v120
	s_setprio 2
	v_cvt_pk_bf16_f32 v64, v64, v65
	v_cvt_pk_bf16_f32 v65, v66, v67
	v_cvt_pk_bf16_f32 v66, v68, v69
	v_cvt_pk_bf16_f32 v67, v70, v71
	v_cvt_pk_bf16_f32 v68, v72, v73
	v_cvt_pk_bf16_f32 v69, v74, v75
	v_cvt_pk_bf16_f32 v70, v76, v77
	v_cvt_pk_bf16_f32 v71, v78, v79
	s_nop 0
	v_permlane32_swap_b32_e32 v64, v66
	v_permlane32_swap_b32_e32 v65, v67
	v_permlane32_swap_b32_e32 v68, v70
	v_permlane32_swap_b32_e32 v69, v71
	s_waitcnt lgkmcnt(0)
	s_setprio 1
	v_mfma_f32_32x32x16_bf16 v[0:15], v[64:67], v[132:135], v[0:15]
	s_cmp_gt_i32 s55, 61
	s_cselect_b64 s[0:1], -1, 0
	s_cmp_lt_i32 s58, 62
	s_cselect_b64 s[2:3], -1, 0
	s_or_b64 s[0:1], s[0:1], s[2:3]
	s_and_b64 vcc, exec, s[0:1]
	v_mfma_f32_32x32x16_bf16 v[48:63], v[64:67], v[140:143], v[48:63]
	v_mfma_f32_32x32x16_bf16 v[32:47], v[64:67], v[148:151], v[32:47]
	v_mfma_f32_32x32x16_bf16 v[16:31], v[64:67], v[156:159], v[16:31]
	v_mfma_f32_32x32x16_bf16 v[0:15], v[68:71], v[136:139], v[0:15]
	v_mfma_f32_32x32x16_bf16 v[48:63], v[68:71], v[144:147], v[48:63]
	v_mfma_f32_32x32x16_bf16 v[32:47], v[68:71], v[152:155], v[32:47]
	v_mfma_f32_32x32x16_bf16 v[16:31], v[68:71], v[162:165], v[16:31]
	s_waitcnt lgkmcnt(0)
	v_mfma_f32_32x32x16_bf16 v[64:79], v[98:101], v[92:95], 0
	v_mfma_f32_32x32x16_bf16 v[64:79], v[102:105], v[88:91], v[64:79]
	v_mfma_f32_32x32x16_bf16 v[64:79], v[114:117], v[84:87], v[64:79]
	v_mfma_f32_32x32x16_bf16 v[64:79], v[122:125], v[80:83], v[64:79]
	s_setprio 0
	s_cbranch_vccnz .LBB0_1932
	v_sub_u32_e32 v98, 0xf40, v111
	v_lshlrev_b32_e32 v98, 2, v98
	v_add3_u32 v98, s88, v98, v130
	v_add_u32_e32 v114, 0x400, v98
	v_add_u32_e32 v116, 0x408, v98
	v_add_u32_e32 v118, 0x420, v98
	v_add_u32_e32 v120, 0x428, v98
	v_add_u32_e32 v99, 0x440, v98
	v_add_u32_e32 v100, 0x448, v98
	v_add_u32_e32 v102, 0x460, v98
	v_add_u32_e32 v104, 0x468, v98
	ds_read2_b32 v[98:99], v99 offset1:1
	ds_read2_b32 v[100:101], v100 offset1:1
	ds_read2_b32 v[102:103], v102 offset1:1
	ds_read2_b32 v[104:105], v104 offset1:1
	ds_read2_b32 v[114:115], v114 offset1:1
	ds_read2_b32 v[116:117], v116 offset1:1
	ds_read2_b32 v[118:119], v118 offset1:1
	ds_read2_b32 v[120:121], v120 offset1:1
	s_waitcnt lgkmcnt(0)
	v_pk_add_f32 v[78:79], v[78:79], v[104:105]
	v_pk_add_f32 v[76:77], v[76:77], v[102:103]
	v_pk_add_f32 v[74:75], v[74:75], v[100:101]
	v_pk_add_f32 v[72:73], v[72:73], v[98:99]
	v_pk_add_f32 v[70:71], v[70:71], v[120:121]
	v_pk_add_f32 v[68:69], v[68:69], v[118:119]
	v_pk_add_f32 v[66:67], v[66:67], v[116:117]
	v_pk_add_f32 v[64:65], v[64:65], v[114:115]
.LBB0_1932:
	s_movk_i32 s64, 0x70
	ds_read_b128 v[98:101], v107 offset:16384
	ds_read_b128 v[102:105], v108 offset:16384
	ds_read_b128 v[114:117], v109 offset:16384
	ds_read_b128 v[118:121], v110 offset:16384
	ds_read_b64_tr_b16 v[122:123], v96 offset:0x2000
	ds_read_b64_tr_b16 v[124:125], v96 offset:0x2800
	ds_read_b64_tr_b16 v[132:133], v96 offset:0x3000
	ds_read_b64_tr_b16 v[134:135], v96 offset:0x3800
	ds_read_b64_tr_b16 v[136:137], v96 offset:0x2200
	ds_read_b64_tr_b16 v[138:139], v96 offset:0x2a00
	ds_read_b64_tr_b16 v[140:141], v96 offset:0x3200
	ds_read_b64_tr_b16 v[142:143], v96 offset:0x3a00
	ds_read_b64_tr_b16 v[144:145], v96 offset:0x2400
	ds_read_b64_tr_b16 v[146:147], v96 offset:0x2c00
	ds_read_b64_tr_b16 v[148:149], v96 offset:0x3400
	ds_read_b64_tr_b16 v[150:151], v96 offset:0x3c00
	ds_read_b64_tr_b16 v[152:153], v96 offset:0x2600
	ds_read_b64_tr_b16 v[154:155], v96 offset:0x2e00
	ds_read_b64_tr_b16 v[156:157], v96 offset:0x3600
	ds_read_b64_tr_b16 v[158:159], v96 offset:0x3e00
	s_nop 5
	v_exp_f32_e32 v64, v64
	v_exp_f32_e32 v65, v65
	v_exp_f32_e32 v66, v66
	v_exp_f32_e32 v67, v67
	v_exp_f32_e32 v68, v68
	v_exp_f32_e32 v69, v69
	v_add_f32_e32 v96, v65, v64
	v_exp_f32_e32 v70, v70
	v_add_f32_e32 v96, v66, v96
	v_exp_f32_e32 v71, v71
	v_add_f32_e32 v96, v67, v96
	v_exp_f32_e32 v72, v72
	v_add_f32_e32 v96, v68, v96
	v_exp_f32_e32 v73, v73
	v_add_f32_e32 v96, v69, v96
	v_exp_f32_e32 v74, v74
	v_add_f32_e32 v96, v70, v96
	v_exp_f32_e32 v75, v75
	v_add_f32_e32 v96, v71, v96
	v_exp_f32_e32 v76, v76
	v_add_f32_e32 v96, v72, v96
	v_exp_f32_e32 v77, v77
	v_add_f32_e32 v96, v73, v96
	v_exp_f32_e32 v78, v78
	v_add_f32_e32 v96, v74, v96
	v_exp_f32_e32 v79, v79
	v_add_f32_e32 v96, v75, v96
	v_add_f32_e32 v96, v76, v96
	v_add_f32_e32 v96, v77, v96
	v_add_f32_e32 v96, v78, v96
	v_add_f32_e32 v96, v79, v96
	v_add_f32_e32 v96, v97, v96
	s_setprio 2
	v_cvt_pk_bf16_f32 v64, v64, v65
	v_cvt_pk_bf16_f32 v65, v66, v67
	v_cvt_pk_bf16_f32 v66, v68, v69
	v_cvt_pk_bf16_f32 v67, v70, v71
	v_cvt_pk_bf16_f32 v68, v72, v73
	v_cvt_pk_bf16_f32 v69, v74, v75
	v_cvt_pk_bf16_f32 v70, v76, v77
	v_cvt_pk_bf16_f32 v71, v78, v79
	s_nop 0
	v_permlane32_swap_b32_e32 v64, v66
	v_permlane32_swap_b32_e32 v65, v67
	v_permlane32_swap_b32_e32 v68, v70
	v_permlane32_swap_b32_e32 v69, v71
	s_waitcnt lgkmcnt(0)
	s_setprio 1
	s_cmp_lt_u32 s33, 0x100
	s_cbranch_scc1 .Lstg_d0_m61_13
	s_waitcnt vmcnt(0)
	s_barrier

.LBB0_1936:
	ds_read_b128 v[100:103], v107 offset:20480
	ds_read_b128 v[114:117], v108 offset:20480
	ds_read_b128 v[118:121], v109 offset:20480
	ds_read_b128 v[122:125], v110 offset:20480
	v_add_u32_e32 v98, 0x8000, v106
	ds_read_b64_tr_b16 v[132:133], v98 offset:0
	ds_read_b64_tr_b16 v[134:135], v98 offset:0x800
	ds_read_b64_tr_b16 v[136:137], v98 offset:0x1000
	ds_read_b64_tr_b16 v[138:139], v98 offset:0x1800
	ds_read_b64_tr_b16 v[140:141], v98 offset:0x200
	ds_read_b64_tr_b16 v[142:143], v98 offset:0xa00
	ds_read_b64_tr_b16 v[144:145], v98 offset:0x1200
	ds_read_b64_tr_b16 v[146:147], v98 offset:0x1a00
	ds_read_b64_tr_b16 v[148:149], v98 offset:0x400
	ds_read_b64_tr_b16 v[150:151], v98 offset:0xc00
	ds_read_b64_tr_b16 v[152:153], v98 offset:0x1400
	ds_read_b64_tr_b16 v[154:155], v98 offset:0x1c00
	ds_read_b64_tr_b16 v[156:157], v98 offset:0x600
	ds_read_b64_tr_b16 v[158:159], v98 offset:0xe00
	ds_read_b64_tr_b16 v[162:163], v98 offset:0x1600
	ds_read_b64_tr_b16 v[164:165], v98 offset:0x1e00
	v_exp_f32_e32 v64, v64
	v_exp_f32_e32 v65, v65
	v_exp_f32_e32 v66, v66
	v_exp_f32_e32 v67, v67
	v_exp_f32_e32 v68, v68
	v_exp_f32_e32 v69, v69
	v_add_f32_e32 v99, v65, v64
	v_exp_f32_e32 v70, v70
	v_add_f32_e32 v99, v66, v99
	v_exp_f32_e32 v71, v71
	v_add_f32_e32 v99, v67, v99
	v_exp_f32_e32 v72, v72
	v_add_f32_e32 v99, v68, v99
	v_exp_f32_e32 v73, v73
	v_add_f32_e32 v99, v69, v99
	v_exp_f32_e32 v74, v74
	v_add_f32_e32 v99, v70, v99
	v_exp_f32_e32 v75, v75
	v_add_f32_e32 v99, v71, v99
	v_exp_f32_e32 v76, v76
	v_add_f32_e32 v99, v72, v99
	v_exp_f32_e32 v77, v77
	v_add_f32_e32 v99, v73, v99
	v_exp_f32_e32 v78, v78
	v_add_f32_e32 v99, v74, v99
	v_exp_f32_e32 v79, v79
	v_add_f32_e32 v99, v75, v99
	v_add_f32_e32 v99, v76, v99
	v_add_f32_e32 v99, v77, v99
	v_add_f32_e32 v99, v78, v99
	v_add_f32_e32 v99, v79, v99
	v_add_f32_e32 v96, v99, v96
	s_setprio 2
	v_cvt_pk_bf16_f32 v64, v64, v65
	v_cvt_pk_bf16_f32 v65, v66, v67
	v_cvt_pk_bf16_f32 v66, v68, v69
	v_cvt_pk_bf16_f32 v67, v70, v71
	v_cvt_pk_bf16_f32 v68, v72, v73
	v_cvt_pk_bf16_f32 v69, v74, v75
	v_cvt_pk_bf16_f32 v70, v76, v77
	v_cvt_pk_bf16_f32 v71, v78, v79
	s_nop 0
	v_permlane32_swap_b32_e32 v64, v66
	v_permlane32_swap_b32_e32 v65, v67
	v_permlane32_swap_b32_e32 v68, v70
	v_permlane32_swap_b32_e32 v69, v71
	s_waitcnt lgkmcnt(0)
	s_setprio 1
	v_mfma_f32_32x32x16_bf16 v[0:15], v[64:67], v[132:135], v[0:15]
	s_and_b64 vcc, exec, s[2:3]
	v_mfma_f32_32x32x16_bf16 v[48:63], v[64:67], v[140:143], v[48:63]
	v_mfma_f32_32x32x16_bf16 v[32:47], v[64:67], v[148:151], v[32:47]
	v_mfma_f32_32x32x16_bf16 v[16:31], v[64:67], v[156:159], v[16:31]
	v_mfma_f32_32x32x16_bf16 v[0:15], v[68:71], v[136:139], v[0:15]
	v_mfma_f32_32x32x16_bf16 v[48:63], v[68:71], v[144:147], v[48:63]
	v_mfma_f32_32x32x16_bf16 v[32:47], v[68:71], v[152:155], v[32:47]
	v_mfma_f32_32x32x16_bf16 v[16:31], v[68:71], v[162:165], v[16:31]
	s_waitcnt lgkmcnt(0)
	v_mfma_f32_32x32x16_bf16 v[64:79], v[100:103], v[92:95], 0
	v_mfma_f32_32x32x16_bf16 v[64:79], v[114:117], v[88:91], v[64:79]
	v_mfma_f32_32x32x16_bf16 v[64:79], v[118:121], v[84:87], v[64:79]
	v_mfma_f32_32x32x16_bf16 v[64:79], v[122:125], v[80:83], v[64:79]
	s_setprio 0
	s_cbranch_vccnz .LBB0_1938
	v_add3_u32 v97, s88, v97, v130
	v_add_u32_e32 v118, 0x408, v97
	v_add_u32_e32 v120, 0x420, v97
	v_add_u32_e32 v122, 0x428, v97
	v_add_u32_e32 v100, 0x440, v97
	v_add_u32_e32 v102, 0x448, v97
	v_add_u32_e32 v104, 0x460, v97
	v_add_u32_e32 v99, 0x400, v97
	v_add_u32_e32 v97, 0x468, v97
	ds_read2_b32 v[100:101], v100 offset1:1
	ds_read2_b32 v[102:103], v102 offset1:1
	ds_read2_b32 v[104:105], v104 offset1:1
	ds_read2_b32 v[114:115], v97 offset1:1
	ds_read2_b32 v[116:117], v99 offset1:1
	ds_read2_b32 v[118:119], v118 offset1:1
	ds_read2_b32 v[120:121], v120 offset1:1
	ds_read2_b32 v[122:123], v122 offset1:1
	s_waitcnt lgkmcnt(0)
	v_pk_add_f32 v[78:79], v[78:79], v[114:115]
	v_pk_add_f32 v[76:77], v[76:77], v[104:105]
	v_pk_add_f32 v[74:75], v[74:75], v[102:103]
	v_pk_add_f32 v[72:73], v[72:73], v[100:101]
	v_pk_add_f32 v[70:71], v[70:71], v[122:123]
	v_pk_add_f32 v[68:69], v[68:69], v[120:121]
	v_pk_add_f32 v[66:67], v[66:67], v[118:119]
	v_pk_add_f32 v[64:65], v[64:65], v[116:117]
.LBB0_1938:
	ds_read_b128 v[100:103], v107 offset:24576
	ds_read_b128 v[114:117], v108 offset:24576
	ds_read_b128 v[118:121], v109 offset:24576
	ds_read_b128 v[122:125], v110 offset:24576
	ds_read_b64_tr_b16 v[132:133], v98 offset:0x2000
	ds_read_b64_tr_b16 v[134:135], v98 offset:0x2800
	ds_read_b64_tr_b16 v[136:137], v98 offset:0x3000
	ds_read_b64_tr_b16 v[138:139], v98 offset:0x3800
	ds_read_b64_tr_b16 v[140:141], v98 offset:0x2200
	ds_read_b64_tr_b16 v[142:143], v98 offset:0x2a00
	ds_read_b64_tr_b16 v[144:145], v98 offset:0x3200
	ds_read_b64_tr_b16 v[146:147], v98 offset:0x3a00
	ds_read_b64_tr_b16 v[148:149], v98 offset:0x2400
	ds_read_b64_tr_b16 v[150:151], v98 offset:0x2c00
	ds_read_b64_tr_b16 v[152:153], v98 offset:0x3400
	ds_read_b64_tr_b16 v[154:155], v98 offset:0x3c00
	ds_read_b64_tr_b16 v[156:157], v98 offset:0x2600
	ds_read_b64_tr_b16 v[158:159], v98 offset:0x2e00
	ds_read_b64_tr_b16 v[162:163], v98 offset:0x3600
	ds_read_b64_tr_b16 v[164:165], v98 offset:0x3e00
	s_nop 6
	v_exp_f32_e32 v64, v64
	v_exp_f32_e32 v65, v65
	v_exp_f32_e32 v66, v66
	v_exp_f32_e32 v67, v67
	v_exp_f32_e32 v68, v68
	v_exp_f32_e32 v69, v69
	v_add_f32_e32 v97, v65, v64
	v_exp_f32_e32 v70, v70
	v_add_f32_e32 v97, v66, v97
	v_exp_f32_e32 v71, v71
	v_add_f32_e32 v97, v67, v97
	v_exp_f32_e32 v72, v72
	v_add_f32_e32 v97, v68, v97
	v_exp_f32_e32 v73, v73
	v_add_f32_e32 v97, v69, v97
	v_exp_f32_e32 v74, v74
	v_add_f32_e32 v97, v70, v97
	v_exp_f32_e32 v75, v75
	v_add_f32_e32 v97, v71, v97
	v_exp_f32_e32 v76, v76
	v_add_f32_e32 v97, v72, v97
	v_exp_f32_e32 v77, v77
	v_add_f32_e32 v97, v73, v97
	v_exp_f32_e32 v78, v78
	v_add_f32_e32 v97, v74, v97
	v_exp_f32_e32 v79, v79
	v_add_f32_e32 v97, v75, v97
	v_add_f32_e32 v97, v76, v97
	v_add_f32_e32 v97, v77, v97
	v_add_f32_e32 v97, v78, v97
	v_add_f32_e32 v97, v79, v97
	v_add_f32_e32 v96, v96, v97
	s_setprio 2
	v_cvt_pk_bf16_f32 v64, v64, v65
	v_cvt_pk_bf16_f32 v65, v66, v67
	v_cvt_pk_bf16_f32 v66, v68, v69
	v_cvt_pk_bf16_f32 v67, v70, v71
	v_cvt_pk_bf16_f32 v68, v72, v73
	v_cvt_pk_bf16_f32 v69, v74, v75
	v_cvt_pk_bf16_f32 v70, v76, v77
	v_cvt_pk_bf16_f32 v71, v78, v79
	s_nop 0
	v_permlane32_swap_b32_e32 v64, v66
	v_permlane32_swap_b32_e32 v65, v67
	v_permlane32_swap_b32_e32 v68, v70
	v_permlane32_swap_b32_e32 v69, v71
	s_waitcnt lgkmcnt(0)
	s_setprio 1
	s_cmp_lt_u32 s33, 0x100
	s_cbranch_scc1 .Lstg_d0_m62_15
	s_waitcnt vmcnt(0)
	s_barrier

; DI void expsum(f32x16& p, float& l_reg, bf16x8& pa0, bf16x8& pa1) {
; #pragma unroll
;     for (int r = 0; r < 16; ++r) p[r] = __builtin_amdgcn_exp2f(p[r]);
;     float ps = 0.f;
; #pragma unroll
;     for (int r = 0; r < 16; ++r) ps += p[r];
;     l_reg += ps; asm volatile("" : "+v"(l_reg));
;     ...
;     ATT_PK4(p, 0, pa0); ATT_PK4(p, 8, pa1);
.LBB0_1942:
	ds_read_b128 v[98:101], v107 offset:28672
	ds_read_b128 v[102:105], v108 offset:28672
	ds_read_b128 v[112:115], v109 offset:28672
	ds_read_b128 v[108:111], v110 offset:28672
	ds_read_b64_tr_b16 v[116:117], v106 offset:0
	ds_read_b64_tr_b16 v[118:119], v106 offset:0x800
	ds_read_b64_tr_b16 v[120:121], v106 offset:0x1000
	ds_read_b64_tr_b16 v[122:123], v106 offset:0x1800
	ds_read_b64_tr_b16 v[124:125], v106 offset:0x200
	ds_read_b64_tr_b16 v[126:127], v106 offset:0xa00
	ds_read_b64_tr_b16 v[132:133], v106 offset:0x1200
	ds_read_b64_tr_b16 v[134:135], v106 offset:0x1a00
	ds_read_b64_tr_b16 v[136:137], v106 offset:0x400
	ds_read_b64_tr_b16 v[138:139], v106 offset:0xc00
	ds_read_b64_tr_b16 v[140:141], v106 offset:0x1400
	ds_read_b64_tr_b16 v[142:143], v106 offset:0x1c00
	ds_read_b64_tr_b16 v[144:145], v106 offset:0x600
	ds_read_b64_tr_b16 v[146:147], v106 offset:0xe00
	ds_read_b64_tr_b16 v[148:149], v106 offset:0x1600
	ds_read_b64_tr_b16 v[150:151], v106 offset:0x1e00
	v_exp_f32_e32 v64, v64
	v_exp_f32_e32 v65, v65
	v_exp_f32_e32 v66, v66
	v_exp_f32_e32 v67, v67
	v_exp_f32_e32 v68, v68
	v_exp_f32_e32 v69, v69
	v_add_f32_e32 v107, v65, v64
	v_exp_f32_e32 v70, v70
	v_add_f32_e32 v107, v66, v107
	v_exp_f32_e32 v71, v71
	v_add_f32_e32 v107, v67, v107
	v_exp_f32_e32 v72, v72
	v_add_f32_e32 v107, v68, v107
	v_exp_f32_e32 v73, v73
	v_add_f32_e32 v107, v69, v107
	v_exp_f32_e32 v74, v74
	v_add_f32_e32 v107, v70, v107
	v_exp_f32_e32 v75, v75
	v_add_f32_e32 v107, v71, v107
	v_exp_f32_e32 v76, v76
	v_add_f32_e32 v107, v72, v107
	v_exp_f32_e32 v77, v77
	v_add_f32_e32 v107, v73, v107
	v_exp_f32_e32 v78, v78
	v_add_f32_e32 v107, v74, v107
	v_exp_f32_e32 v79, v79
	v_add_f32_e32 v107, v75, v107
	v_add_f32_e32 v107, v76, v107
	v_add_f32_e32 v107, v77, v107
	v_add_f32_e32 v107, v78, v107
	v_add_f32_e32 v107, v79, v107
	v_add_f32_e32 v96, v107, v96
	s_setprio 2
	v_cvt_pk_bf16_f32 v64, v64, v65
	v_cvt_pk_bf16_f32 v65, v66, v67
	v_cvt_pk_bf16_f32 v66, v68, v69
	v_cvt_pk_bf16_f32 v67, v70, v71
	v_cvt_pk_bf16_f32 v68, v72, v73
	v_cvt_pk_bf16_f32 v69, v74, v75
	v_cvt_pk_bf16_f32 v70, v76, v77
	v_cvt_pk_bf16_f32 v71, v78, v79
	s_nop 0
	v_permlane32_swap_b32_e32 v64, v66
	v_permlane32_swap_b32_e32 v65, v67
	v_permlane32_swap_b32_e32 v68, v70
	v_permlane32_swap_b32_e32 v69, v71
	s_waitcnt lgkmcnt(0)
	s_setprio 1
	v_mfma_f32_32x32x16_bf16 v[0:15], v[64:67], v[116:119], v[0:15]
	s_and_b64 vcc, exec, s[2:3]
	v_mfma_f32_32x32x16_bf16 v[48:63], v[64:67], v[124:127], v[48:63]
	v_mfma_f32_32x32x16_bf16 v[32:47], v[64:67], v[136:139], v[32:47]
	v_mfma_f32_32x32x16_bf16 v[16:31], v[64:67], v[144:147], v[16:31]
	v_mfma_f32_32x32x16_bf16 v[0:15], v[68:71], v[120:123], v[0:15]
	v_mfma_f32_32x32x16_bf16 v[48:63], v[68:71], v[132:135], v[48:63]
	v_mfma_f32_32x32x16_bf16 v[32:47], v[68:71], v[140:143], v[32:47]
	v_mfma_f32_32x32x16_bf16 v[16:31], v[68:71], v[148:151], v[16:31]
	s_waitcnt lgkmcnt(0)
	v_mfma_f32_32x32x16_bf16 v[64:79], v[98:101], v[92:95], 0
	v_mfma_f32_32x32x16_bf16 v[64:79], v[102:105], v[88:91], v[64:79]
	v_mfma_f32_32x32x16_bf16 v[64:79], v[112:115], v[84:87], v[64:79]
	v_mfma_f32_32x32x16_bf16 v[64:79], v[108:111], v[80:83], v[64:79]
	s_setprio 0
	s_cbranch_vccnz .LBB0_1944
	v_add3_u32 v80, s88, v97, v130
	v_add_u32_e32 v88, 0x400, v80
	v_add_u32_e32 v90, 0x408, v80
	v_add_u32_e32 v92, 0x420, v80
	v_add_u32_e32 v94, 0x428, v80
	v_add_u32_e32 v81, 0x440, v80
	v_add_u32_e32 v82, 0x448, v80
	v_add_u32_e32 v84, 0x460, v80
	v_add_u32_e32 v86, 0x468, v80
	ds_read2_b32 v[80:81], v81 offset1:1
	ds_read2_b32 v[82:83], v82 offset1:1
	ds_read2_b32 v[84:85], v84 offset1:1
	ds_read2_b32 v[86:87], v86 offset1:1
	ds_read2_b32 v[88:89], v88 offset1:1
	ds_read2_b32 v[90:91], v90 offset1:1
	ds_read2_b32 v[92:93], v92 offset1:1
	ds_read2_b32 v[94:95], v94 offset1:1
	s_waitcnt lgkmcnt(0)
	v_pk_add_f32 v[78:79], v[78:79], v[86:87]
	v_pk_add_f32 v[76:77], v[76:77], v[84:85]
	v_pk_add_f32 v[74:75], v[74:75], v[82:83]
	v_pk_add_f32 v[72:73], v[72:73], v[80:81]
	v_pk_add_f32 v[70:71], v[70:71], v[94:95]
	v_pk_add_f32 v[68:69], v[68:69], v[92:93]
	v_pk_add_f32 v[66:67], v[66:67], v[90:91]
	v_pk_add_f32 v[64:65], v[64:65], v[88:89]
.LBB0_1944:
	s_lshl_b32 s0, s54, 2
	s_add_i32 s0, s0, 0
	s_add_i32 s0, s0, 0x24000
	ds_read_b64_tr_b16 v[80:81], v106 offset:0x2000
	ds_read_b64_tr_b16 v[82:83], v106 offset:0x2800
	ds_read_b64_tr_b16 v[84:85], v106 offset:0x3000
	ds_read_b64_tr_b16 v[86:87], v106 offset:0x3800
	ds_read_b64_tr_b16 v[88:89], v106 offset:0x2200
	ds_read_b64_tr_b16 v[90:91], v106 offset:0x2a00
	ds_read_b64_tr_b16 v[92:93], v106 offset:0x3200
	ds_read_b64_tr_b16 v[94:95], v106 offset:0x3a00
	ds_read_b64_tr_b16 v[98:99], v106 offset:0x2400
	ds_read_b64_tr_b16 v[100:101], v106 offset:0x2c00
	ds_read_b64_tr_b16 v[102:103], v106 offset:0x3400
	ds_read_b64_tr_b16 v[104:105], v106 offset:0x3c00
	ds_read_b64_tr_b16 v[108:109], v106 offset:0x2600
	ds_read_b64_tr_b16 v[110:111], v106 offset:0x2e00
	ds_read_b64_tr_b16 v[112:113], v106 offset:0x3600
	ds_read_b64_tr_b16 v[114:115], v106 offset:0x3e00
	s_nop 7
	v_exp_f32_e32 v97, v64
	v_exp_f32_e32 v65, v65
	v_exp_f32_e32 v106, v66
	v_exp_f32_e32 v67, v67
	v_exp_f32_e32 v68, v68
	v_exp_f32_e32 v69, v69
	v_add_f32_e32 v64, v65, v97
	v_exp_f32_e32 v70, v70
	v_add_f32_e32 v64, v106, v64
	v_exp_f32_e32 v71, v71
	v_add_f32_e32 v64, v67, v64
	v_exp_f32_e32 v72, v72
	v_add_f32_e32 v64, v68, v64
	v_exp_f32_e32 v73, v73
	v_add_f32_e32 v64, v69, v64
	v_exp_f32_e32 v74, v74
	v_add_f32_e32 v64, v70, v64
	v_exp_f32_e32 v75, v75
	v_add_f32_e32 v64, v71, v64
	v_exp_f32_e32 v76, v76
	v_add_f32_e32 v64, v72, v64
	v_exp_f32_e32 v77, v77
	v_add_f32_e32 v64, v73, v64
	v_exp_f32_e32 v78, v78
	v_add_f32_e32 v64, v74, v64
	v_exp_f32_e32 v79, v79
	v_add_f32_e32 v64, v75, v64
	v_add_f32_e32 v64, v76, v64
	v_add_f32_e32 v64, v77, v64
	v_add_f32_e32 v64, v78, v64
	v_add_f32_e32 v64, v79, v64
	v_add_f32_e32 v64, v96, v64
	s_setprio 2
	v_cvt_pk_bf16_f32 v66, v97, v65
	v_cvt_pk_bf16_f32 v67, v106, v67
	v_cvt_pk_bf16_f32 v68, v68, v69
	v_cvt_pk_bf16_f32 v69, v70, v71
	v_cvt_pk_bf16_f32 v70, v72, v73
	v_cvt_pk_bf16_f32 v71, v74, v75
	v_cvt_pk_bf16_f32 v72, v76, v77
	v_cvt_pk_bf16_f32 v73, v78, v79
	s_nop 0
	v_permlane32_swap_b32_e32 v66, v68
	v_permlane32_swap_b32_e32 v67, v69
	v_permlane32_swap_b32_e32 v70, v72
	v_permlane32_swap_b32_e32 v71, v73
	s_waitcnt lgkmcnt(0)
; template <int TAG = 0> DI int fresh_tid(int wv) { int l; asm volatile("v_mbcnt_lo_u32_b32 %0, -1, 0\n\tv_mbcnt_hi_u32_b32 %0, -1, %0 ; site %1" : "=v"(l) : "n"(TAG)); return wv * 64 + l; }
; DI unsigned short f2bf(float x) { unsigned u = __float_as_uint(x); u += 0x7fffu + ((u >> 16) & 1u); return (unsigned short)(u >> 16); }
; DI int crow(int r, int hi) { return (r & 3) + 8 * (r >> 2) + 4 * hi; }
; DI float swap_sum(float v) { auto rr = __builtin_amdgcn_permlane32_swap(__float_as_uint(v), __float_as_uint(v), false, false); return __uint_as_float(rr[0]) + __uint_as_float(rr[1]); }
; template <int DQK, int MODE, int LDQ, int LDK, int LDV> ...
;     ...
;     l_reg = swap_sum(l_reg);
;     { const int lane2 = fresh_tid<110 + MODE>(wv) & 63, r32 = lane2 & 31, hi = lane2 >> 5;
;     if (hi == 0) li_l[r32] = l_reg;
;     asm volatile("s_waitcnt lgkmcnt(0)" ::: "memory");
;     float s0v[MODE == 2 ? 16 : 1][4];
;     if constexpr (MODE == 2) {
; #pragma unroll
;         for (int r = 0; r < 16; ++r)
; #pragma unroll
;             for (int d0 = 0; d0 < 4; ++d0) s0v[r][d0] = S0[(size_t)(wid * 32 + crow(r, hi)) * 512 + d0 * 32 + r32];
;     }
; #pragma unroll
;     for (int r = 0; r < 16; ++r) { const int orow = wid * 32 + crow(r, hi); const float rl = __builtin_amdgcn_rcpf(li_l[crow(r, hi)]);
;         if constexpr (MODE == 0) {
; #pragma unroll
;             for (int d0 = 0; d0 < 4; ++d0) AOb[(size_t)orow * 1024 + d0 * 32 + r32] = f2bf(o[d0][r] * rl);
;         } else if constexpr (MODE == 1) {
; #pragma unroll
;             for (int d0 = 0; d0 < 4; ++d0) S0[(size_t)orow * 512 + d0 * 32 + r32] = o[d0][r] * rl;
	s_setprio 1
	v_mfma_f32_32x32x16_bf16 v[0:15], v[66:69], v[80:83], v[0:15]
	v_mfma_f32_32x32x16_bf16 v[48:63], v[66:69], v[88:91], v[48:63]
	v_mfma_f32_32x32x16_bf16 v[32:47], v[66:69], v[98:101], v[32:47]
	v_mfma_f32_32x32x16_bf16 v[16:31], v[66:69], v[108:111], v[16:31]
	v_mfma_f32_32x32x16_bf16 v[0:15], v[70:73], v[84:87], v[0:15]
	v_mfma_f32_32x32x16_bf16 v[48:63], v[70:73], v[92:95], v[48:63]
	v_mfma_f32_32x32x16_bf16 v[32:47], v[70:73], v[102:105], v[32:47]
	v_mfma_f32_32x32x16_bf16 v[16:31], v[70:73], v[112:115], v[16:31]
	s_setprio 0
	v_mbcnt_lo_u32_b32 v66, -1, 0
	v_mbcnt_hi_u32_b32 v66, -1, v66
	v_mov_b32_e32 v67, v64
	v_and_b32_e32 v65, 31, v66
	v_bfe_u32 v66, v66, 5, 1
	v_permlane32_swap_b32_e32 v64, v67
	v_cmp_eq_u32_e32 vcc, 0, v66
	s_and_saveexec_b64 s[2:3], vcc
	v_lshl_add_u32 v68, v65, 2, s0
	v_add_f32_e32 v64, v64, v67
	ds_write_b32 v68, v64
	s_or_b64 exec, exec, s[2:3]
	s_waitcnt lgkmcnt(0)
	v_lshl_add_u32 v68, v66, 4, s0
	ds_read_b128 v[70:73], v68
	ds_read_b128 v[74:77], v68 offset:32
	s_lshl_b64 s[58:59], s[40:41], 11
	v_readlane_b32 s1, v255, 2
	s_add_u32 s1, s1, s58
	v_readlane_b32 s2, v255, 0
	s_addc_u32 s2, s2, s59
	s_lshl_b32 s3, s87, 2
	s_waitcnt lgkmcnt(0)
	v_rcp_f32_e32 v69, v70
	s_add_u32 s54, s1, s3
	v_lshl_or_b32 v66, v66, 2, s94
	s_addc_u32 s55, s2, 0
	v_lshlrev_b32_e32 v130, 2, v65
	v_ashrrev_i32_e32 v67, 31, v66
	v_lshl_add_u64 v[64:65], s[54:55], 0, v[130:131]
	v_lshlrev_b64 v[78:79], 11, v[66:67]
	v_lshl_add_u64 v[78:79], v[64:65], 0, v[78:79]
	v_mul_f32_e32 v0, v0, v69
	global_store_dword v[78:79], v0, off
	v_mul_f32_e32 v0, v48, v69
	global_store_dword v[78:79], v0, off offset:128
	v_mul_f32_e32 v0, v32, v69
	global_store_dword v[78:79], v0, off offset:256
	v_mul_f32_e32 v0, v16, v69
	global_store_dword v[78:79], v0, off offset:384
	v_rcp_f32_e32 v0, v71
	v_or_b32_e32 v70, 1, v66
	v_ashrrev_i32_e32 v71, 31, v70
	v_lshlrev_b64 v[70:71], 11, v[70:71]
	v_lshl_add_u64 v[70:71], v[64:65], 0, v[70:71]
	v_mul_f32_e32 v1, v1, v0
	global_store_dword v[70:71], v1, off
	v_mul_f32_e32 v1, v49, v0
	global_store_dword v[70:71], v1, off offset:128
	v_mul_f32_e32 v1, v33, v0
	v_mul_f32_e32 v0, v17, v0
	v_rcp_f32_e32 v16, v72
	global_store_dword v[70:71], v0, off offset:384
	v_or_b32_e32 v0, 2, v66
	global_store_dword v[70:71], v1, off offset:256
	v_ashrrev_i32_e32 v1, 31, v0
	v_lshlrev_b64 v[0:1], 11, v[0:1]
	v_lshl_add_u64 v[0:1], v[64:65], 0, v[0:1]
	v_mul_f32_e32 v2, v2, v16
	global_store_dword v[0:1], v2, off
	v_mul_f32_e32 v2, v50, v16
	global_store_dword v[0:1], v2, off offset:128
	v_mul_f32_e32 v2, v34, v16
	global_store_dword v[0:1], v2, off offset:256
	v_mul_f32_e32 v2, v18, v16
	global_store_dword v[0:1], v2, off offset:384
	v_rcp_f32_e32 v2, v73
	v_or_b32_e32 v0, 3, v66
	v_ashrrev_i32_e32 v1, 31, v0
	v_lshlrev_b64 v[0:1], 11, v[0:1]
	v_lshl_add_u64 v[0:1], v[64:65], 0, v[0:1]
	v_mul_f32_e32 v3, v3, v2
	global_store_dword v[0:1], v3, off
	v_mul_f32_e32 v3, v51, v2
	global_store_dword v[0:1], v3, off offset:128
	v_mul_f32_e32 v3, v35, v2
	v_mul_f32_e32 v2, v19, v2
	global_store_dword v[0:1], v2, off offset:384
	v_rcp_f32_e32 v2, v74
	global_store_dword v[0:1], v3, off offset:256
	v_or_b32_e32 v0, 8, v66
	v_ashrrev_i32_e32 v1, 31, v0
	v_lshlrev_b64 v[0:1], 11, v[0:1]
	v_lshl_add_u64 v[0:1], v[64:65], 0, v[0:1]
	v_mul_f32_e32 v3, v4, v2
	global_store_dword v[0:1], v3, off
	v_mul_f32_e32 v3, v52, v2
	global_store_dword v[0:1], v3, off offset:128
	v_mul_f32_e32 v3, v36, v2
	v_mul_f32_e32 v2, v20, v2
	global_store_dword v[0:1], v2, off offset:384
	v_rcp_f32_e32 v2, v75
	global_store_dword v[0:1], v3, off offset:256
	v_or_b32_e32 v0, 9, v66
	v_ashrrev_i32_e32 v1, 31, v0
	v_lshlrev_b64 v[0:1], 11, v[0:1]
	v_lshl_add_u64 v[0:1], v[64:65], 0, v[0:1]
	v_mul_f32_e32 v3, v5, v2
	global_store_dword v[0:1], v3, off
	v_mul_f32_e32 v3, v53, v2
	global_store_dword v[0:1], v3, off offset:128
	v_mul_f32_e32 v3, v37, v2
	v_mul_f32_e32 v2, v21, v2
	global_store_dword v[0:1], v2, off offset:384
	v_rcp_f32_e32 v2, v76
	global_store_dword v[0:1], v3, off offset:256
	v_or_b32_e32 v0, 10, v66
	v_ashrrev_i32_e32 v1, 31, v0
	v_lshlrev_b64 v[0:1], 11, v[0:1]
	v_lshl_add_u64 v[0:1], v[64:65], 0, v[0:1]
	v_mul_f32_e32 v3, v6, v2
	global_store_dword v[0:1], v3, off
	v_mul_f32_e32 v3, v54, v2
	global_store_dword v[0:1], v3, off offset:128
	v_mul_f32_e32 v3, v38, v2
	v_mul_f32_e32 v2, v22, v2
	v_rcp_f32_e32 v6, v77
	global_store_dword v[0:1], v3, off offset:256
	global_store_dword v[0:1], v2, off offset:384
	v_or_b32_e32 v0, 11, v66
	v_ashrrev_i32_e32 v1, 31, v0
	v_lshlrev_b64 v[0:1], 11, v[0:1]
	v_lshl_add_u64 v[4:5], v[64:65], 0, v[0:1]
	v_mul_f32_e32 v0, v7, v6
	global_store_dword v[4:5], v0, off
	v_mul_f32_e32 v0, v55, v6
	global_store_dword v[4:5], v0, off offset:128
	v_mul_f32_e32 v0, v39, v6
	global_store_dword v[4:5], v0, off offset:256
	ds_read_b128 v[0:3], v68 offset:64
	v_mul_f32_e32 v6, v23, v6
	global_store_dword v[4:5], v6, off offset:384
	ds_read_b128 v[4:7], v68 offset:96
	v_or_b32_e32 v16, 16, v66
	s_waitcnt lgkmcnt(0)
; DI unsigned short f2bf(float x) { unsigned u = __float_as_uint(x); u += 0x7fffu + ((u >> 16) & 1u); return (unsigned short)(u >> 16); }
; DI int crow(int r, int hi) { return (r & 3) + 8 * (r >> 2) + 4 * hi; }
; template <int DQK, int MODE, int LDQ, int LDK, int LDV> ...
;     ...
;     for (int r = 0; r < 16; ++r) { const int orow = wid * 32 + crow(r, hi); const float rl = __builtin_amdgcn_rcpf(li_l[crow(r, hi)]);
;         if constexpr (MODE == 0) {
; #pragma unroll
;             for (int d0 = 0; d0 < 4; ++d0) AOb[(size_t)orow * 1024 + d0 * 32 + r32] = f2bf(o[d0][r] * rl);
;         } else if constexpr (MODE == 1) {
; #pragma unroll
;             for (int d0 = 0; d0 < 4; ++d0) S0[(size_t)orow * 512 + d0 * 32 + r32] = o[d0][r] * rl;
; DI void phase4(const Params& p, LAS unsigned char* lds, int wv) {
;     ...
;             __syncthreads();
	v_rcp_f32_e32 v0, v0
	v_ashrrev_i32_e32 v17, 31, v16
	v_lshlrev_b64 v[16:17], 11, v[16:17]
	v_lshl_add_u64 v[16:17], v[64:65], 0, v[16:17]
	v_mul_f32_e32 v8, v8, v0
	global_store_dword v[16:17], v8, off
	v_mul_f32_e32 v8, v56, v0
	global_store_dword v[16:17], v8, off offset:128
	v_mul_f32_e32 v8, v40, v0
	global_store_dword v[16:17], v8, off offset:256
	v_mul_f32_e32 v0, v24, v0
	v_rcp_f32_e32 v8, v1
	global_store_dword v[16:17], v0, off offset:384
	v_or_b32_e32 v0, 17, v66
	v_ashrrev_i32_e32 v1, 31, v0
	v_lshlrev_b64 v[0:1], 11, v[0:1]
	v_lshl_add_u64 v[0:1], v[64:65], 0, v[0:1]
	v_mul_f32_e32 v9, v9, v8
	global_store_dword v[0:1], v9, off
	v_mul_f32_e32 v9, v57, v8
	global_store_dword v[0:1], v9, off offset:128
	v_mul_f32_e32 v9, v41, v8
	v_mul_f32_e32 v8, v25, v8
	v_rcp_f32_e32 v2, v2
	global_store_dword v[0:1], v9, off offset:256
	global_store_dword v[0:1], v8, off offset:384
	v_or_b32_e32 v0, 18, v66
	v_ashrrev_i32_e32 v1, 31, v0
	v_lshlrev_b64 v[0:1], 11, v[0:1]
	v_lshl_add_u64 v[0:1], v[64:65], 0, v[0:1]
	v_mul_f32_e32 v8, v10, v2
	global_store_dword v[0:1], v8, off
	v_mul_f32_e32 v8, v58, v2
	global_store_dword v[0:1], v8, off offset:128
	v_mul_f32_e32 v8, v42, v2
	v_mul_f32_e32 v2, v26, v2
	global_store_dword v[0:1], v2, off offset:384
	v_rcp_f32_e32 v2, v3
	global_store_dword v[0:1], v8, off offset:256
	v_or_b32_e32 v0, 19, v66
	v_ashrrev_i32_e32 v1, 31, v0
	v_lshlrev_b64 v[0:1], 11, v[0:1]
	v_lshl_add_u64 v[0:1], v[64:65], 0, v[0:1]
	v_mul_f32_e32 v3, v11, v2
	global_store_dword v[0:1], v3, off
	v_mul_f32_e32 v3, v59, v2
	global_store_dword v[0:1], v3, off offset:128
	v_mul_f32_e32 v3, v43, v2
	v_mul_f32_e32 v2, v27, v2
	global_store_dword v[0:1], v2, off offset:384
	v_rcp_f32_e32 v2, v4
	global_store_dword v[0:1], v3, off offset:256
	v_or_b32_e32 v0, 24, v66
	v_ashrrev_i32_e32 v1, 31, v0
	v_lshlrev_b64 v[0:1], 11, v[0:1]
	v_lshl_add_u64 v[0:1], v[64:65], 0, v[0:1]
	v_mul_f32_e32 v3, v12, v2
	global_store_dword v[0:1], v3, off
	v_mul_f32_e32 v3, v60, v2
	global_store_dword v[0:1], v3, off offset:128
	v_mul_f32_e32 v3, v44, v2
	v_mul_f32_e32 v2, v28, v2
	global_store_dword v[0:1], v2, off offset:384
	v_rcp_f32_e32 v2, v5
	global_store_dword v[0:1], v3, off offset:256
	v_or_b32_e32 v0, 25, v66
	v_ashrrev_i32_e32 v1, 31, v0
	v_lshlrev_b64 v[0:1], 11, v[0:1]
	v_lshl_add_u64 v[0:1], v[64:65], 0, v[0:1]
	v_mul_f32_e32 v3, v13, v2
	global_store_dword v[0:1], v3, off
	v_mul_f32_e32 v3, v61, v2
	global_store_dword v[0:1], v3, off offset:128
	v_mul_f32_e32 v3, v45, v2
	v_mul_f32_e32 v2, v29, v2
	global_store_dword v[0:1], v2, off offset:384
	v_rcp_f32_e32 v2, v6
	global_store_dword v[0:1], v3, off offset:256
	v_or_b32_e32 v0, 26, v66
	v_ashrrev_i32_e32 v1, 31, v0
	v_lshlrev_b64 v[0:1], 11, v[0:1]
	v_lshl_add_u64 v[0:1], v[64:65], 0, v[0:1]
	v_mul_f32_e32 v3, v14, v2
	global_store_dword v[0:1], v3, off
	v_mul_f32_e32 v3, v62, v2
	global_store_dword v[0:1], v3, off offset:128
	v_mul_f32_e32 v3, v46, v2
	v_mul_f32_e32 v2, v30, v2
	global_store_dword v[0:1], v2, off offset:384
	v_rcp_f32_e32 v2, v7
	global_store_dword v[0:1], v3, off offset:256
	v_or_b32_e32 v0, 27, v66
	v_ashrrev_i32_e32 v1, 31, v0
	v_lshlrev_b64 v[0:1], 11, v[0:1]
	v_lshl_add_u64 v[0:1], v[64:65], 0, v[0:1]
	v_mul_f32_e32 v3, v15, v2
	global_store_dword v[0:1], v3, off
	v_mul_f32_e32 v3, v63, v2
	global_store_dword v[0:1], v3, off offset:128
	v_mul_f32_e32 v3, v47, v2
	v_mul_f32_e32 v2, v31, v2
	global_store_dword v[0:1], v3, off offset:256
	global_store_dword v[0:1], v2, off offset:384
	s_waitcnt vmcnt(0)
	s_barrier
; DI float bf2f(unsigned short h) { return __uint_as_float((unsigned)h << 16); }
; template <int DQK, int MODE, int LDQ, int LDK, int LDV> ...
;     ...
;     int kgo[NKP], vgo[2];
; #pragma unroll
;     for (int i = 0; i < NKP; ++i) { const int L = (wid + 8 * i) * 64 + lane, row = L / CPR, slot = L % CPR, cc = (slot & ~7) | ((slot & 7) ^ ((row >> 1) & 7)); kgo[i] = row * LDK + cc * 8; }
; #pragma unroll
;     for (int i = 0; i < 2; ++i) { const int L = (2 * wid + i) * 64 + lane, st = L >> 5, w5 = L & 31, kk = (st >> 2) * 8 + (w5 >> 2), c = (st & 3) * 32 + (w5 & 3) * 8;
;         const int k = (kk & ~0xC) | ((kk & 4) << 1) | ((kk & 8) >> 1); vgo[i] = k * LDV + c; }
;     ...
;     ATT_DMA_K(0); ATT_DMA_K(1); ATT_DMA_V(0, 0); ATT_DMA_K(2); ATT_DMA_V(1, 1);
;     bf16x8 qr[ND0];
;     { const bf16_t* Qw = Qb + (size_t)(wid * 32 + r32) * LDQ + hi * 8;
; #pragma unroll
;       for (int d0 = 0; d0 < ND0; ++d0) qr[d0] = *(const bf16x8*)(Qw + d0 * 16);
;       if constexpr (MODE == 0) {
;           float ss = 0.f;
; #pragma unroll
;           for (int d0 = 0; d0 < ND0; ++d0)
; #pragma unroll
;               for (int j = 0; j < 8; ++j) { const float f = bf2f((unsigned short)qr[d0][j]); ss += f * f; }
;           ss = swap_sum(ss);
;           const float rstd = rsqrtf(ss * (1.f / DQK) + EPS) * C;
; #pragma unroll
;           for (int d0 = 0; d0 < ND0; ++d0) { const float* g = gq + d0 * 16 + hi * 8;
;               { float f[8]; _Pragma("unroll") for (int j = 0; j < 8; ++j) f[j] = bf2f((unsigned short)qr[d0][j]) * rstd * g[j];
;                 u32x4 w = {cvtpk(f[0], f[1]), cvtpk(f[2], f[3]), cvtpk(f[4], f[5]), cvtpk(f[6], f[7])}; qr[d0] = __builtin_bit_cast(bf16x8, w); asm volatile("" ::: "memory"); } }
;       } }
;     const int qlo = q0 + wid * 32, qpos = qlo + r32;
;     const int tL = MODE == 0 ? 0 : (qlo >= 191 ? (qlo - 127) >> 6 : 0), tR = MODE == 0 ? NT : min(NT, (qlo + 222) >> 6);
;     float fL = 1.f, fR = 1.f; if constexpr (MODE != 0) { fL = __builtin_amdgcn_exp2f(bt[0]); fR = __builtin_amdgcn_exp2f(-bt[448]); }
;     ...
;     const int vbase = (int)(unsigned)(size_t)lds + V_OFF + v_rd_base(lane);
;     ...
;     constexpr int NDA = ND0 > 6 ? 6 : ND0;
;     ...
;     f32x16 pA, pB; bf16x8 pa0, pa1;
;     int v0 = 0, v1 = 1, v2 = 2;
;     ATT_TOP(NKP + 2);
;     { bf16x8 kf[NDA]; k_reads<DQK, 0, NDA>(kf, lds, 0, r32, hi); ATT_LGKM0(); qk_mma<0, NDA>(pA, kf, qr);
	v_mbcnt_lo_u32_b32 v7, -1, 0
	v_mbcnt_hi_u32_b32 v7, -1, v7
	s_mov_b64 s[4:5], 0x880
	v_add_u32_e32 v0, s33, v7
	v_bfe_u32 v4, v0, 2, 2
	v_readfirstlane_b32 s0, v0
	s_ashr_i32 s2, s0, 31
	s_ashr_i32 s1, s0, 6
	v_mov_b32_e32 v1, s0
	v_bfi_b32 v1, s63, v1, v7
	s_lshr_b32 s2, s2, 29
	v_add_u32_e32 v3, s2, v1
	s_lshl_b32 s2, s1, 7
	v_ashrrev_i32_e32 v9, 3, v3
	v_and_b32_e32 v3, 0x1ffffff8, v3
	s_ashr_i32 s3, s2, 4
	v_lshrrev_b32_e32 v0, 1, v0
	v_sub_u32_e32 v1, v1, v3
	v_lshrrev_b32_e32 v3, 1, v9
	v_lshlrev_b32_e32 v18, 3, v7
	s_and_b32 s2, s3, -16
	v_and_b32_e32 v6, 8, v0
	s_lshr_b32 s3, s3, 1
	v_bitop3_b32 v1, v3, v1, 7 bitop3:0x6c
	v_and_b32_e32 v3, 32, v7
	v_and_b32_e32 v5, 24, v18
	s_and_b32 s3, s3, 4
	v_or3_b32 v0, v6, v4, s2
	v_or_b32_e32 v10, v3, v5
	v_or_b32_e32 v0, s3, v0
	v_lshl_or_b32 v96, v0, 11, v10
	v_lshlrev_b32_e32 v0, 11, v9
	v_lshl_add_u32 v0, v1, 3, v0
	v_ashrrev_i32_e32 v1, 31, v0
	v_lshlrev_b64 v[10:11], 1, v[0:1]
	v_lshl_add_u64 v[12:13], s[46:47], 0, v[10:11]
	v_lshl_add_u64 v[12:13], v[12:13], 0, s[4:5]
	s_lshl_b32 s4, s1, 10
	s_add_i32 s94, s4, 0
	s_mov_b32 m0, s94
	v_lshl_add_u64 v[10:11], s[48:49], 0, v[10:11]
	s_mov_b64 s[4:5], 0x40080
	global_load_lds_dwordx4 v[12:13], off
	v_lshl_add_u64 v[12:13], v[10:11], 0, s[4:5]
	s_add_i32 m0, s94, 0x2000
	s_lshl_b32 s4, s1, 11
	v_ashrrev_i32_e32 v97, 31, v96
	global_load_lds_dwordx4 v[12:13], off
	s_add_i32 s6, s4, 0
	v_lshlrev_b64 v[12:13], 1, v[96:97]
	s_add_i32 s48, s6, 0x18000
	v_lshl_add_u64 v[14:15], s[46:47], 0, v[12:13]
	v_lshl_add_u64 v[16:17], v[14:15], 0, s[96:97]
	s_mov_b32 m0, s48
	s_mov_b64 s[4:5], 0xc80
	global_load_lds_dwordx4 v[16:17], off
	v_lshl_add_u64 v[14:15], v[14:15], 0, s[4:5]
	s_add_i32 m0, s6, 0x18400
	s_mov_b64 s[4:5], 0x80080
	v_or_b32_e32 v98, 64, v96
	global_load_lds_dwordx4 v[14:15], off
	v_lshl_add_u64 v[10:11], v[10:11], 0, s[4:5]
	s_add_i32 m0, s94, 0x4000
	v_ashrrev_i32_e32 v99, 31, v98
	global_load_lds_dwordx4 v[10:11], off
	s_add_i32 m0, s6, 0x1c000
	v_lshl_add_u64 v[10:11], s[52:53], 0, v[12:13]
	v_and_b32_e32 v2, 31, v7
	global_load_lds_dwordx4 v[10:11], off
	v_lshl_add_u64 v[10:11], v[98:99], 1, s[52:53]
	s_add_i32 m0, s6, 0x1c400
	s_lshl_b32 s46, s1, 5
	global_load_lds_dwordx4 v[10:11], off
	v_or_b32_e32 v10, s46, v2
	v_ashrrev_i32_e32 v11, 31, v10
	v_bfe_u32 v8, v7, 5, 1
	v_lshlrev_b64 v[10:11], 12, v[10:11]
	v_lshl_add_u64 v[10:11], s[44:45], 0, v[10:11]
	v_lshlrev_b32_e32 v130, 4, v8
	v_lshl_add_u64 v[10:11], v[10:11], 0, v[130:131]
	global_load_dwordx4 v[92:95], v[10:11], off offset:1152
	global_load_dwordx4 v[88:91], v[10:11], off offset:1184
	global_load_dwordx4 v[84:87], v[10:11], off offset:1216
	global_load_dwordx4 v[80:83], v[10:11], off offset:1248
	v_and_b32_e32 v11, 0x70, v18
	v_mov_b32_e32 v9, s88
	v_mov_b32_e32 v10, s81
	v_lshl_add_u32 v114, v2, 7, 0
	v_bitop3_b32 v115, v130, v18, s64 bitop3:0x78
	v_bitop3_b32 v117, v130, v11, 64 bitop3:0x36
	s_add_i32 s4, s46, s89
	ds_read_b32 v9, v9
	ds_read_b32 v10, v10
	s_waitcnt vmcnt(3)
	s_barrier
	v_add_u32_e32 v107, v114, v115
	v_bitop3_b32 v116, v130, v11, 32 bitop3:0x36
	v_add_u32_e32 v109, v114, v117
	v_bitop3_b32 v118, v130, v11, s65 bitop3:0x36
	s_add_i32 s5, s4, 0xffffff81
	v_add_u32_e32 v108, v114, v116
	ds_read_b128 v[12:15], v107
	ds_read_b128 v[16:19], v108
	v_add_u32_e32 v110, v114, v118
	ds_read_b128 v[20:23], v109
	ds_read_b128 v[24:27], v110
	s_ashr_i32 s5, s5, 6
	s_cmpk_gt_i32 s4, 0xbe
	v_or_b32_e32 v111, s4, v2
	s_cselect_b32 s47, s5, 0
	s_addk_i32 s4, 0xde
	s_ashr_i32 s45, s4, 6
	s_waitcnt lgkmcnt(0)
	s_waitcnt vmcnt(0) lgkmcnt(0)
	v_mfma_f32_32x32x16_bf16 v[64:79], v[12:15], v[92:95], 0
	s_cmp_gt_i32 s47, 0
	s_cselect_b64 s[4:5], -1, 0
	s_cmp_lt_i32 s45, 1
	s_cselect_b64 s[6:7], -1, 0
	s_or_b64 s[4:5], s[6:7], s[4:5]
	s_and_b64 vcc, exec, s[4:5]
	v_mfma_f32_32x32x16_bf16 v[64:79], v[16:19], v[88:91], v[64:79]
	v_mfma_f32_32x32x16_bf16 v[64:79], v[20:23], v[84:87], v[64:79]
	v_mfma_f32_32x32x16_bf16 v[64:79], v[24:27], v[80:83], v[64:79]
	s_cbranch_vccnz .LBB0_1948
	v_lshlrev_b32_e32 v8, 2, v8
	v_sub_u32_e32 v8, v8, v111
	v_lshl_add_u32 v8, v8, 2, s88
	ds_read2_b32 v[12:13], v8 offset0:240 offset1:241
	ds_read2_b32 v[14:15], v8 offset0:242 offset1:243
	ds_read2_b32 v[16:17], v8 offset0:248 offset1:249
	ds_read2_b32 v[18:19], v8 offset0:250 offset1:251
	ds_read2_b32 v[20:21], v8 offset0:224 offset1:225
	ds_read2_b32 v[22:23], v8 offset0:226 offset1:227
	ds_read2_b32 v[24:25], v8 offset0:232 offset1:233
	ds_read2_b32 v[26:27], v8 offset0:234 offset1:235
	s_waitcnt lgkmcnt(4)
	v_pk_add_f32 v[78:79], v[78:79], v[18:19]
	v_pk_add_f32 v[76:77], v[76:77], v[16:17]
	v_pk_add_f32 v[74:75], v[74:75], v[14:15]
	v_pk_add_f32 v[72:73], v[72:73], v[12:13]
	s_waitcnt lgkmcnt(0)
	v_pk_add_f32 v[70:71], v[70:71], v[26:27]
	v_pk_add_f32 v[68:69], v[68:69], v[24:25]
	v_pk_add_f32 v[66:67], v[66:67], v[22:23]
	v_pk_add_f32 v[64:65], v[64:65], v[20:21]

.LBB0_1953:
	s_add_i32 s3, s0, -1
	s_add_i32 s2, s22, 0xffffa000
	s_and_b32 s2, s2, 0x6000
	v_add_u32_e32 v121, s2, v114
	v_add_u32_e32 v122, v121, v115
	v_add_u32_e32 v126, v121, v116
	ds_read_b128 v[122:125], v122 offset:4096
	ds_read_b128 v[132:135], v126 offset:4096
	v_add_u32_e32 v126, v121, v117
	v_add_u32_e32 v121, v121, v118
	s_lshl_b32 s2, s23, 14
	ds_read_b128 v[136:139], v126 offset:4096
	ds_read_b128 v[140:143], v121 offset:4096
	v_add_u32_e32 v121, s2, v106
	ds_read_b64_tr_b16 v[144:145], v121 offset:0
	ds_read_b64_tr_b16 v[146:147], v121 offset:0x800
	ds_read_b64_tr_b16 v[148:149], v121 offset:0x1000
	ds_read_b64_tr_b16 v[150:151], v121 offset:0x1800
	ds_read_b64_tr_b16 v[152:153], v121 offset:0x200
	ds_read_b64_tr_b16 v[154:155], v121 offset:0xa00
	ds_read_b64_tr_b16 v[156:157], v121 offset:0x1200
	ds_read_b64_tr_b16 v[158:159], v121 offset:0x1a00
	ds_read_b64_tr_b16 v[162:163], v121 offset:0x400
	ds_read_b64_tr_b16 v[164:165], v121 offset:0xc00
	ds_read_b64_tr_b16 v[166:167], v121 offset:0x1400
	ds_read_b64_tr_b16 v[168:169], v121 offset:0x1c00
	ds_read_b64_tr_b16 v[170:171], v121 offset:0x600
	ds_read_b64_tr_b16 v[172:173], v121 offset:0xe00
	ds_read_b64_tr_b16 v[174:175], v121 offset:0x1600
	ds_read_b64_tr_b16 v[176:177], v121 offset:0x1e00
	v_exp_f32_e32 v64, v64
	v_exp_f32_e32 v65, v65
	v_exp_f32_e32 v66, v66
	v_exp_f32_e32 v67, v67
	v_exp_f32_e32 v68, v68
	v_exp_f32_e32 v69, v69
	v_add_f32_e32 v126, v65, v64
	v_exp_f32_e32 v70, v70
	v_add_f32_e32 v126, v66, v126
	v_exp_f32_e32 v71, v71
	v_add_f32_e32 v126, v67, v126
	v_exp_f32_e32 v72, v72
	v_add_f32_e32 v126, v68, v126
	v_exp_f32_e32 v73, v73
	v_add_f32_e32 v126, v69, v126
	v_exp_f32_e32 v74, v74
	v_add_f32_e32 v126, v70, v126
	v_exp_f32_e32 v75, v75
	v_add_f32_e32 v126, v71, v126
	v_exp_f32_e32 v76, v76
	v_add_f32_e32 v126, v72, v126
	v_exp_f32_e32 v77, v77
	v_add_f32_e32 v126, v73, v126
	v_exp_f32_e32 v78, v78
	v_add_f32_e32 v126, v74, v126
	v_exp_f32_e32 v79, v79
	v_add_f32_e32 v126, v75, v126
	v_add_f32_e32 v126, v76, v126
	v_add_f32_e32 v126, v77, v126
	v_add_f32_e32 v126, v78, v126
	v_add_f32_e32 v126, v79, v126
	v_add_f32_e32 v120, v126, v120
	s_setprio 2
	v_cvt_pk_bf16_f32 v64, v64, v65
	v_cvt_pk_bf16_f32 v65, v66, v67
	v_cvt_pk_bf16_f32 v66, v68, v69
	v_cvt_pk_bf16_f32 v67, v70, v71
	v_cvt_pk_bf16_f32 v68, v72, v73
	v_cvt_pk_bf16_f32 v69, v74, v75
	v_cvt_pk_bf16_f32 v70, v76, v77
	v_cvt_pk_bf16_f32 v71, v78, v79
	s_nop 0
	v_permlane32_swap_b32_e32 v64, v66
	v_permlane32_swap_b32_e32 v65, v67
	v_permlane32_swap_b32_e32 v68, v70
	v_permlane32_swap_b32_e32 v69, v71
	s_waitcnt lgkmcnt(0)
	s_setprio 1
	v_mfma_f32_32x32x16_bf16 v[0:15], v[64:67], v[144:147], v[0:15]
	s_cmp_lt_i32 s3, s47
	s_cselect_b64 s[74:75], -1, 0
	s_cmp_ge_i32 s3, s52
	s_cselect_b64 s[90:91], -1, 0
	s_or_b64 s[74:75], s[74:75], s[90:91]
	s_and_b64 vcc, exec, s[74:75]
	v_mfma_f32_32x32x16_bf16 v[48:63], v[64:67], v[152:155], v[48:63]
	v_mfma_f32_32x32x16_bf16 v[16:31], v[64:67], v[162:165], v[16:31]
	v_mfma_f32_32x32x16_bf16 v[32:47], v[64:67], v[170:173], v[32:47]
	v_mfma_f32_32x32x16_bf16 v[0:15], v[68:71], v[148:151], v[0:15]
	v_mfma_f32_32x32x16_bf16 v[48:63], v[68:71], v[156:159], v[48:63]
	v_mfma_f32_32x32x16_bf16 v[16:31], v[68:71], v[166:169], v[16:31]
	v_mfma_f32_32x32x16_bf16 v[32:47], v[68:71], v[174:177], v[32:47]
	v_mfma_f32_32x32x16_bf16 v[64:79], v[122:125], v[92:95], 0
	v_mfma_f32_32x32x16_bf16 v[64:79], v[132:135], v[88:91], v[64:79]
	v_mfma_f32_32x32x16_bf16 v[64:79], v[136:139], v[84:87], v[64:79]
	v_mfma_f32_32x32x16_bf16 v[64:79], v[140:143], v[80:83], v[64:79]
	s_setprio 0
	v_add_u32_e32 v122, s7, v119
	s_cbranch_vccnz .LBB0_1955
	v_add_u32_e32 v138, 0x28908, v122
	v_add_u32_e32 v140, 0x28920, v122
	v_add_u32_e32 v142, 0x28928, v122
	v_add_u32_e32 v124, 0x28940, v122
	v_add_u32_e32 v126, 0x28948, v122
	v_add_u32_e32 v132, 0x28960, v122
	v_add_u32_e32 v134, 0x28968, v122
	v_add_u32_e32 v123, 0x28900, v122
	ds_read2_b32 v[124:125], v124 offset1:1
	ds_read2_b32 v[126:127], v126 offset1:1
	ds_read2_b32 v[132:133], v132 offset1:1
	ds_read2_b32 v[134:135], v134 offset1:1
	ds_read2_b32 v[136:137], v123 offset1:1
	ds_read2_b32 v[138:139], v138 offset1:1
	ds_read2_b32 v[140:141], v140 offset1:1
	ds_read2_b32 v[142:143], v142 offset1:1
	s_waitcnt lgkmcnt(0)
	v_pk_add_f32 v[78:79], v[78:79], v[134:135]
	v_pk_add_f32 v[76:77], v[76:77], v[132:133]
	v_pk_add_f32 v[74:75], v[74:75], v[126:127]
	v_pk_add_f32 v[72:73], v[72:73], v[124:125]
	v_pk_add_f32 v[70:71], v[70:71], v[142:143]
	v_pk_add_f32 v[68:69], v[68:69], v[140:141]
	v_pk_add_f32 v[66:67], v[66:67], v[138:139]
	v_pk_add_f32 v[64:65], v[64:65], v[136:137]

.LBB0_1961:
	ds_read_b128 v[98:101], v107 offset:12288
	ds_read_b128 v[102:105], v108 offset:12288
	ds_read_b128 v[114:117], v109 offset:12288
	ds_read_b128 v[122:125], v110 offset:12288
	v_lshl_add_u32 v96, s49, 14, v106
	ds_read_b64_tr_b16 v[132:133], v96 offset:0
	ds_read_b64_tr_b16 v[134:135], v96 offset:0x800
	ds_read_b64_tr_b16 v[136:137], v96 offset:0x1000
	ds_read_b64_tr_b16 v[138:139], v96 offset:0x1800
	ds_read_b64_tr_b16 v[140:141], v96 offset:0x200
	ds_read_b64_tr_b16 v[142:143], v96 offset:0xa00
	ds_read_b64_tr_b16 v[144:145], v96 offset:0x1200
	ds_read_b64_tr_b16 v[146:147], v96 offset:0x1a00
	ds_read_b64_tr_b16 v[148:149], v96 offset:0x400
	ds_read_b64_tr_b16 v[150:151], v96 offset:0xc00
	ds_read_b64_tr_b16 v[152:153], v96 offset:0x1400
	ds_read_b64_tr_b16 v[154:155], v96 offset:0x1c00
	ds_read_b64_tr_b16 v[156:157], v96 offset:0x600
	ds_read_b64_tr_b16 v[158:159], v96 offset:0xe00
	ds_read_b64_tr_b16 v[162:163], v96 offset:0x1600
	ds_read_b64_tr_b16 v[164:165], v96 offset:0x1e00
	v_exp_f32_e32 v64, v64
	v_exp_f32_e32 v65, v65
	v_exp_f32_e32 v66, v66
	v_exp_f32_e32 v67, v67
	v_exp_f32_e32 v68, v68
	v_exp_f32_e32 v69, v69
	v_add_f32_e32 v97, v65, v64
	v_exp_f32_e32 v70, v70
	v_add_f32_e32 v97, v66, v97
	v_exp_f32_e32 v71, v71
	v_add_f32_e32 v97, v67, v97
	v_exp_f32_e32 v72, v72
	v_add_f32_e32 v97, v68, v97
	v_exp_f32_e32 v73, v73
	v_add_f32_e32 v97, v69, v97
	v_exp_f32_e32 v74, v74
	v_add_f32_e32 v97, v70, v97
	v_exp_f32_e32 v75, v75
	v_add_f32_e32 v97, v71, v97
	v_exp_f32_e32 v76, v76
	v_add_f32_e32 v97, v72, v97
	v_exp_f32_e32 v77, v77
	v_add_f32_e32 v97, v73, v97
	v_exp_f32_e32 v78, v78
	v_add_f32_e32 v97, v74, v97
	v_exp_f32_e32 v79, v79
	v_add_f32_e32 v97, v75, v97
	v_add_f32_e32 v97, v76, v97
	v_add_f32_e32 v97, v77, v97
	v_add_f32_e32 v97, v78, v97
	v_add_f32_e32 v97, v79, v97
	v_add_f32_e32 v97, v97, v120
	s_setprio 2
	v_cvt_pk_bf16_f32 v64, v64, v65
	v_cvt_pk_bf16_f32 v65, v66, v67
	v_cvt_pk_bf16_f32 v66, v68, v69
	v_cvt_pk_bf16_f32 v67, v70, v71
	v_cvt_pk_bf16_f32 v68, v72, v73
	v_cvt_pk_bf16_f32 v69, v74, v75
	v_cvt_pk_bf16_f32 v70, v76, v77
	v_cvt_pk_bf16_f32 v71, v78, v79
	s_nop 0
	v_permlane32_swap_b32_e32 v64, v66
	v_permlane32_swap_b32_e32 v65, v67
	v_permlane32_swap_b32_e32 v68, v70
	v_permlane32_swap_b32_e32 v69, v71
	s_waitcnt lgkmcnt(0)
	s_setprio 1
	v_mfma_f32_32x32x16_bf16 v[0:15], v[64:67], v[132:135], v[0:15]
	s_cmp_gt_i32 s47, 61
	s_cselect_b64 s[0:1], -1, 0
	s_cmp_lt_i32 s45, 62
	s_cselect_b64 s[2:3], -1, 0
	s_or_b64 s[0:1], s[0:1], s[2:3]
	s_and_b64 vcc, exec, s[0:1]
	v_mfma_f32_32x32x16_bf16 v[48:63], v[64:67], v[140:143], v[48:63]
	v_mfma_f32_32x32x16_bf16 v[16:31], v[64:67], v[148:151], v[16:31]
	v_mfma_f32_32x32x16_bf16 v[32:47], v[64:67], v[156:159], v[32:47]
	v_mfma_f32_32x32x16_bf16 v[0:15], v[68:71], v[136:139], v[0:15]
	v_mfma_f32_32x32x16_bf16 v[48:63], v[68:71], v[144:147], v[48:63]
	v_mfma_f32_32x32x16_bf16 v[16:31], v[68:71], v[152:155], v[16:31]
	v_mfma_f32_32x32x16_bf16 v[32:47], v[68:71], v[162:165], v[32:47]
	s_waitcnt lgkmcnt(0)
	v_mfma_f32_32x32x16_bf16 v[64:79], v[98:101], v[92:95], 0
	v_mfma_f32_32x32x16_bf16 v[64:79], v[102:105], v[88:91], v[64:79]
	v_mfma_f32_32x32x16_bf16 v[64:79], v[114:117], v[84:87], v[64:79]
	v_mfma_f32_32x32x16_bf16 v[64:79], v[122:125], v[80:83], v[64:79]
	s_setprio 0
	s_cbranch_vccnz .LBB0_1963
	v_sub_u32_e32 v98, 0xf40, v111
	v_lshlrev_b32_e32 v98, 2, v98
	v_add3_u32 v98, s88, v98, v130
	v_add_u32_e32 v114, 0x400, v98
	v_add_u32_e32 v116, 0x408, v98
	v_add_u32_e32 v118, 0x420, v98
	v_add_u32_e32 v120, 0x428, v98
	v_add_u32_e32 v99, 0x440, v98
	v_add_u32_e32 v100, 0x448, v98
	v_add_u32_e32 v102, 0x460, v98
	v_add_u32_e32 v104, 0x468, v98
	ds_read2_b32 v[98:99], v99 offset1:1
	ds_read2_b32 v[100:101], v100 offset1:1
	ds_read2_b32 v[102:103], v102 offset1:1
	ds_read2_b32 v[104:105], v104 offset1:1
	ds_read2_b32 v[114:115], v114 offset1:1
	ds_read2_b32 v[116:117], v116 offset1:1
	ds_read2_b32 v[118:119], v118 offset1:1
	ds_read2_b32 v[120:121], v120 offset1:1
	s_waitcnt lgkmcnt(0)
	v_pk_add_f32 v[78:79], v[78:79], v[104:105]
	v_pk_add_f32 v[76:77], v[76:77], v[102:103]
	v_pk_add_f32 v[74:75], v[74:75], v[100:101]
	v_pk_add_f32 v[72:73], v[72:73], v[98:99]
	v_pk_add_f32 v[70:71], v[70:71], v[120:121]
	v_pk_add_f32 v[68:69], v[68:69], v[118:119]
	v_pk_add_f32 v[66:67], v[66:67], v[116:117]
	v_pk_add_f32 v[64:65], v[64:65], v[114:115]
.LBB0_1963:
	ds_read_b128 v[98:101], v107 offset:16384
	ds_read_b128 v[102:105], v108 offset:16384
	ds_read_b128 v[114:117], v109 offset:16384
	ds_read_b128 v[118:121], v110 offset:16384
	ds_read_b64_tr_b16 v[122:123], v96 offset:0x2000
	ds_read_b64_tr_b16 v[124:125], v96 offset:0x2800
	ds_read_b64_tr_b16 v[132:133], v96 offset:0x3000
	ds_read_b64_tr_b16 v[134:135], v96 offset:0x3800
	ds_read_b64_tr_b16 v[136:137], v96 offset:0x2200
	ds_read_b64_tr_b16 v[138:139], v96 offset:0x2a00
	ds_read_b64_tr_b16 v[140:141], v96 offset:0x3200
	ds_read_b64_tr_b16 v[142:143], v96 offset:0x3a00
	ds_read_b64_tr_b16 v[144:145], v96 offset:0x2400
	ds_read_b64_tr_b16 v[146:147], v96 offset:0x2c00
	ds_read_b64_tr_b16 v[148:149], v96 offset:0x3400
	ds_read_b64_tr_b16 v[150:151], v96 offset:0x3c00
	ds_read_b64_tr_b16 v[152:153], v96 offset:0x2600
	ds_read_b64_tr_b16 v[154:155], v96 offset:0x2e00
	ds_read_b64_tr_b16 v[156:157], v96 offset:0x3600
	ds_read_b64_tr_b16 v[158:159], v96 offset:0x3e00
	s_nop 6
	v_exp_f32_e32 v64, v64
	v_exp_f32_e32 v65, v65
	v_exp_f32_e32 v66, v66
	v_exp_f32_e32 v67, v67
	v_exp_f32_e32 v68, v68
	v_exp_f32_e32 v69, v69
	v_add_f32_e32 v96, v65, v64
	v_exp_f32_e32 v70, v70
	v_add_f32_e32 v96, v66, v96
	v_exp_f32_e32 v71, v71
	v_add_f32_e32 v96, v67, v96
	v_exp_f32_e32 v72, v72
	v_add_f32_e32 v96, v68, v96
	v_exp_f32_e32 v73, v73
	v_add_f32_e32 v96, v69, v96
	v_exp_f32_e32 v74, v74
	v_add_f32_e32 v96, v70, v96
	v_exp_f32_e32 v75, v75
	v_add_f32_e32 v96, v71, v96
	v_exp_f32_e32 v76, v76
	v_add_f32_e32 v96, v72, v96
	v_exp_f32_e32 v77, v77
	v_add_f32_e32 v96, v73, v96
	v_exp_f32_e32 v78, v78
	v_add_f32_e32 v96, v74, v96
	v_exp_f32_e32 v79, v79
	v_add_f32_e32 v96, v75, v96
	v_add_f32_e32 v96, v76, v96
	v_add_f32_e32 v96, v77, v96
	v_add_f32_e32 v96, v78, v96
	v_add_f32_e32 v96, v79, v96
	v_add_f32_e32 v96, v97, v96
	s_setprio 2
	v_cvt_pk_bf16_f32 v64, v64, v65
	v_cvt_pk_bf16_f32 v65, v66, v67
	v_cvt_pk_bf16_f32 v66, v68, v69
	v_cvt_pk_bf16_f32 v67, v70, v71
	v_cvt_pk_bf16_f32 v68, v72, v73
	v_cvt_pk_bf16_f32 v69, v74, v75
	v_cvt_pk_bf16_f32 v70, v76, v77
	v_cvt_pk_bf16_f32 v71, v78, v79
	s_nop 0
	v_permlane32_swap_b32_e32 v64, v66
	v_permlane32_swap_b32_e32 v65, v67
	v_permlane32_swap_b32_e32 v68, v70
	v_permlane32_swap_b32_e32 v69, v71
	s_waitcnt lgkmcnt(0)
	s_setprio 1
	s_cmp_lt_u32 s33, 0x100
	s_cbranch_scc1 .Lstg_d1_m61_21
	s_waitcnt vmcnt(0)
	s_barrier

.LBB0_1967:
	ds_read_b128 v[100:103], v107 offset:20480
	ds_read_b128 v[114:117], v108 offset:20480
	ds_read_b128 v[118:121], v109 offset:20480
	ds_read_b128 v[122:125], v110 offset:20480
	v_add_u32_e32 v98, 0x8000, v106
	ds_read_b64_tr_b16 v[132:133], v98 offset:0
	ds_read_b64_tr_b16 v[134:135], v98 offset:0x800
	ds_read_b64_tr_b16 v[136:137], v98 offset:0x1000
	ds_read_b64_tr_b16 v[138:139], v98 offset:0x1800
	ds_read_b64_tr_b16 v[140:141], v98 offset:0x200
	ds_read_b64_tr_b16 v[142:143], v98 offset:0xa00
	ds_read_b64_tr_b16 v[144:145], v98 offset:0x1200
	ds_read_b64_tr_b16 v[146:147], v98 offset:0x1a00
	ds_read_b64_tr_b16 v[148:149], v98 offset:0x400
	ds_read_b64_tr_b16 v[150:151], v98 offset:0xc00
	ds_read_b64_tr_b16 v[152:153], v98 offset:0x1400
	ds_read_b64_tr_b16 v[154:155], v98 offset:0x1c00
	ds_read_b64_tr_b16 v[156:157], v98 offset:0x600
	ds_read_b64_tr_b16 v[158:159], v98 offset:0xe00
	ds_read_b64_tr_b16 v[162:163], v98 offset:0x1600
	ds_read_b64_tr_b16 v[164:165], v98 offset:0x1e00
	v_exp_f32_e32 v64, v64
	v_exp_f32_e32 v65, v65
	v_exp_f32_e32 v66, v66
	v_exp_f32_e32 v67, v67
	v_exp_f32_e32 v68, v68
	v_exp_f32_e32 v69, v69
	v_add_f32_e32 v99, v65, v64
	v_exp_f32_e32 v70, v70
	v_add_f32_e32 v99, v66, v99
	v_exp_f32_e32 v71, v71
	v_add_f32_e32 v99, v67, v99
	v_exp_f32_e32 v72, v72
	v_add_f32_e32 v99, v68, v99
	v_exp_f32_e32 v73, v73
	v_add_f32_e32 v99, v69, v99
	v_exp_f32_e32 v74, v74
	v_add_f32_e32 v99, v70, v99
	v_exp_f32_e32 v75, v75
	v_add_f32_e32 v99, v71, v99
	v_exp_f32_e32 v76, v76
	v_add_f32_e32 v99, v72, v99
	v_exp_f32_e32 v77, v77
	v_add_f32_e32 v99, v73, v99
	v_exp_f32_e32 v78, v78
	v_add_f32_e32 v99, v74, v99
	v_exp_f32_e32 v79, v79
	v_add_f32_e32 v99, v75, v99
	v_add_f32_e32 v99, v76, v99
	v_add_f32_e32 v99, v77, v99
	v_add_f32_e32 v99, v78, v99
	v_add_f32_e32 v99, v79, v99
	v_add_f32_e32 v96, v99, v96
	s_setprio 2
	v_cvt_pk_bf16_f32 v64, v64, v65
	v_cvt_pk_bf16_f32 v65, v66, v67
	v_cvt_pk_bf16_f32 v66, v68, v69
	v_cvt_pk_bf16_f32 v67, v70, v71
	v_cvt_pk_bf16_f32 v68, v72, v73
	v_cvt_pk_bf16_f32 v69, v74, v75
	v_cvt_pk_bf16_f32 v70, v76, v77
	v_cvt_pk_bf16_f32 v71, v78, v79
	s_nop 0
	v_permlane32_swap_b32_e32 v64, v66
	v_permlane32_swap_b32_e32 v65, v67
	v_permlane32_swap_b32_e32 v68, v70
	v_permlane32_swap_b32_e32 v69, v71
	s_waitcnt lgkmcnt(0)
	s_setprio 1
	v_mfma_f32_32x32x16_bf16 v[0:15], v[64:67], v[132:135], v[0:15]
	s_and_b64 vcc, exec, s[2:3]
	v_mfma_f32_32x32x16_bf16 v[48:63], v[64:67], v[140:143], v[48:63]
	v_mfma_f32_32x32x16_bf16 v[16:31], v[64:67], v[148:151], v[16:31]
	v_mfma_f32_32x32x16_bf16 v[32:47], v[64:67], v[156:159], v[32:47]
	v_mfma_f32_32x32x16_bf16 v[0:15], v[68:71], v[136:139], v[0:15]
	v_mfma_f32_32x32x16_bf16 v[48:63], v[68:71], v[144:147], v[48:63]
	v_mfma_f32_32x32x16_bf16 v[16:31], v[68:71], v[152:155], v[16:31]
	v_mfma_f32_32x32x16_bf16 v[32:47], v[68:71], v[162:165], v[32:47]
	s_waitcnt lgkmcnt(0)
	v_mfma_f32_32x32x16_bf16 v[64:79], v[100:103], v[92:95], 0
	v_mfma_f32_32x32x16_bf16 v[64:79], v[114:117], v[88:91], v[64:79]
	v_mfma_f32_32x32x16_bf16 v[64:79], v[118:121], v[84:87], v[64:79]
	v_mfma_f32_32x32x16_bf16 v[64:79], v[122:125], v[80:83], v[64:79]
	s_setprio 0
	s_cbranch_vccnz .LBB0_1969
	v_add3_u32 v97, s88, v97, v130
	v_add_u32_e32 v118, 0x408, v97
	v_add_u32_e32 v120, 0x420, v97
	v_add_u32_e32 v122, 0x428, v97
	v_add_u32_e32 v100, 0x440, v97
	v_add_u32_e32 v102, 0x448, v97
	v_add_u32_e32 v104, 0x460, v97
	v_add_u32_e32 v99, 0x400, v97
	v_add_u32_e32 v97, 0x468, v97
	ds_read2_b32 v[100:101], v100 offset1:1
	ds_read2_b32 v[102:103], v102 offset1:1
	ds_read2_b32 v[104:105], v104 offset1:1
	ds_read2_b32 v[114:115], v97 offset1:1
	ds_read2_b32 v[116:117], v99 offset1:1
	ds_read2_b32 v[118:119], v118 offset1:1
	ds_read2_b32 v[120:121], v120 offset1:1
	ds_read2_b32 v[122:123], v122 offset1:1
	s_waitcnt lgkmcnt(0)
	v_pk_add_f32 v[78:79], v[78:79], v[114:115]
	v_pk_add_f32 v[76:77], v[76:77], v[104:105]
	v_pk_add_f32 v[74:75], v[74:75], v[102:103]
	v_pk_add_f32 v[72:73], v[72:73], v[100:101]
	v_pk_add_f32 v[70:71], v[70:71], v[122:123]
	v_pk_add_f32 v[68:69], v[68:69], v[120:121]
	v_pk_add_f32 v[66:67], v[66:67], v[118:119]
	v_pk_add_f32 v[64:65], v[64:65], v[116:117]

; DI void expsum(f32x16& p, float& l_reg, bf16x8& pa0, bf16x8& pa1) {
; #pragma unroll
;     for (int r = 0; r < 16; ++r) p[r] = __builtin_amdgcn_exp2f(p[r]);
;     float ps = 0.f;
; #pragma unroll
;     for (int r = 0; r < 16; ++r) ps += p[r];
;     l_reg += ps; asm volatile("" : "+v"(l_reg));
;     ...
;     ATT_PK4(p, 0, pa0); ATT_PK4(p, 8, pa1);
.LBB0_1973:
	ds_read_b128 v[98:101], v107 offset:28672
	ds_read_b128 v[102:105], v108 offset:28672
	ds_read_b128 v[112:115], v109 offset:28672
	ds_read_b128 v[108:111], v110 offset:28672
	ds_read_b64_tr_b16 v[116:117], v106 offset:0
	ds_read_b64_tr_b16 v[118:119], v106 offset:0x800
	ds_read_b64_tr_b16 v[120:121], v106 offset:0x1000
	ds_read_b64_tr_b16 v[122:123], v106 offset:0x1800
	ds_read_b64_tr_b16 v[124:125], v106 offset:0x200
	ds_read_b64_tr_b16 v[126:127], v106 offset:0xa00
	ds_read_b64_tr_b16 v[132:133], v106 offset:0x1200
	ds_read_b64_tr_b16 v[134:135], v106 offset:0x1a00
	ds_read_b64_tr_b16 v[136:137], v106 offset:0x400
	ds_read_b64_tr_b16 v[138:139], v106 offset:0xc00
	ds_read_b64_tr_b16 v[140:141], v106 offset:0x1400
	ds_read_b64_tr_b16 v[142:143], v106 offset:0x1c00
	ds_read_b64_tr_b16 v[144:145], v106 offset:0x600
	ds_read_b64_tr_b16 v[146:147], v106 offset:0xe00
	ds_read_b64_tr_b16 v[148:149], v106 offset:0x1600
	ds_read_b64_tr_b16 v[150:151], v106 offset:0x1e00
	v_exp_f32_e32 v64, v64
	v_exp_f32_e32 v65, v65
	v_exp_f32_e32 v66, v66
	v_exp_f32_e32 v67, v67
	v_exp_f32_e32 v68, v68
	v_exp_f32_e32 v69, v69
	v_add_f32_e32 v107, v65, v64
	v_exp_f32_e32 v70, v70
	v_add_f32_e32 v107, v66, v107
	v_exp_f32_e32 v71, v71
	v_add_f32_e32 v107, v67, v107
	v_exp_f32_e32 v72, v72
	v_add_f32_e32 v107, v68, v107
	v_exp_f32_e32 v73, v73
	v_add_f32_e32 v107, v69, v107
	v_exp_f32_e32 v74, v74
	v_add_f32_e32 v107, v70, v107
	v_exp_f32_e32 v75, v75
	v_add_f32_e32 v107, v71, v107
	v_exp_f32_e32 v76, v76
	v_add_f32_e32 v107, v72, v107
	v_exp_f32_e32 v77, v77
	v_add_f32_e32 v107, v73, v107
	v_exp_f32_e32 v78, v78
	v_add_f32_e32 v107, v74, v107
	v_exp_f32_e32 v79, v79
	v_add_f32_e32 v107, v75, v107
	v_add_f32_e32 v107, v76, v107
	v_add_f32_e32 v107, v77, v107
	v_add_f32_e32 v107, v78, v107
	v_add_f32_e32 v107, v79, v107
	v_add_f32_e32 v96, v107, v96
	s_setprio 2
	v_cvt_pk_bf16_f32 v64, v64, v65
	v_cvt_pk_bf16_f32 v65, v66, v67
	v_cvt_pk_bf16_f32 v66, v68, v69
	v_cvt_pk_bf16_f32 v67, v70, v71
	v_cvt_pk_bf16_f32 v68, v72, v73
	v_cvt_pk_bf16_f32 v69, v74, v75
	v_cvt_pk_bf16_f32 v70, v76, v77
	v_cvt_pk_bf16_f32 v71, v78, v79
	s_nop 0
	v_permlane32_swap_b32_e32 v64, v66
	v_permlane32_swap_b32_e32 v65, v67
	v_permlane32_swap_b32_e32 v68, v70
	v_permlane32_swap_b32_e32 v69, v71
	s_waitcnt lgkmcnt(0)
	s_setprio 1
	v_mfma_f32_32x32x16_bf16 v[0:15], v[64:67], v[116:119], v[0:15]
	s_and_b64 vcc, exec, s[2:3]
	v_mfma_f32_32x32x16_bf16 v[48:63], v[64:67], v[124:127], v[48:63]
	v_mfma_f32_32x32x16_bf16 v[16:31], v[64:67], v[136:139], v[16:31]
	v_mfma_f32_32x32x16_bf16 v[32:47], v[64:67], v[144:147], v[32:47]
	v_mfma_f32_32x32x16_bf16 v[0:15], v[68:71], v[120:123], v[0:15]
	v_mfma_f32_32x32x16_bf16 v[48:63], v[68:71], v[132:135], v[48:63]
	v_mfma_f32_32x32x16_bf16 v[16:31], v[68:71], v[140:143], v[16:31]
	v_mfma_f32_32x32x16_bf16 v[32:47], v[68:71], v[148:151], v[32:47]
	s_waitcnt lgkmcnt(0)
	v_mfma_f32_32x32x16_bf16 v[64:79], v[98:101], v[92:95], 0
	v_mfma_f32_32x32x16_bf16 v[64:79], v[102:105], v[88:91], v[64:79]
	v_mfma_f32_32x32x16_bf16 v[64:79], v[112:115], v[84:87], v[64:79]
	v_mfma_f32_32x32x16_bf16 v[64:79], v[108:111], v[80:83], v[64:79]
	s_setprio 0
	s_cbranch_vccnz .LBB0_1975
	v_add3_u32 v80, s88, v97, v130
	v_add_u32_e32 v88, 0x400, v80
	v_add_u32_e32 v90, 0x408, v80
	v_add_u32_e32 v92, 0x420, v80
	v_add_u32_e32 v94, 0x428, v80
	v_add_u32_e32 v81, 0x440, v80
	v_add_u32_e32 v82, 0x448, v80
	v_add_u32_e32 v84, 0x460, v80
	v_add_u32_e32 v86, 0x468, v80
	ds_read2_b32 v[80:81], v81 offset1:1
	ds_read2_b32 v[82:83], v82 offset1:1
	ds_read2_b32 v[84:85], v84 offset1:1
	ds_read2_b32 v[86:87], v86 offset1:1
	ds_read2_b32 v[88:89], v88 offset1:1
	ds_read2_b32 v[90:91], v90 offset1:1
	ds_read2_b32 v[92:93], v92 offset1:1
	ds_read2_b32 v[94:95], v94 offset1:1
	s_waitcnt lgkmcnt(0)
	v_pk_add_f32 v[78:79], v[78:79], v[86:87]
	v_pk_add_f32 v[76:77], v[76:77], v[84:85]
	v_pk_add_f32 v[74:75], v[74:75], v[82:83]
	v_pk_add_f32 v[72:73], v[72:73], v[80:81]
	v_pk_add_f32 v[70:71], v[70:71], v[94:95]
	v_pk_add_f32 v[68:69], v[68:69], v[92:93]
	v_pk_add_f32 v[66:67], v[66:67], v[90:91]
	v_pk_add_f32 v[64:65], v[64:65], v[88:89]
.LBB0_1975:
	s_lshl_b32 s0, s44, 2
	s_add_i32 s0, s0, 0
	s_add_i32 s0, s0, 0x24000
	ds_read_b64_tr_b16 v[80:81], v106 offset:0x2000
	ds_read_b64_tr_b16 v[82:83], v106 offset:0x2800
	ds_read_b64_tr_b16 v[84:85], v106 offset:0x3000
	ds_read_b64_tr_b16 v[86:87], v106 offset:0x3800
	ds_read_b64_tr_b16 v[88:89], v106 offset:0x2200
	ds_read_b64_tr_b16 v[90:91], v106 offset:0x2a00
	ds_read_b64_tr_b16 v[92:93], v106 offset:0x3200
	ds_read_b64_tr_b16 v[94:95], v106 offset:0x3a00
	ds_read_b64_tr_b16 v[98:99], v106 offset:0x2400
	ds_read_b64_tr_b16 v[100:101], v106 offset:0x2c00
	ds_read_b64_tr_b16 v[102:103], v106 offset:0x3400
	ds_read_b64_tr_b16 v[104:105], v106 offset:0x3c00
	ds_read_b64_tr_b16 v[108:109], v106 offset:0x2600
	ds_read_b64_tr_b16 v[110:111], v106 offset:0x2e00
	ds_read_b64_tr_b16 v[112:113], v106 offset:0x3600
	ds_read_b64_tr_b16 v[114:115], v106 offset:0x3e00
	s_nop 7
	v_exp_f32_e32 v97, v64
	v_exp_f32_e32 v65, v65
	v_exp_f32_e32 v106, v66
	v_exp_f32_e32 v67, v67
	v_exp_f32_e32 v68, v68
	v_exp_f32_e32 v69, v69
	v_add_f32_e32 v64, v65, v97
	v_exp_f32_e32 v70, v70
	v_add_f32_e32 v64, v106, v64
	v_exp_f32_e32 v71, v71
	v_add_f32_e32 v64, v67, v64
	v_exp_f32_e32 v72, v72
	v_add_f32_e32 v64, v68, v64
	v_exp_f32_e32 v73, v73
	v_add_f32_e32 v64, v69, v64
	v_exp_f32_e32 v74, v74
	v_add_f32_e32 v64, v70, v64
	v_exp_f32_e32 v75, v75
	v_add_f32_e32 v64, v71, v64
	v_exp_f32_e32 v76, v76
	v_add_f32_e32 v64, v72, v64
	v_exp_f32_e32 v77, v77
	v_add_f32_e32 v64, v73, v64
	v_exp_f32_e32 v78, v78
	v_add_f32_e32 v64, v74, v64
	v_exp_f32_e32 v79, v79
	v_add_f32_e32 v64, v75, v64
	v_add_f32_e32 v64, v76, v64
	v_add_f32_e32 v64, v77, v64
	v_add_f32_e32 v64, v78, v64
	v_add_f32_e32 v64, v79, v64
	v_add_f32_e32 v64, v96, v64
	s_setprio 2
	v_cvt_pk_bf16_f32 v66, v97, v65
	v_cvt_pk_bf16_f32 v67, v106, v67
	v_cvt_pk_bf16_f32 v68, v68, v69
	v_cvt_pk_bf16_f32 v69, v70, v71
	v_cvt_pk_bf16_f32 v70, v72, v73
	v_cvt_pk_bf16_f32 v71, v74, v75
	v_cvt_pk_bf16_f32 v72, v76, v77
	v_cvt_pk_bf16_f32 v73, v78, v79
	s_nop 0
	v_permlane32_swap_b32_e32 v66, v68
	v_permlane32_swap_b32_e32 v67, v69
	v_permlane32_swap_b32_e32 v70, v72
	v_permlane32_swap_b32_e32 v71, v73
	s_waitcnt lgkmcnt(0)
; template <int TAG = 0> DI int fresh_tid(int wv) { int l; asm volatile("v_mbcnt_lo_u32_b32 %0, -1, 0\n\tv_mbcnt_hi_u32_b32 %0, -1, %0 ; site %1" : "=v"(l) : "n"(TAG)); return wv * 64 + l; }
; DI int crow(int r, int hi) { return (r & 3) + 8 * (r >> 2) + 4 * hi; }
; DI float swap_sum(float v) { auto rr = __builtin_amdgcn_permlane32_swap(__float_as_uint(v), __float_as_uint(v), false, false); return __uint_as_float(rr[0]) + __uint_as_float(rr[1]); }
; template <int DQK, int MODE, int LDQ, int LDK, int LDV> ...
;     ...
;     l_reg = swap_sum(l_reg);
;     { const int lane2 = fresh_tid<110 + MODE>(wv) & 63, r32 = lane2 & 31, hi = lane2 >> 5;
;     if (hi == 0) li_l[r32] = l_reg;
;     asm volatile("s_waitcnt lgkmcnt(0)" ::: "memory");
;     float s0v[MODE == 2 ? 16 : 1][4];
;     if constexpr (MODE == 2) {
; #pragma unroll
;         for (int r = 0; r < 16; ++r)
; #pragma unroll
;             for (int d0 = 0; d0 < 4; ++d0) s0v[r][d0] = S0[(size_t)(wid * 32 + crow(r, hi)) * 512 + d0 * 32 + r32];
;     }
; #pragma unroll
;     for (int r = 0; r < 16; ++r) { const int orow = wid * 32 + crow(r, hi); const float rl = __builtin_amdgcn_rcpf(li_l[crow(r, hi)]);
	s_setprio 1
	v_mfma_f32_32x32x16_bf16 v[0:15], v[66:69], v[80:83], v[0:15]
	v_mfma_f32_32x32x16_bf16 v[48:63], v[66:69], v[88:91], v[48:63]
	v_mfma_f32_32x32x16_bf16 v[16:31], v[66:69], v[98:101], v[16:31]
	v_mfma_f32_32x32x16_bf16 v[32:47], v[66:69], v[108:111], v[32:47]
	v_mfma_f32_32x32x16_bf16 v[0:15], v[70:73], v[84:87], v[0:15]
	v_mfma_f32_32x32x16_bf16 v[48:63], v[70:73], v[92:95], v[48:63]
	v_mfma_f32_32x32x16_bf16 v[16:31], v[70:73], v[102:105], v[16:31]
	v_mfma_f32_32x32x16_bf16 v[32:47], v[70:73], v[112:115], v[32:47]
	s_setprio 0
	v_mov_b32_e32 v66, v64
	v_mbcnt_lo_u32_b32 v65, -1, 0
	v_mbcnt_hi_u32_b32 v65, -1, v65
	s_nop 1
	v_permlane32_swap_b32_e32 v64, v66
	v_and_b32_e32 v114, 63, v65
	v_and_b32_e32 v170, 31, v65
	v_cmp_gt_u32_e32 vcc, 32, v114
	s_and_saveexec_b64 s[2:3], vcc
	v_lshl_add_u32 v67, v170, 2, s0
	v_add_f32_e32 v64, v64, v66
	ds_write_b32 v67, v64
	s_or_b64 exec, exec, s[2:3]
	v_lshrrev_b32_e32 v64, 3, v65
	v_and_b32_e32 v69, 4, v64
	v_or_b32_e32 v102, s46, v69
	v_lshlrev_b32_e32 v130, 2, v170
	v_ashrrev_i32_e32 v103, 31, v102
	v_or_b32_e32 v66, 1, v102
	v_lshl_add_u64 v[92:93], s[54:55], 0, v[130:131]
	v_lshlrev_b64 v[156:157], 11, v[102:103]
	v_ashrrev_i32_e32 v67, 31, v66
	s_waitcnt lgkmcnt(0)
	v_lshl_add_u64 v[64:65], v[92:93], 0, v[156:157]
	v_lshlrev_b64 v[148:149], 11, v[66:67]
	v_lshl_add_u64 v[66:67], v[92:93], 0, v[148:149]
	global_load_dword v110, v[64:65], off
	global_load_dword v111, v[64:65], off offset:128
	global_load_dword v109, v[64:65], off offset:256
	global_load_dword v108, v[64:65], off offset:384
	global_load_dword v106, v[66:67], off
	global_load_dword v107, v[66:67], off offset:128
	global_load_dword v105, v[66:67], off offset:256
	global_load_dword v104, v[66:67], off offset:384
	v_or_b32_e32 v64, 2, v102
	v_or_b32_e32 v66, 3, v102
	v_ashrrev_i32_e32 v65, 31, v64
	v_ashrrev_i32_e32 v67, 31, v66
	v_lshlrev_b64 v[146:147], 11, v[64:65]
	v_lshlrev_b64 v[136:137], 11, v[66:67]
	v_lshl_add_u64 v[64:65], v[92:93], 0, v[146:147]
	v_lshl_add_u64 v[66:67], v[92:93], 0, v[136:137]
	global_load_dword v158, v[64:65], off
	global_load_dword v159, v[64:65], off offset:128
	global_load_dword v155, v[64:65], off offset:256
	global_load_dword v154, v[64:65], off offset:384
	global_load_dword v152, v[66:67], off
	global_load_dword v153, v[66:67], off offset:128
	global_load_dword v151, v[66:67], off offset:256
	global_load_dword v150, v[66:67], off offset:384
	v_or_b32_e32 v64, 8, v102
	v_or_b32_e32 v66, 9, v102
	v_ashrrev_i32_e32 v65, 31, v64
	v_ashrrev_i32_e32 v67, 31, v66
	v_lshlrev_b64 v[134:135], 11, v[64:65]
	v_lshlrev_b64 v[120:121], 11, v[66:67]
	v_lshl_add_u64 v[64:65], v[92:93], 0, v[134:135]
	v_lshl_add_u64 v[66:67], v[92:93], 0, v[120:121]
	global_load_dword v144, v[64:65], off
	global_load_dword v145, v[64:65], off offset:128
	global_load_dword v143, v[64:65], off offset:256
	global_load_dword v142, v[64:65], off offset:384
	global_load_dword v140, v[66:67], off
	global_load_dword v141, v[66:67], off offset:128
	global_load_dword v139, v[66:67], off offset:256
	global_load_dword v138, v[66:67], off offset:384
	v_or_b32_e32 v64, 10, v102
	v_or_b32_e32 v66, 11, v102
	v_ashrrev_i32_e32 v65, 31, v64
	v_ashrrev_i32_e32 v67, 31, v66
	v_lshlrev_b64 v[118:119], 11, v[64:65]
	v_lshlrev_b64 v[90:91], 11, v[66:67]
	v_lshl_add_u64 v[64:65], v[92:93], 0, v[118:119]
	v_lshl_add_u64 v[66:67], v[92:93], 0, v[90:91]
	global_load_dword v132, v[64:65], off
	global_load_dword v133, v[64:65], off offset:128
	global_load_dword v127, v[64:65], off offset:256
	global_load_dword v126, v[64:65], off offset:384
	global_load_dword v124, v[66:67], off
	global_load_dword v125, v[66:67], off offset:128
	global_load_dword v123, v[66:67], off offset:256
	global_load_dword v122, v[66:67], off offset:384
	v_or_b32_e32 v64, 16, v102
	v_or_b32_e32 v66, 17, v102
	v_ashrrev_i32_e32 v65, 31, v64
	v_ashrrev_i32_e32 v67, 31, v66
	v_lshlrev_b64 v[86:87], 11, v[64:65]
	v_lshlrev_b64 v[78:79], 11, v[66:67]
	v_lshl_add_u64 v[64:65], v[92:93], 0, v[86:87]
	v_lshl_add_u64 v[66:67], v[92:93], 0, v[78:79]
	global_load_dword v100, v[64:65], off
	global_load_dword v101, v[64:65], off offset:128
	global_load_dword v99, v[64:65], off offset:256
	global_load_dword v98, v[64:65], off offset:384
	global_load_dword v96, v[66:67], off
	global_load_dword v97, v[66:67], off offset:128
	global_load_dword v95, v[66:67], off offset:256
	global_load_dword v94, v[66:67], off offset:384
	v_or_b32_e32 v64, 18, v102
	v_or_b32_e32 v66, 19, v102
	v_ashrrev_i32_e32 v65, 31, v64
	v_ashrrev_i32_e32 v67, 31, v66
	v_lshlrev_b64 v[76:77], 11, v[64:65]
	v_lshlrev_b64 v[72:73], 11, v[66:67]
	v_lshl_add_u64 v[64:65], v[92:93], 0, v[76:77]
	v_lshl_add_u64 v[66:67], v[92:93], 0, v[72:73]
	v_lshl_add_u32 v169, v69, 2, s0
	global_load_dword v88, v[64:65], off
	global_load_dword v89, v[64:65], off offset:128
	global_load_dword v85, v[64:65], off offset:256
	global_load_dword v84, v[64:65], off offset:384
	global_load_dword v82, v[66:67], off
	global_load_dword v83, v[66:67], off offset:128
	global_load_dword v81, v[66:67], off offset:256
	global_load_dword v80, v[66:67], off offset:384
	ds_read_b128 v[64:67], v169
	v_or_b32_e32 v68, 24, v102
	v_ashrrev_i32_e32 v69, 31, v68
	v_lshlrev_b64 v[74:75], 11, v[68:69]
	ds_read_b128 v[68:71], v169 offset:32
	s_waitcnt lgkmcnt(0)
; DI unsigned short f2bf(float x) { unsigned u = __float_as_uint(x); u += 0x7fffu + ((u >> 16) & 1u); return (unsigned short)(u >> 16); }
; DI float shx(float v, int mask, int lane) { return __int_as_float(__builtin_amdgcn_ds_bpermute((lane ^ mask) << 2, __float_as_int(v))); }
; DI int crow(int r, int hi) { return (r & 3) + 8 * (r >> 2) + 4 * hi; }
; template <int DQK, int MODE, int LDQ, int LDK, int LDV> ...
;     ...
;     if constexpr (MODE == 2) {
; #pragma unroll
;         for (int r = 0; r < 16; ++r)
; #pragma unroll
;             for (int d0 = 0; d0 < 4; ++d0) s0v[r][d0] = S0[(size_t)(wid * 32 + crow(r, hi)) * 512 + d0 * 32 + r32];
;     }
; #pragma unroll
;     for (int r = 0; r < 16; ++r) { const int orow = wid * 32 + crow(r, hi); const float rl = __builtin_amdgcn_rcpf(li_l[crow(r, hi)]);
;         if constexpr (MODE == 0) {
; #pragma unroll
;             for (int d0 = 0; d0 < 4; ++d0) AOb[(size_t)orow * 1024 + d0 * 32 + r32] = f2bf(o[d0][r] * rl);
;         } else if constexpr (MODE == 1) {
; #pragma unroll
;             for (int d0 = 0; d0 < 4; ++d0) S0[(size_t)orow * 512 + d0 * 32 + r32] = o[d0][r] * rl;
;         } else {
;             float v[4]; float ss = 0.f;
; #pragma unroll
;             for (int d0 = 0; d0 < 4; ++d0) { v[d0] = s0v[r][d0] - lam * (o[d0][r] * rl); ss += v[d0] * v[d0]; }
; #pragma unroll
;             for (int mk = 1; mk <= 16; mk <<= 1) ss += shx(ss, mk, lane2);
;             const float rs = rsqrtf(ss * (1.f / 128.f) + EPS) * 0.8f;
; #pragma unroll
;             for (int d0 = 0; d0 < 4; ++d0) AOb[(size_t)orow * 1024 + d0 * 32 + r32] = f2bf(v[d0] * rs * gout[d0 * 32 + r32]);
;         } }
	v_rcp_f32_e32 v64, v64
	v_mov_b32_e32 v162, v0
	v_mov_b32_e32 v163, v48
	v_rcp_f32_e32 v0, v65
	v_pk_mul_f32 v[162:163], v[162:163], v[64:65] op_sel_hi:[1,0]
	v_mov_b32_e32 v48, v1
	v_lshlrev_b32_e32 v166, 2, v114
	v_pk_mul_f32 v[48:49], v[48:49], v[0:1] op_sel_hi:[1,0]
	v_xor_b32_e32 v164, 4, v166
	v_xor_b32_e32 v165, 8, v166
	v_xor_b32_e32 v168, 16, v166
	v_xor_b32_e32 v167, 32, v166
	v_or_b32_e32 v116, 25, v102
	v_ashrrev_i32_e32 v117, 31, v116
	v_xor_b32_e32 v166, 64, v166
	v_lshl_add_u64 v[112:113], v[92:93], 0, v[74:75]
	s_add_u32 s1, s60, s58
	s_mov_b32 s0, 0x358637bd
	s_addc_u32 s3, s61, s59
	s_lshl_b32 s2, s87, 1
	s_add_u32 s2, s1, s2
	s_addc_u32 s3, s3, 0
	s_waitcnt vmcnt(0)
	v_pk_fma_f32 v[172:173], v[128:129], v[162:163], v[110:111] neg_lo:[1,0,0] neg_hi:[1,0,0]
	v_mov_b32_e32 v162, v32
	v_mov_b32_e32 v163, v16
	v_pk_mul_f32 v[162:163], v[162:163], v[64:65] op_sel_hi:[1,0]
	v_mov_b32_e32 v16, v33
	v_pk_fma_f32 v[174:175], v[128:129], v[162:163], v[108:109] neg_lo:[1,0,0] neg_hi:[1,0,0]
	global_load_dword v163, v130, s[50:51]
	global_load_dword v162, v130, s[50:51] offset:128
	global_load_dword v161, v130, s[50:51] offset:256
	s_nop 0
	global_load_dword v130, v130, s[50:51] offset:384
	v_pk_fma_f32 v[176:177], v[128:129], v[48:49], v[106:107] neg_lo:[1,0,0] neg_hi:[1,0,0]
	v_pk_mul_f32 v[0:1], v[16:17], v[0:1] op_sel_hi:[1,0]
	v_pk_mul_f32 v[110:111], v[172:173], v[172:173]
	v_pk_mul_f32 v[48:49], v[176:177], v[176:177]
	v_pk_fma_f32 v[0:1], v[128:129], v[0:1], v[104:105] neg_lo:[1,0,0] neg_hi:[1,0,0]
	v_pk_mul_f32 v[108:109], v[174:175], v[174:175]
	v_pk_mul_f32 v[16:17], v[0:1], v[0:1]
	v_mov_b32_e32 v32, v48
	v_mov_b32_e32 v33, v110
	v_mov_b32_e32 v110, v49
	v_pk_add_f32 v[32:33], v[32:33], v[110:111]
	v_mov_b32_e32 v48, v17
	v_mov_b32_e32 v49, v109
	v_pk_add_f32 v[32:33], v[48:49], v[32:33]
	v_mov_b32_e32 v17, v108
	v_pk_add_f32 v[16:17], v[16:17], v[32:33]
	ds_bpermute_b32 v33, v164, v17
	ds_bpermute_b32 v32, v164, v16
	v_lshlrev_b64 v[64:65], 11, v[116:117]
	v_lshl_add_u64 v[48:49], v[92:93], 0, v[64:65]
	global_load_dword v116, v[112:113], off
	global_load_dword v117, v[112:113], off offset:128
	global_load_dword v115, v[112:113], off offset:256
	global_load_dword v114, v[112:113], off offset:384
	s_nop 0
	global_load_dword v112, v[48:49], off
	global_load_dword v113, v[48:49], off offset:128
	global_load_dword v111, v[48:49], off offset:256
	global_load_dword v110, v[48:49], off offset:384
	v_or_b32_e32 v48, 26, v102
	s_waitcnt lgkmcnt(0)
	v_pk_add_f32 v[16:17], v[16:17], v[32:33]
	ds_bpermute_b32 v33, v165, v17
	ds_bpermute_b32 v32, v165, v16
	v_or_b32_e32 v102, 27, v102
	v_ashrrev_i32_e32 v49, 31, v48
	v_ashrrev_i32_e32 v103, 31, v102
	v_lshlrev_b64 v[48:49], 11, v[48:49]
	s_waitcnt lgkmcnt(0)
	v_pk_add_f32 v[16:17], v[16:17], v[32:33]
	ds_bpermute_b32 v33, v168, v17
	ds_bpermute_b32 v32, v168, v16
	v_lshl_add_u64 v[104:105], v[92:93], 0, v[48:49]
	v_lshlrev_b32_e32 v170, 1, v170
	v_mov_b32_e32 v171, v131
	v_rcp_f32_e32 v66, v66
	s_waitcnt lgkmcnt(0)
	v_pk_add_f32 v[32:33], v[16:17], v[32:33]
	ds_bpermute_b32 v107, v167, v33
	ds_bpermute_b32 v106, v167, v32
	v_lshlrev_b64 v[16:17], 11, v[102:103]
	v_lshl_add_u64 v[92:93], v[92:93], 0, v[16:17]
	s_waitcnt lgkmcnt(0)
	v_pk_add_f32 v[32:33], v[32:33], v[106:107]
	ds_bpermute_b32 v179, v166, v33
	ds_bpermute_b32 v178, v166, v32
	global_load_dword v108, v[104:105], off
	global_load_dword v109, v[104:105], off offset:128
	global_load_dword v107, v[104:105], off offset:256
	global_load_dword v106, v[104:105], off offset:384
	s_nop 0
	global_load_dword v104, v[92:93], off
	global_load_dword v105, v[92:93], off offset:128
	global_load_dword v103, v[92:93], off offset:256
	global_load_dword v102, v[92:93], off offset:384
	v_mov_b64_e32 v[92:93], s[0:1]
	s_waitcnt lgkmcnt(0)
	v_pk_add_f32 v[32:33], v[32:33], v[178:179]
	s_nop 0
	v_pk_fma_f32 v[178:179], v[32:33], s[24:25], v[92:93] op_sel_hi:[1,0,0]
	s_nop 0
	v_mul_f32_e32 v32, 0x4b800000, v179
	v_cmp_gt_f32_e32 vcc, s67, v179
	s_nop 1
	v_cndmask_b32_e32 v32, v179, v32, vcc
	v_rsq_f32_e32 v179, v32
	v_lshl_add_u64 v[32:33], s[2:3], 0, v[170:171]
	v_lshl_add_u64 v[156:157], v[32:33], 0, v[156:157]
	v_lshl_add_u64 v[148:149], v[32:33], 0, v[148:149]
	v_mul_f32_e32 v170, 0x45800000, v179
	v_cndmask_b32_e32 v170, v179, v170, vcc
	v_mul_f32_e32 v170, 0x3f4ccccd, v170
	v_mul_f32_e32 v171, v172, v170
	v_cmp_gt_f32_e32 vcc, s67, v178
	s_mov_b64 s[2:3], 0
	s_waitcnt vmcnt(19)
	v_mul_f32_e32 v171, v163, v171
	v_bfe_u32 v172, v171, 16, 1
	v_add3_u32 v171, v171, v172, s68
	global_store_short_d16_hi v[156:157], v171, off offset:1024
	v_mul_f32_e32 v171, v173, v170
	s_waitcnt vmcnt(19)
	v_mul_f32_e32 v171, v162, v171
	v_bfe_u32 v172, v171, 16, 1
	v_add3_u32 v171, v171, v172, s68
	global_store_short_d16_hi v[156:157], v171, off offset:1088
	v_mul_f32_e32 v171, v175, v170
	s_waitcnt vmcnt(19)
	v_mul_f32_e32 v171, v161, v171
	v_bfe_u32 v172, v171, 16, 1
	v_add3_u32 v171, v171, v172, s68
	global_store_short_d16_hi v[156:157], v171, off offset:1152
	v_mul_f32_e32 v171, 0x4b800000, v178
	v_cndmask_b32_e32 v171, v178, v171, vcc
	v_mul_f32_e32 v170, v174, v170
	v_rsq_f32_e32 v171, v171
	s_waitcnt vmcnt(19)
; DI unsigned short f2bf(float x) { unsigned u = __float_as_uint(x); u += 0x7fffu + ((u >> 16) & 1u); return (unsigned short)(u >> 16); }
; DI float shx(float v, int mask, int lane) { return __int_as_float(__builtin_amdgcn_ds_bpermute((lane ^ mask) << 2, __float_as_int(v))); }
; DI int crow(int r, int hi) { return (r & 3) + 8 * (r >> 2) + 4 * hi; }
; template <int DQK, int MODE, int LDQ, int LDK, int LDV> ...
;     ...
;     if constexpr (MODE == 2) {
; #pragma unroll
;         for (int r = 0; r < 16; ++r)
; #pragma unroll
;             for (int d0 = 0; d0 < 4; ++d0) s0v[r][d0] = S0[(size_t)(wid * 32 + crow(r, hi)) * 512 + d0 * 32 + r32];
;     }
; #pragma unroll
;     for (int r = 0; r < 16; ++r) { const int orow = wid * 32 + crow(r, hi); const float rl = __builtin_amdgcn_rcpf(li_l[crow(r, hi)]);
;         if constexpr (MODE == 0) {
; #pragma unroll
;             for (int d0 = 0; d0 < 4; ++d0) AOb[(size_t)orow * 1024 + d0 * 32 + r32] = f2bf(o[d0][r] * rl);
;         } else if constexpr (MODE == 1) {
; #pragma unroll
;             for (int d0 = 0; d0 < 4; ++d0) S0[(size_t)orow * 512 + d0 * 32 + r32] = o[d0][r] * rl;
;         } else {
;             float v[4]; float ss = 0.f;
; #pragma unroll
;             for (int d0 = 0; d0 < 4; ++d0) { v[d0] = s0v[r][d0] - lam * (o[d0][r] * rl); ss += v[d0] * v[d0]; }
; #pragma unroll
;             for (int mk = 1; mk <= 16; mk <<= 1) ss += shx(ss, mk, lane2);
;             const float rs = rsqrtf(ss * (1.f / 128.f) + EPS) * 0.8f;
; #pragma unroll
;             for (int d0 = 0; d0 < 4; ++d0) AOb[(size_t)orow * 1024 + d0 * 32 + r32] = f2bf(v[d0] * rs * gout[d0 * 32 + r32]);
;         } }
	v_mul_f32_e32 v170, v130, v170
	v_bfe_u32 v172, v170, 16, 1
	v_add3_u32 v170, v170, v172, s68
	global_store_short_d16_hi v[156:157], v170, off offset:1216
	v_mul_f32_e32 v156, 0x45800000, v171
	v_cndmask_b32_e32 v172, v171, v156, vcc
	v_mov_b32_e32 v156, v2
	v_rcp_f32_e32 v2, v67
	v_mov_b32_e32 v157, v50
	v_mov_b32_e32 v50, v3
	v_pk_mul_f32 v[156:157], v[156:157], v[66:67] op_sel_hi:[1,0]
	v_mov_b32_e32 v170, v34
	v_mov_b32_e32 v171, v18
	v_pk_mul_f32 v[50:51], v[50:51], v[2:3] op_sel_hi:[1,0]
	v_mov_b32_e32 v18, v35
	v_pk_fma_f32 v[156:157], v[128:129], v[156:157], v[158:159] neg_lo:[1,0,0] neg_hi:[1,0,0]
	v_pk_mul_f32 v[170:171], v[170:171], v[66:67] op_sel_hi:[1,0]
	v_pk_fma_f32 v[50:51], v[128:129], v[50:51], v[152:153] neg_lo:[1,0,0] neg_hi:[1,0,0]
	v_pk_mul_f32 v[2:3], v[18:19], v[2:3] op_sel_hi:[1,0]
	v_pk_mul_f32 v[158:159], v[156:157], v[156:157]
	v_pk_fma_f32 v[66:67], v[128:129], v[170:171], v[154:155] neg_lo:[1,0,0] neg_hi:[1,0,0]
	v_pk_mul_f32 v[152:153], v[50:51], v[50:51]
	v_pk_fma_f32 v[2:3], v[128:129], v[2:3], v[150:151] neg_lo:[1,0,0] neg_hi:[1,0,0]
	v_pk_mul_f32 v[154:155], v[66:67], v[66:67]
	v_pk_mul_f32 v[18:19], v[2:3], v[2:3]
	v_mov_b32_e32 v34, v152
	v_mov_b32_e32 v35, v158
	v_mov_b32_e32 v158, v153
	v_pk_add_f32 v[34:35], v[34:35], v[158:159]
	v_mov_b32_e32 v150, v19
	v_mov_b32_e32 v151, v155
	v_pk_add_f32 v[34:35], v[150:151], v[34:35]
	v_mov_b32_e32 v19, v154
	v_pk_add_f32 v[18:19], v[18:19], v[34:35]
	ds_bpermute_b32 v35, v164, v19
	ds_bpermute_b32 v34, v164, v18
	v_mul_f32_e32 v150, 0x3f4ccccd, v172
	v_mul_f32_e32 v151, v176, v150
	v_mul_f32_e32 v151, v163, v151
	v_bfe_u32 v152, v151, 16, 1
	s_waitcnt lgkmcnt(0)
	v_pk_add_f32 v[18:19], v[18:19], v[34:35]
	ds_bpermute_b32 v35, v165, v19
	ds_bpermute_b32 v34, v165, v18
	v_add3_u32 v151, v151, v152, s68
	global_store_short_d16_hi v[148:149], v151, off offset:1024
	v_mul_f32_e32 v151, v177, v150
	v_mul_f32_e32 v151, v162, v151
	s_waitcnt lgkmcnt(0)
	v_pk_add_f32 v[18:19], v[18:19], v[34:35]
	ds_bpermute_b32 v35, v168, v19
	ds_bpermute_b32 v34, v168, v18
	v_bfe_u32 v152, v151, 16, 1
	v_mul_f32_e32 v1, v1, v150
	v_add3_u32 v151, v151, v152, s68
	v_mul_f32_e32 v1, v161, v1
	s_waitcnt lgkmcnt(0)
	v_pk_add_f32 v[18:19], v[18:19], v[34:35]
	ds_bpermute_b32 v35, v167, v19
	ds_bpermute_b32 v34, v167, v18
	global_store_short_d16_hi v[148:149], v151, off offset:1088
	v_bfe_u32 v151, v1, 16, 1
	v_add3_u32 v1, v1, v151, s68
	v_mul_f32_e32 v0, v0, v150
	s_waitcnt lgkmcnt(0)
	v_pk_add_f32 v[18:19], v[18:19], v[34:35]
	ds_bpermute_b32 v35, v166, v19
	ds_bpermute_b32 v34, v166, v18
	global_store_short_d16_hi v[148:149], v1, off offset:1152
	v_mul_f32_e32 v150, v130, v0
	v_bfe_u32 v151, v150, 16, 1
	s_waitcnt lgkmcnt(0)
	v_pk_add_f32 v[0:1], v[18:19], v[34:35]
	s_nop 0
	v_pk_fma_f32 v[0:1], v[0:1], s[24:25], v[92:93] op_sel_hi:[1,0,0]
	s_nop 0
	v_mul_f32_e32 v18, 0x4b800000, v1
	v_cmp_gt_f32_e32 vcc, s67, v1
	s_nop 1
	v_cndmask_b32_e32 v1, v1, v18, vcc
	v_rsq_f32_e32 v1, v1
	v_add3_u32 v18, v150, v151, s68
	global_store_short_d16_hi v[148:149], v18, off offset:1216
	v_lshl_add_u64 v[18:19], v[32:33], 0, v[146:147]
	v_mul_f32_e32 v34, 0x45800000, v1
	v_cndmask_b32_e32 v1, v1, v34, vcc
	v_mul_f32_e32 v1, 0x3f4ccccd, v1
	v_mul_f32_e32 v34, v156, v1
	v_mul_f32_e32 v34, v163, v34
	v_bfe_u32 v35, v34, 16, 1
	v_add3_u32 v34, v34, v35, s68
	global_store_short_d16_hi v[18:19], v34, off offset:1024
	v_mul_f32_e32 v34, v157, v1
	v_mul_f32_e32 v34, v162, v34
	v_bfe_u32 v35, v34, 16, 1
	v_add3_u32 v34, v34, v35, s68
	global_store_short_d16_hi v[18:19], v34, off offset:1088
	v_mul_f32_e32 v34, v67, v1
	v_mul_f32_e32 v34, v161, v34
	v_bfe_u32 v35, v34, 16, 1
	v_add3_u32 v34, v34, v35, s68
	global_store_short_d16_hi v[18:19], v34, off offset:1152
	v_mul_f32_e32 v1, v66, v1
	v_mul_f32_e32 v34, 0x4b800000, v0
	v_cmp_gt_f32_e32 vcc, s67, v0
	v_mul_f32_e32 v1, v130, v1
	v_mov_b32_e32 v66, v36
	v_cndmask_b32_e32 v0, v0, v34, vcc
	v_rsq_f32_e32 v34, v0
	v_bfe_u32 v0, v1, 16, 1
	v_add3_u32 v0, v1, v0, s68
	global_store_short_d16_hi v[18:19], v0, off offset:1216
	v_rcp_f32_e32 v0, v68
	v_mov_b32_e32 v18, v4
	v_rcp_f32_e32 v4, v69
	v_mul_f32_e32 v1, 0x45800000, v34
	v_mov_b32_e32 v19, v52
	v_mov_b32_e32 v52, v5
	v_pk_mul_f32 v[18:19], v[18:19], v[0:1] op_sel_hi:[1,0]
	v_mov_b32_e32 v67, v20
	v_pk_mul_f32 v[52:53], v[52:53], v[4:5] op_sel_hi:[1,0]
	v_mov_b32_e32 v20, v37
	v_cndmask_b32_e32 v146, v34, v1, vcc
	v_pk_fma_f32 v[18:19], v[128:129], v[18:19], v[144:145] neg_lo:[1,0,0] neg_hi:[1,0,0]
	v_pk_mul_f32 v[0:1], v[66:67], v[0:1] op_sel_hi:[1,0]
	v_pk_fma_f32 v[52:53], v[128:129], v[52:53], v[140:141] neg_lo:[1,0,0] neg_hi:[1,0,0]
	v_pk_mul_f32 v[4:5], v[20:21], v[4:5] op_sel_hi:[1,0]
	v_pk_mul_f32 v[34:35], v[18:19], v[18:19]
	v_pk_fma_f32 v[0:1], v[128:129], v[0:1], v[142:143] neg_lo:[1,0,0] neg_hi:[1,0,0]
	v_pk_mul_f32 v[68:69], v[52:53], v[52:53]
	v_pk_fma_f32 v[4:5], v[128:129], v[4:5], v[138:139] neg_lo:[1,0,0] neg_hi:[1,0,0]
	v_pk_mul_f32 v[66:67], v[0:1], v[0:1]
	v_pk_mul_f32 v[20:21], v[4:5], v[4:5]
	v_mov_b32_e32 v36, v68
	v_mov_b32_e32 v37, v34
	v_mov_b32_e32 v34, v69
	v_pk_add_f32 v[34:35], v[36:37], v[34:35]
	v_mov_b32_e32 v36, v21
	v_mov_b32_e32 v37, v67
	v_pk_add_f32 v[34:35], v[36:37], v[34:35]
	v_mov_b32_e32 v21, v66
	v_pk_add_f32 v[20:21], v[20:21], v[34:35]
	ds_bpermute_b32 v35, v164, v21
	ds_bpermute_b32 v34, v164, v20
	v_mul_f32_e32 v66, 0x3f4ccccd, v146
	v_mul_f32_e32 v50, v50, v66
	v_mul_f32_e32 v50, v163, v50
	v_bfe_u32 v67, v50, 16, 1
	s_waitcnt lgkmcnt(0)
; DI unsigned short f2bf(float x) { unsigned u = __float_as_uint(x); u += 0x7fffu + ((u >> 16) & 1u); return (unsigned short)(u >> 16); }
; DI float shx(float v, int mask, int lane) { return __int_as_float(__builtin_amdgcn_ds_bpermute((lane ^ mask) << 2, __float_as_int(v))); }
; DI int crow(int r, int hi) { return (r & 3) + 8 * (r >> 2) + 4 * hi; }
; template <int DQK, int MODE, int LDQ, int LDK, int LDV> ...
;     ...
;     if constexpr (MODE == 2) {
; #pragma unroll
;         for (int r = 0; r < 16; ++r)
; #pragma unroll
;             for (int d0 = 0; d0 < 4; ++d0) s0v[r][d0] = S0[(size_t)(wid * 32 + crow(r, hi)) * 512 + d0 * 32 + r32];
;     }
; #pragma unroll
;     for (int r = 0; r < 16; ++r) { const int orow = wid * 32 + crow(r, hi); const float rl = __builtin_amdgcn_rcpf(li_l[crow(r, hi)]);
;         if constexpr (MODE == 0) {
; #pragma unroll
;             for (int d0 = 0; d0 < 4; ++d0) AOb[(size_t)orow * 1024 + d0 * 32 + r32] = f2bf(o[d0][r] * rl);
;         } else if constexpr (MODE == 1) {
; #pragma unroll
;             for (int d0 = 0; d0 < 4; ++d0) S0[(size_t)orow * 512 + d0 * 32 + r32] = o[d0][r] * rl;
;         } else {
;             float v[4]; float ss = 0.f;
; #pragma unroll
;             for (int d0 = 0; d0 < 4; ++d0) { v[d0] = s0v[r][d0] - lam * (o[d0][r] * rl); ss += v[d0] * v[d0]; }
; #pragma unroll
;             for (int mk = 1; mk <= 16; mk <<= 1) ss += shx(ss, mk, lane2);
;             const float rs = rsqrtf(ss * (1.f / 128.f) + EPS) * 0.8f;
; #pragma unroll
;             for (int d0 = 0; d0 < 4; ++d0) AOb[(size_t)orow * 1024 + d0 * 32 + r32] = f2bf(v[d0] * rs * gout[d0 * 32 + r32]);
;         } }
	v_pk_add_f32 v[20:21], v[20:21], v[34:35]
	ds_bpermute_b32 v35, v165, v21
	ds_bpermute_b32 v34, v165, v20
	v_lshl_add_u64 v[36:37], v[32:33], 0, v[136:137]
	v_add3_u32 v50, v50, v67, s68
	global_store_short_d16_hi v[36:37], v50, off offset:1024
	v_mul_f32_e32 v50, v51, v66
	s_waitcnt lgkmcnt(0)
	v_pk_add_f32 v[20:21], v[20:21], v[34:35]
	ds_bpermute_b32 v35, v168, v21
	ds_bpermute_b32 v34, v168, v20
	v_mul_f32_e32 v50, v162, v50
	v_bfe_u32 v51, v50, 16, 1
	v_mul_f32_e32 v3, v3, v66
	v_add3_u32 v50, v50, v51, s68
	s_waitcnt lgkmcnt(0)
	v_pk_add_f32 v[20:21], v[20:21], v[34:35]
	ds_bpermute_b32 v35, v167, v21
	ds_bpermute_b32 v34, v167, v20
	v_mul_f32_e32 v3, v161, v3
	global_store_short_d16_hi v[36:37], v50, off offset:1088
	v_bfe_u32 v50, v3, 16, 1
	v_add3_u32 v3, v3, v50, s68
	s_waitcnt lgkmcnt(0)
	v_pk_add_f32 v[20:21], v[20:21], v[34:35]
	ds_bpermute_b32 v35, v166, v21
	ds_bpermute_b32 v34, v166, v20
	v_mul_f32_e32 v2, v2, v66
	global_store_short_d16_hi v[36:37], v3, off offset:1152
	v_mul_f32_e32 v50, v130, v2
	v_bfe_u32 v51, v50, 16, 1
	s_waitcnt lgkmcnt(0)
	v_pk_add_f32 v[2:3], v[20:21], v[34:35]
	s_nop 0
	v_pk_fma_f32 v[2:3], v[2:3], s[24:25], v[92:93] op_sel_hi:[1,0,0]
	s_nop 0
	v_mul_f32_e32 v20, 0x4b800000, v3
	v_cmp_gt_f32_e32 vcc, s67, v3
	s_nop 1
	v_cndmask_b32_e32 v3, v3, v20, vcc
	v_rsq_f32_e32 v3, v3
	v_add3_u32 v20, v50, v51, s68
	global_store_short_d16_hi v[36:37], v20, off offset:1216
	v_lshl_add_u64 v[20:21], v[32:33], 0, v[134:135]
	v_mul_f32_e32 v34, 0x45800000, v3
	v_cndmask_b32_e32 v3, v3, v34, vcc
	v_mul_f32_e32 v3, 0x3f4ccccd, v3
	v_mul_f32_e32 v18, v18, v3
	v_mul_f32_e32 v18, v163, v18
	v_bfe_u32 v34, v18, 16, 1
	v_add3_u32 v18, v18, v34, s68
	global_store_short_d16_hi v[20:21], v18, off offset:1024
	v_mul_f32_e32 v18, v19, v3
	v_mul_f32_e32 v18, v162, v18
	v_bfe_u32 v19, v18, 16, 1
	v_mul_f32_e32 v1, v1, v3
	v_add3_u32 v18, v18, v19, s68
	v_mul_f32_e32 v1, v161, v1
	global_store_short_d16_hi v[20:21], v18, off offset:1088
	v_bfe_u32 v18, v1, 16, 1
	v_add3_u32 v1, v1, v18, s68
	global_store_short_d16_hi v[20:21], v1, off offset:1152
	v_mul_f32_e32 v1, 0x4b800000, v2
	v_cmp_gt_f32_e32 vcc, s67, v2
	v_mul_f32_e32 v0, v0, v3
	v_mul_f32_e32 v0, v130, v0
	v_cndmask_b32_e32 v1, v2, v1, vcc
	v_rsq_f32_e32 v1, v1
	v_bfe_u32 v2, v0, 16, 1
	v_add3_u32 v0, v0, v2, s68
	global_store_short_d16_hi v[20:21], v0, off offset:1216
	v_mul_f32_e32 v2, 0x45800000, v1
	v_rcp_f32_e32 v0, v70
	v_cndmask_b32_e32 v66, v1, v2, vcc
	v_mov_b32_e32 v2, v6
	v_rcp_f32_e32 v6, v71
	v_mov_b32_e32 v3, v54
	v_mov_b32_e32 v18, v38
	v_mov_b32_e32 v19, v22
	v_mov_b32_e32 v54, v7
	v_pk_mul_f32 v[2:3], v[2:3], v[0:1] op_sel_hi:[1,0]
	v_pk_mul_f32 v[0:1], v[18:19], v[0:1] op_sel_hi:[1,0]
	v_pk_mul_f32 v[18:19], v[54:55], v[6:7] op_sel_hi:[1,0]
	v_mov_b32_e32 v22, v39
	v_pk_fma_f32 v[2:3], v[128:129], v[2:3], v[132:133] neg_lo:[1,0,0] neg_hi:[1,0,0]
	v_pk_fma_f32 v[20:21], v[128:129], v[18:19], v[124:125] neg_lo:[1,0,0] neg_hi:[1,0,0]
	v_pk_mul_f32 v[6:7], v[22:23], v[6:7] op_sel_hi:[1,0]
	v_pk_mul_f32 v[34:35], v[2:3], v[2:3]
	v_pk_fma_f32 v[0:1], v[128:129], v[0:1], v[126:127] neg_lo:[1,0,0] neg_hi:[1,0,0]
	v_pk_mul_f32 v[50:51], v[20:21], v[20:21]
	v_pk_fma_f32 v[18:19], v[128:129], v[6:7], v[122:123] neg_lo:[1,0,0] neg_hi:[1,0,0]
	v_pk_mul_f32 v[36:37], v[0:1], v[0:1]
	v_pk_mul_f32 v[6:7], v[18:19], v[18:19]
	v_mov_b32_e32 v22, v50
	v_mov_b32_e32 v23, v34
	v_mov_b32_e32 v34, v51
	v_pk_add_f32 v[22:23], v[22:23], v[34:35]
	v_mov_b32_e32 v34, v7
	v_mov_b32_e32 v35, v37
	v_pk_add_f32 v[22:23], v[34:35], v[22:23]
	v_mov_b32_e32 v7, v36
	v_pk_add_f32 v[6:7], v[6:7], v[22:23]
	ds_bpermute_b32 v23, v164, v7
	ds_bpermute_b32 v22, v164, v6
	v_mul_f32_e32 v36, 0x3f4ccccd, v66
	v_mul_f32_e32 v37, v52, v36
	v_mul_f32_e32 v37, v163, v37
	v_bfe_u32 v38, v37, 16, 1
	s_waitcnt lgkmcnt(0)
	v_pk_add_f32 v[6:7], v[6:7], v[22:23]
	ds_bpermute_b32 v23, v165, v7
	ds_bpermute_b32 v22, v165, v6
	v_lshl_add_u64 v[34:35], v[32:33], 0, v[120:121]
	v_add3_u32 v37, v37, v38, s68
	global_store_short_d16_hi v[34:35], v37, off offset:1024
	v_mul_f32_e32 v37, v53, v36
	s_waitcnt lgkmcnt(0)
	v_pk_add_f32 v[6:7], v[6:7], v[22:23]
	ds_bpermute_b32 v23, v168, v7
	ds_bpermute_b32 v22, v168, v6
	v_mul_f32_e32 v37, v162, v37
	v_bfe_u32 v38, v37, 16, 1
	v_mul_f32_e32 v5, v5, v36
	v_add3_u32 v37, v37, v38, s68
	s_waitcnt lgkmcnt(0)
	v_pk_add_f32 v[6:7], v[6:7], v[22:23]
	ds_bpermute_b32 v23, v167, v7
	ds_bpermute_b32 v22, v167, v6
	v_mul_f32_e32 v5, v161, v5
	global_store_short_d16_hi v[34:35], v37, off offset:1088
	v_bfe_u32 v37, v5, 16, 1
	v_add3_u32 v5, v5, v37, s68
	s_waitcnt lgkmcnt(0)
	v_pk_add_f32 v[6:7], v[6:7], v[22:23]
	ds_bpermute_b32 v23, v166, v7
	ds_bpermute_b32 v22, v166, v6
	v_mul_f32_e32 v4, v4, v36
	global_store_short_d16_hi v[34:35], v5, off offset:1152
	v_mul_f32_e32 v36, v130, v4
	v_bfe_u32 v37, v36, 16, 1
	s_waitcnt lgkmcnt(0)
	v_pk_add_f32 v[4:5], v[6:7], v[22:23]
	v_lshl_add_u64 v[22:23], v[32:33], 0, v[118:119]
	v_pk_fma_f32 v[4:5], v[4:5], s[24:25], v[92:93] op_sel_hi:[1,0,0]
	s_nop 0
	v_mul_f32_e32 v6, 0x4b800000, v5
	v_cmp_gt_f32_e32 vcc, s67, v5
	s_nop 1
	v_cndmask_b32_e32 v5, v5, v6, vcc
	v_rsq_f32_e32 v5, v5
	v_add3_u32 v6, v36, v37, s68
	global_store_short_d16_hi v[34:35], v6, off offset:1216
	v_mov_b32_e32 v36, v40
	v_mul_f32_e32 v6, 0x45800000, v5
	v_cndmask_b32_e32 v5, v5, v6, vcc
	v_mul_f32_e32 v5, 0x3f4ccccd, v5
	v_mul_f32_e32 v2, v2, v5
	v_mul_f32_e32 v2, v163, v2
	v_bfe_u32 v6, v2, 16, 1
	v_add3_u32 v2, v2, v6, s68
	global_store_short_d16_hi v[22:23], v2, off offset:1024
	v_mul_f32_e32 v2, v3, v5
	v_mul_f32_e32 v2, v162, v2
	v_bfe_u32 v3, v2, 16, 1
	v_mul_f32_e32 v1, v1, v5
	v_add3_u32 v2, v2, v3, s68
	v_mul_f32_e32 v1, v161, v1
	global_store_short_d16_hi v[22:23], v2, off offset:1088
	v_bfe_u32 v2, v1, 16, 1
	v_add3_u32 v1, v1, v2, s68
	v_mul_f32_e32 v2, 0x4b800000, v4
	v_cmp_gt_f32_e32 vcc, s67, v4
	v_mul_f32_e32 v0, v0, v5
	v_mul_f32_e32 v0, v130, v0
	v_cndmask_b32_e32 v2, v4, v2, vcc
	ds_read_b128 v[4:7], v169 offset:64
	global_store_short_d16_hi v[22:23], v1, off offset:1152
	v_bfe_u32 v1, v0, 16, 1
	v_rsq_f32_e32 v34, v2
	v_add3_u32 v0, v0, v1, s68
	global_store_short_d16_hi v[22:23], v0, off offset:1216
	ds_read_b128 v[0:3], v169 offset:96
	s_waitcnt lgkmcnt(1)
; DI unsigned short f2bf(float x) { unsigned u = __float_as_uint(x); u += 0x7fffu + ((u >> 16) & 1u); return (unsigned short)(u >> 16); }
; DI float shx(float v, int mask, int lane) { return __int_as_float(__builtin_amdgcn_ds_bpermute((lane ^ mask) << 2, __float_as_int(v))); }
; DI int crow(int r, int hi) { return (r & 3) + 8 * (r >> 2) + 4 * hi; }
; template <int DQK, int MODE, int LDQ, int LDK, int LDV> ...
;     ...
;     if constexpr (MODE == 2) {
; #pragma unroll
;         for (int r = 0; r < 16; ++r)
; #pragma unroll
;             for (int d0 = 0; d0 < 4; ++d0) s0v[r][d0] = S0[(size_t)(wid * 32 + crow(r, hi)) * 512 + d0 * 32 + r32];
;     }
; #pragma unroll
;     for (int r = 0; r < 16; ++r) { const int orow = wid * 32 + crow(r, hi); const float rl = __builtin_amdgcn_rcpf(li_l[crow(r, hi)]);
;         if constexpr (MODE == 0) {
; #pragma unroll
;             for (int d0 = 0; d0 < 4; ++d0) AOb[(size_t)orow * 1024 + d0 * 32 + r32] = f2bf(o[d0][r] * rl);
;         } else if constexpr (MODE == 1) {
; #pragma unroll
;             for (int d0 = 0; d0 < 4; ++d0) S0[(size_t)orow * 512 + d0 * 32 + r32] = o[d0][r] * rl;
;         } else {
;             float v[4]; float ss = 0.f;
; #pragma unroll
;             for (int d0 = 0; d0 < 4; ++d0) { v[d0] = s0v[r][d0] - lam * (o[d0][r] * rl); ss += v[d0] * v[d0]; }
; #pragma unroll
;             for (int mk = 1; mk <= 16; mk <<= 1) ss += shx(ss, mk, lane2);
;             const float rs = rsqrtf(ss * (1.f / 128.f) + EPS) * 0.8f;
; #pragma unroll
;             for (int d0 = 0; d0 < 4; ++d0) AOb[(size_t)orow * 1024 + d0 * 32 + r32] = f2bf(v[d0] * rs * gout[d0 * 32 + r32]);
;         } }
	v_rcp_f32_e32 v4, v4
	v_mul_f32_e32 v22, 0x45800000, v34
	v_cndmask_b32_e32 v52, v34, v22, vcc
	v_mov_b32_e32 v22, v8
	v_mov_b32_e32 v23, v56
	v_mov_b32_e32 v37, v24
	v_pk_mul_f32 v[22:23], v[22:23], v[4:5] op_sel_hi:[1,0]
	v_pk_mul_f32 v[36:37], v[36:37], v[4:5] op_sel_hi:[1,0]
	v_rcp_f32_e32 v4, v5
	v_mov_b32_e32 v56, v9
	v_mov_b32_e32 v24, v41
	v_pk_fma_f32 v[22:23], v[128:129], v[22:23], v[100:101] neg_lo:[1,0,0] neg_hi:[1,0,0]
	v_pk_mul_f32 v[8:9], v[56:57], v[4:5] op_sel_hi:[1,0]
	v_pk_mul_f32 v[4:5], v[24:25], v[4:5] op_sel_hi:[1,0]
	v_pk_fma_f32 v[8:9], v[128:129], v[8:9], v[96:97] neg_lo:[1,0,0] neg_hi:[1,0,0]
	v_pk_mul_f32 v[34:35], v[22:23], v[22:23]
	v_pk_fma_f32 v[36:37], v[128:129], v[36:37], v[98:99] neg_lo:[1,0,0] neg_hi:[1,0,0]
	v_pk_mul_f32 v[50:51], v[8:9], v[8:9]
	v_pk_fma_f32 v[4:5], v[128:129], v[4:5], v[94:95] neg_lo:[1,0,0] neg_hi:[1,0,0]
	v_pk_mul_f32 v[38:39], v[36:37], v[36:37]
	v_pk_mul_f32 v[24:25], v[4:5], v[4:5]
	v_mov_b32_e32 v40, v50
	v_mov_b32_e32 v41, v34
	v_mov_b32_e32 v34, v51
	v_pk_add_f32 v[34:35], v[40:41], v[34:35]
	v_mov_b32_e32 v40, v25
	v_mov_b32_e32 v41, v39
	v_pk_add_f32 v[34:35], v[40:41], v[34:35]
	v_mov_b32_e32 v25, v38
	v_pk_add_f32 v[24:25], v[24:25], v[34:35]
	ds_bpermute_b32 v35, v164, v25
	ds_bpermute_b32 v34, v164, v24
	v_mul_f32_e32 v40, 0x3f4ccccd, v52
	v_mul_f32_e32 v20, v20, v40
	v_mul_f32_e32 v20, v163, v20
	v_bfe_u32 v41, v20, 16, 1
	s_waitcnt lgkmcnt(0)
	v_pk_add_f32 v[24:25], v[24:25], v[34:35]
	ds_bpermute_b32 v35, v165, v25
	ds_bpermute_b32 v34, v165, v24
	v_lshl_add_u64 v[38:39], v[32:33], 0, v[90:91]
	v_add3_u32 v20, v20, v41, s68
	global_store_short_d16_hi v[38:39], v20, off offset:1024
	v_mul_f32_e32 v41, v21, v40
	s_waitcnt lgkmcnt(0)
	v_pk_add_f32 v[20:21], v[24:25], v[34:35]
	ds_bpermute_b32 v25, v168, v21
	ds_bpermute_b32 v24, v168, v20
	v_mul_f32_e32 v34, v162, v41
	v_bfe_u32 v35, v34, 16, 1
	v_mul_f32_e32 v19, v19, v40
	v_add3_u32 v34, v34, v35, s68
	s_waitcnt lgkmcnt(0)
	v_pk_add_f32 v[20:21], v[20:21], v[24:25]
	ds_bpermute_b32 v25, v167, v21
	ds_bpermute_b32 v24, v167, v20
	v_mul_f32_e32 v19, v161, v19
	global_store_short_d16_hi v[38:39], v34, off offset:1088
	v_bfe_u32 v34, v19, 16, 1
	v_add3_u32 v19, v19, v34, s68
	s_waitcnt lgkmcnt(0)
	v_pk_add_f32 v[20:21], v[20:21], v[24:25]
	ds_bpermute_b32 v25, v166, v21
	ds_bpermute_b32 v24, v166, v20
	v_mul_f32_e32 v18, v18, v40
	global_store_short_d16_hi v[38:39], v19, off offset:1152
	v_mul_f32_e32 v34, v130, v18
	v_bfe_u32 v35, v34, 16, 1
	s_waitcnt lgkmcnt(0)
	v_pk_add_f32 v[18:19], v[20:21], v[24:25]
	v_rcp_f32_e32 v6, v6
	v_pk_fma_f32 v[18:19], v[18:19], s[24:25], v[92:93] op_sel_hi:[1,0,0]
	v_rcp_f32_e32 v0, v0
	v_mul_f32_e32 v20, 0x4b800000, v19
	v_cmp_gt_f32_e32 vcc, s67, v19
	v_rcp_f32_e32 v2, v2
	s_nop 0
	v_cndmask_b32_e32 v19, v19, v20, vcc
	v_rsq_f32_e32 v19, v19
	v_add3_u32 v20, v34, v35, s68
	global_store_short_d16_hi v[38:39], v20, off offset:1216
	v_lshl_add_u64 v[20:21], v[32:33], 0, v[86:87]
	v_mul_f32_e32 v24, 0x45800000, v19
	v_cndmask_b32_e32 v19, v19, v24, vcc
	v_mul_f32_e32 v19, 0x3f4ccccd, v19
	v_mul_f32_e32 v22, v22, v19
	v_mul_f32_e32 v22, v163, v22
	v_bfe_u32 v24, v22, 16, 1
	v_add3_u32 v22, v22, v24, s68
	global_store_short_d16_hi v[20:21], v22, off offset:1024
	v_mul_f32_e32 v22, v23, v19
	v_mul_f32_e32 v22, v162, v22
	v_bfe_u32 v23, v22, 16, 1
	v_add3_u32 v22, v22, v23, s68
	global_store_short_d16_hi v[20:21], v22, off offset:1088
	v_mul_f32_e32 v22, v37, v19
	v_mul_f32_e32 v22, v161, v22
	v_bfe_u32 v23, v22, 16, 1
	v_add3_u32 v22, v22, v23, s68
	global_store_short_d16_hi v[20:21], v22, off offset:1152
	v_mul_f32_e32 v22, 0x4b800000, v18
	v_cmp_gt_f32_e32 vcc, s67, v18
	v_mul_f32_e32 v19, v36, v19
	v_mul_f32_e32 v19, v130, v19
	v_cndmask_b32_e32 v18, v18, v22, vcc
	v_rsq_f32_e32 v18, v18
	v_bfe_u32 v22, v19, 16, 1
	v_add3_u32 v19, v19, v22, s68
	global_store_short_d16_hi v[20:21], v19, off offset:1216
	v_mul_f32_e32 v19, 0x45800000, v18
	v_cndmask_b32_e32 v38, v18, v19, vcc
	v_mov_b32_e32 v18, v10
	v_mov_b32_e32 v19, v58
	v_mov_b32_e32 v22, v42
	v_mov_b32_e32 v23, v26
	v_pk_mul_f32 v[18:19], v[18:19], v[6:7] op_sel_hi:[1,0]
	v_pk_mul_f32 v[22:23], v[22:23], v[6:7] op_sel_hi:[1,0]
	v_rcp_f32_e32 v6, v7
	v_mov_b32_e32 v58, v11
	v_mov_b32_e32 v26, v43
	v_pk_fma_f32 v[18:19], v[128:129], v[18:19], v[88:89] neg_lo:[1,0,0] neg_hi:[1,0,0]
	v_pk_mul_f32 v[10:11], v[58:59], v[6:7] op_sel_hi:[1,0]
	v_pk_mul_f32 v[6:7], v[26:27], v[6:7] op_sel_hi:[1,0]
	v_pk_fma_f32 v[10:11], v[128:129], v[10:11], v[82:83] neg_lo:[1,0,0] neg_hi:[1,0,0]
	v_pk_mul_f32 v[20:21], v[18:19], v[18:19]
	v_pk_fma_f32 v[22:23], v[128:129], v[22:23], v[84:85] neg_lo:[1,0,0] neg_hi:[1,0,0]
	v_pk_mul_f32 v[34:35], v[10:11], v[10:11]
	v_pk_fma_f32 v[6:7], v[128:129], v[6:7], v[80:81] neg_lo:[1,0,0] neg_hi:[1,0,0]
	v_pk_mul_f32 v[24:25], v[22:23], v[22:23]
	v_pk_mul_f32 v[26:27], v[6:7], v[6:7]
	v_mov_b32_e32 v36, v34
	v_mov_b32_e32 v37, v20
	v_mov_b32_e32 v20, v35
	v_pk_add_f32 v[20:21], v[36:37], v[20:21]
	v_mov_b32_e32 v34, v27
	v_mov_b32_e32 v35, v25
	v_pk_add_f32 v[20:21], v[34:35], v[20:21]
	v_mov_b32_e32 v27, v24
	v_pk_add_f32 v[20:21], v[26:27], v[20:21]
	ds_bpermute_b32 v25, v164, v21
	ds_bpermute_b32 v24, v164, v20
	v_mul_f32_e32 v34, 0x3f4ccccd, v38
	v_mul_f32_e32 v8, v8, v34
	v_mul_f32_e32 v8, v163, v8
	v_bfe_u32 v35, v8, 16, 1
	s_waitcnt lgkmcnt(0)
	v_pk_add_f32 v[20:21], v[20:21], v[24:25]
	ds_bpermute_b32 v25, v165, v21
	ds_bpermute_b32 v24, v165, v20
	v_lshl_add_u64 v[26:27], v[32:33], 0, v[78:79]
	v_add3_u32 v8, v8, v35, s68
	global_store_short_d16_hi v[26:27], v8, off offset:1024
	v_mul_f32_e32 v35, v9, v34
	s_waitcnt lgkmcnt(0)
; DI unsigned short f2bf(float x) { unsigned u = __float_as_uint(x); u += 0x7fffu + ((u >> 16) & 1u); return (unsigned short)(u >> 16); }
; DI float shx(float v, int mask, int lane) { return __int_as_float(__builtin_amdgcn_ds_bpermute((lane ^ mask) << 2, __float_as_int(v))); }
; DI int crow(int r, int hi) { return (r & 3) + 8 * (r >> 2) + 4 * hi; }
; template <int DQK, int MODE, int LDQ, int LDK, int LDV> ...
;     ...
;     if constexpr (MODE == 2) {
; #pragma unroll
;         for (int r = 0; r < 16; ++r)
; #pragma unroll
;             for (int d0 = 0; d0 < 4; ++d0) s0v[r][d0] = S0[(size_t)(wid * 32 + crow(r, hi)) * 512 + d0 * 32 + r32];
;     }
; #pragma unroll
;     for (int r = 0; r < 16; ++r) { const int orow = wid * 32 + crow(r, hi); const float rl = __builtin_amdgcn_rcpf(li_l[crow(r, hi)]);
;         if constexpr (MODE == 0) {
; #pragma unroll
;             for (int d0 = 0; d0 < 4; ++d0) AOb[(size_t)orow * 1024 + d0 * 32 + r32] = f2bf(o[d0][r] * rl);
;         } else if constexpr (MODE == 1) {
; #pragma unroll
;             for (int d0 = 0; d0 < 4; ++d0) S0[(size_t)orow * 512 + d0 * 32 + r32] = o[d0][r] * rl;
;         } else {
;             float v[4]; float ss = 0.f;
; #pragma unroll
;             for (int d0 = 0; d0 < 4; ++d0) { v[d0] = s0v[r][d0] - lam * (o[d0][r] * rl); ss += v[d0] * v[d0]; }
; #pragma unroll
;             for (int mk = 1; mk <= 16; mk <<= 1) ss += shx(ss, mk, lane2);
;             const float rs = rsqrtf(ss * (1.f / 128.f) + EPS) * 0.8f;
; #pragma unroll
;             for (int d0 = 0; d0 < 4; ++d0) AOb[(size_t)orow * 1024 + d0 * 32 + r32] = f2bf(v[d0] * rs * gout[d0 * 32 + r32]);
;         } }
	v_pk_add_f32 v[8:9], v[20:21], v[24:25]
	ds_bpermute_b32 v21, v168, v9
	ds_bpermute_b32 v20, v168, v8
	v_mul_f32_e32 v24, v162, v35
	v_bfe_u32 v25, v24, 16, 1
	v_mul_f32_e32 v5, v5, v34
	v_add3_u32 v24, v24, v25, s68
	s_waitcnt lgkmcnt(0)
	v_pk_add_f32 v[8:9], v[8:9], v[20:21]
	ds_bpermute_b32 v21, v167, v9
	ds_bpermute_b32 v20, v167, v8
	v_mul_f32_e32 v5, v161, v5
	global_store_short_d16_hi v[26:27], v24, off offset:1088
	v_bfe_u32 v24, v5, 16, 1
	v_add3_u32 v5, v5, v24, s68
	s_waitcnt lgkmcnt(0)
	v_pk_add_f32 v[8:9], v[8:9], v[20:21]
	ds_bpermute_b32 v21, v166, v9
	ds_bpermute_b32 v20, v166, v8
	v_mul_f32_e32 v4, v4, v34
	global_store_short_d16_hi v[26:27], v5, off offset:1152
	v_mul_f32_e32 v24, v130, v4
	v_bfe_u32 v25, v24, 16, 1
	s_waitcnt lgkmcnt(0)
	v_pk_add_f32 v[4:5], v[8:9], v[20:21]
	s_nop 0
	v_pk_fma_f32 v[4:5], v[4:5], s[24:25], v[92:93] op_sel_hi:[1,0,0]
	s_nop 0
	v_mul_f32_e32 v8, 0x4b800000, v5
	v_cmp_gt_f32_e32 vcc, s67, v5
	s_nop 1
	v_cndmask_b32_e32 v5, v5, v8, vcc
	v_rsq_f32_e32 v5, v5
	v_add3_u32 v8, v24, v25, s68
	global_store_short_d16_hi v[26:27], v8, off offset:1216
	v_lshl_add_u64 v[8:9], v[32:33], 0, v[76:77]
	v_mul_f32_e32 v20, 0x45800000, v5
	v_cndmask_b32_e32 v5, v5, v20, vcc
	v_mul_f32_e32 v5, 0x3f4ccccd, v5
	v_mul_f32_e32 v18, v18, v5
	v_mul_f32_e32 v18, v163, v18
	v_bfe_u32 v20, v18, 16, 1
	v_add3_u32 v18, v18, v20, s68
	global_store_short_d16_hi v[8:9], v18, off offset:1024
	v_mul_f32_e32 v18, v19, v5
	v_mul_f32_e32 v18, v162, v18
	v_bfe_u32 v19, v18, 16, 1
	v_add3_u32 v18, v18, v19, s68
	global_store_short_d16_hi v[8:9], v18, off offset:1088
	v_mul_f32_e32 v18, v23, v5
	v_mul_f32_e32 v18, v161, v18
	v_bfe_u32 v19, v18, 16, 1
	v_add3_u32 v18, v18, v19, s68
	global_store_short_d16_hi v[8:9], v18, off offset:1152
	v_mul_f32_e32 v18, 0x4b800000, v4
	v_cmp_gt_f32_e32 vcc, s67, v4
	v_mul_f32_e32 v5, v22, v5
	v_mul_f32_e32 v5, v130, v5
	v_cndmask_b32_e32 v4, v4, v18, vcc
	v_rsq_f32_e32 v4, v4
	v_bfe_u32 v18, v5, 16, 1
	v_add3_u32 v5, v5, v18, s68
	global_store_short_d16_hi v[8:9], v5, off offset:1216
	v_mul_f32_e32 v5, 0x45800000, v4
	v_cndmask_b32_e32 v34, v4, v5, vcc
	v_mov_b32_e32 v4, v12
	v_mov_b32_e32 v5, v60
	v_mov_b32_e32 v18, v44
	v_mov_b32_e32 v19, v28
	v_pk_mul_f32 v[4:5], v[4:5], v[0:1] op_sel_hi:[1,0]
	v_pk_mul_f32 v[18:19], v[18:19], v[0:1] op_sel_hi:[1,0]
	v_rcp_f32_e32 v0, v1
	v_mov_b32_e32 v60, v13
	v_mov_b32_e32 v28, v45
	s_waitcnt vmcnt(58)
	v_pk_fma_f32 v[4:5], v[128:129], v[4:5], v[116:117] neg_lo:[1,0,0] neg_hi:[1,0,0]
	v_pk_mul_f32 v[12:13], v[60:61], v[0:1] op_sel_hi:[1,0]
	v_pk_mul_f32 v[0:1], v[28:29], v[0:1] op_sel_hi:[1,0]
	s_waitcnt vmcnt(54)
	v_pk_fma_f32 v[12:13], v[128:129], v[12:13], v[112:113] neg_lo:[1,0,0] neg_hi:[1,0,0]
	v_pk_mul_f32 v[8:9], v[4:5], v[4:5]
	v_pk_fma_f32 v[18:19], v[128:129], v[18:19], v[114:115] neg_lo:[1,0,0] neg_hi:[1,0,0]
	v_pk_mul_f32 v[22:23], v[12:13], v[12:13]
	s_waitcnt vmcnt(52)
	v_pk_fma_f32 v[0:1], v[128:129], v[0:1], v[110:111] neg_lo:[1,0,0] neg_hi:[1,0,0]
	v_pk_mul_f32 v[20:21], v[18:19], v[18:19]
	v_pk_mul_f32 v[24:25], v[0:1], v[0:1]
	v_mov_b32_e32 v26, v22
	v_mov_b32_e32 v27, v8
	v_mov_b32_e32 v8, v23
	v_pk_add_f32 v[8:9], v[26:27], v[8:9]
	v_mov_b32_e32 v22, v25
	v_mov_b32_e32 v23, v21
	v_pk_add_f32 v[8:9], v[22:23], v[8:9]
	v_mov_b32_e32 v25, v20
	v_pk_add_f32 v[8:9], v[24:25], v[8:9]
	ds_bpermute_b32 v21, v164, v9
	ds_bpermute_b32 v20, v164, v8
	v_mul_f32_e32 v24, 0x3f4ccccd, v34
	v_mul_f32_e32 v10, v10, v24
	v_mul_f32_e32 v10, v163, v10
	v_bfe_u32 v25, v10, 16, 1
	s_waitcnt lgkmcnt(0)
	v_pk_add_f32 v[8:9], v[8:9], v[20:21]
	ds_bpermute_b32 v21, v165, v9
	ds_bpermute_b32 v20, v165, v8
	v_lshl_add_u64 v[22:23], v[32:33], 0, v[72:73]
	v_add3_u32 v10, v10, v25, s68
	global_store_short_d16_hi v[22:23], v10, off offset:1024
	v_mul_f32_e32 v25, v11, v24
	s_waitcnt lgkmcnt(0)
	v_pk_add_f32 v[8:9], v[8:9], v[20:21]
	ds_bpermute_b32 v11, v168, v9
	ds_bpermute_b32 v10, v168, v8
	v_mul_f32_e32 v20, v162, v25
	v_bfe_u32 v21, v20, 16, 1
	v_mul_f32_e32 v7, v7, v24
	v_add3_u32 v20, v20, v21, s68
	s_waitcnt lgkmcnt(0)
	v_pk_add_f32 v[8:9], v[8:9], v[10:11]
	ds_bpermute_b32 v11, v167, v9
	ds_bpermute_b32 v10, v167, v8
	v_mul_f32_e32 v7, v161, v7
	global_store_short_d16_hi v[22:23], v20, off offset:1088
	v_bfe_u32 v20, v7, 16, 1
	v_add3_u32 v7, v7, v20, s68
	s_waitcnt lgkmcnt(0)
	v_pk_add_f32 v[8:9], v[8:9], v[10:11]
	ds_bpermute_b32 v11, v166, v9
	ds_bpermute_b32 v10, v166, v8
	v_mul_f32_e32 v6, v6, v24
	global_store_short_d16_hi v[22:23], v7, off offset:1152
	v_mul_f32_e32 v20, v130, v6
	v_bfe_u32 v21, v20, 16, 1
	s_waitcnt lgkmcnt(0)
; DI unsigned short f2bf(float x) { unsigned u = __float_as_uint(x); u += 0x7fffu + ((u >> 16) & 1u); return (unsigned short)(u >> 16); }
; DI float shx(float v, int mask, int lane) { return __int_as_float(__builtin_amdgcn_ds_bpermute((lane ^ mask) << 2, __float_as_int(v))); }
; DI int crow(int r, int hi) { return (r & 3) + 8 * (r >> 2) + 4 * hi; }
; template <int DQK, int MODE, int LDQ, int LDK, int LDV> ...
;     ...
;     if constexpr (MODE == 2) {
; #pragma unroll
;         for (int r = 0; r < 16; ++r)
; #pragma unroll
;             for (int d0 = 0; d0 < 4; ++d0) s0v[r][d0] = S0[(size_t)(wid * 32 + crow(r, hi)) * 512 + d0 * 32 + r32];
;     }
; #pragma unroll
;     for (int r = 0; r < 16; ++r) { const int orow = wid * 32 + crow(r, hi); const float rl = __builtin_amdgcn_rcpf(li_l[crow(r, hi)]);
;         if constexpr (MODE == 0) {
; #pragma unroll
;             for (int d0 = 0; d0 < 4; ++d0) AOb[(size_t)orow * 1024 + d0 * 32 + r32] = f2bf(o[d0][r] * rl);
;         } else if constexpr (MODE == 1) {
; #pragma unroll
;             for (int d0 = 0; d0 < 4; ++d0) S0[(size_t)orow * 512 + d0 * 32 + r32] = o[d0][r] * rl;
;         } else {
;             float v[4]; float ss = 0.f;
; #pragma unroll
;             for (int d0 = 0; d0 < 4; ++d0) { v[d0] = s0v[r][d0] - lam * (o[d0][r] * rl); ss += v[d0] * v[d0]; }
; #pragma unroll
;             for (int mk = 1; mk <= 16; mk <<= 1) ss += shx(ss, mk, lane2);
;             const float rs = rsqrtf(ss * (1.f / 128.f) + EPS) * 0.8f;
; #pragma unroll
;             for (int d0 = 0; d0 < 4; ++d0) AOb[(size_t)orow * 1024 + d0 * 32 + r32] = f2bf(v[d0] * rs * gout[d0 * 32 + r32]);
;         } }
; DI void phase4(const Params& p, LAS unsigned char* lds, int wv) {
;     ...
;             __syncthreads();
	v_pk_add_f32 v[6:7], v[8:9], v[10:11]
	s_nop 0
	v_pk_fma_f32 v[6:7], v[6:7], s[24:25], v[92:93] op_sel_hi:[1,0,0]
	s_nop 0
	v_mul_f32_e32 v8, 0x4b800000, v7
	v_cmp_gt_f32_e32 vcc, s67, v7
	s_nop 1
	v_cndmask_b32_e32 v7, v7, v8, vcc
	v_rsq_f32_e32 v7, v7
	v_add3_u32 v8, v20, v21, s68
	global_store_short_d16_hi v[22:23], v8, off offset:1216
	v_lshl_add_u64 v[8:9], v[32:33], 0, v[74:75]
	v_mul_f32_e32 v10, 0x45800000, v7
	v_cndmask_b32_e32 v7, v7, v10, vcc
	v_mul_f32_e32 v7, 0x3f4ccccd, v7
	v_mul_f32_e32 v4, v4, v7
	v_mul_f32_e32 v4, v163, v4
	v_bfe_u32 v10, v4, 16, 1
	v_add3_u32 v4, v4, v10, s68
	global_store_short_d16_hi v[8:9], v4, off offset:1024
	v_mul_f32_e32 v4, v5, v7
	v_mul_f32_e32 v4, v162, v4
	v_bfe_u32 v5, v4, 16, 1
	v_add3_u32 v4, v4, v5, s68
	global_store_short_d16_hi v[8:9], v4, off offset:1088
	v_mul_f32_e32 v4, v19, v7
	v_mul_f32_e32 v4, v161, v4
	v_bfe_u32 v5, v4, 16, 1
	v_add3_u32 v4, v4, v5, s68
	v_mul_f32_e32 v5, 0x4b800000, v6
	v_cmp_gt_f32_e32 vcc, s67, v6
	global_store_short_d16_hi v[8:9], v4, off offset:1152
	v_mul_f32_e32 v4, v18, v7
	v_cndmask_b32_e32 v5, v6, v5, vcc
	v_rsq_f32_e32 v5, v5
	v_mul_f32_e32 v4, v130, v4
	v_bfe_u32 v6, v4, 16, 1
	v_add3_u32 v4, v4, v6, s68
	global_store_short_d16_hi v[8:9], v4, off offset:1216
	v_mul_f32_e32 v4, 0x45800000, v5
	v_cndmask_b32_e32 v24, v5, v4, vcc
	v_mov_b32_e32 v4, v14
	v_mov_b32_e32 v5, v62
	v_mov_b32_e32 v8, v46
	v_mov_b32_e32 v9, v30
	v_pk_mul_f32 v[4:5], v[4:5], v[2:3] op_sel_hi:[1,0]
	v_pk_mul_f32 v[8:9], v[8:9], v[2:3] op_sel_hi:[1,0]
	v_rcp_f32_e32 v2, v3
	v_mov_b32_e32 v62, v15
	v_mov_b32_e32 v30, v47
	s_waitcnt vmcnt(58)
	v_pk_fma_f32 v[4:5], v[128:129], v[4:5], v[108:109] neg_lo:[1,0,0] neg_hi:[1,0,0]
	v_pk_mul_f32 v[14:15], v[62:63], v[2:3] op_sel_hi:[1,0]
	v_pk_mul_f32 v[2:3], v[30:31], v[2:3] op_sel_hi:[1,0]
	s_waitcnt vmcnt(54)
	v_pk_fma_f32 v[14:15], v[128:129], v[14:15], v[104:105] neg_lo:[1,0,0] neg_hi:[1,0,0]
	v_pk_mul_f32 v[6:7], v[4:5], v[4:5]
	v_pk_fma_f32 v[8:9], v[128:129], v[8:9], v[106:107] neg_lo:[1,0,0] neg_hi:[1,0,0]
	v_pk_mul_f32 v[18:19], v[14:15], v[14:15]
	s_waitcnt vmcnt(52)
	v_pk_fma_f32 v[2:3], v[128:129], v[2:3], v[102:103] neg_lo:[1,0,0] neg_hi:[1,0,0]
	v_pk_mul_f32 v[10:11], v[8:9], v[8:9]
	v_pk_mul_f32 v[20:21], v[2:3], v[2:3]
	v_mov_b32_e32 v22, v18
	v_mov_b32_e32 v23, v6
	v_mov_b32_e32 v6, v19
	v_pk_add_f32 v[6:7], v[22:23], v[6:7]
	v_mov_b32_e32 v18, v21
	v_mov_b32_e32 v19, v11
	v_pk_add_f32 v[6:7], v[18:19], v[6:7]
	v_mov_b32_e32 v21, v10
	v_pk_add_f32 v[6:7], v[20:21], v[6:7]
	ds_bpermute_b32 v11, v164, v7
	ds_bpermute_b32 v10, v164, v6
	v_mul_f32_e32 v20, 0x3f4ccccd, v24
	v_mul_f32_e32 v12, v12, v20
	v_mul_f32_e32 v12, v163, v12
	v_bfe_u32 v21, v12, 16, 1
	s_waitcnt lgkmcnt(0)
	v_pk_add_f32 v[6:7], v[6:7], v[10:11]
	ds_bpermute_b32 v11, v165, v7
	ds_bpermute_b32 v10, v165, v6
	v_lshl_add_u64 v[18:19], v[32:33], 0, v[64:65]
	v_add3_u32 v12, v12, v21, s68
	global_store_short_d16_hi v[18:19], v12, off offset:1024
	v_mul_f32_e32 v12, v13, v20
	s_waitcnt lgkmcnt(0)
	v_pk_add_f32 v[6:7], v[6:7], v[10:11]
	ds_bpermute_b32 v11, v168, v7
	ds_bpermute_b32 v10, v168, v6
	v_mul_f32_e32 v12, v162, v12
	v_bfe_u32 v13, v12, 16, 1
	v_mul_f32_e32 v1, v1, v20
	v_add3_u32 v12, v12, v13, s68
	s_waitcnt lgkmcnt(0)
	v_pk_add_f32 v[6:7], v[6:7], v[10:11]
	ds_bpermute_b32 v11, v167, v7
	ds_bpermute_b32 v10, v167, v6
	v_mul_f32_e32 v1, v161, v1
	global_store_short_d16_hi v[18:19], v12, off offset:1088
	v_bfe_u32 v12, v1, 16, 1
	v_add3_u32 v1, v1, v12, s68
	s_waitcnt lgkmcnt(0)
	v_pk_add_f32 v[6:7], v[6:7], v[10:11]
	ds_bpermute_b32 v11, v166, v7
	ds_bpermute_b32 v10, v166, v6
	v_mul_f32_e32 v0, v0, v20
	global_store_short_d16_hi v[18:19], v1, off offset:1152
	v_mul_f32_e32 v12, v130, v0
	v_bfe_u32 v13, v12, 16, 1
	s_waitcnt lgkmcnt(0)
	v_pk_add_f32 v[0:1], v[6:7], v[10:11]
	s_nop 0
	v_pk_fma_f32 v[0:1], v[0:1], s[24:25], v[92:93] op_sel_hi:[1,0,0]
	s_nop 0
	v_mul_f32_e32 v6, 0x4b800000, v1
	v_cmp_gt_f32_e32 vcc, s67, v1
	s_nop 1
	v_cndmask_b32_e32 v1, v1, v6, vcc
	v_rsq_f32_e32 v1, v1
	v_add3_u32 v6, v12, v13, s68
	global_store_short_d16_hi v[18:19], v6, off offset:1216
	v_lshl_add_u64 v[6:7], v[32:33], 0, v[48:49]
	v_mul_f32_e32 v10, 0x45800000, v1
	v_cndmask_b32_e32 v1, v1, v10, vcc
	v_mul_f32_e32 v1, 0x3f4ccccd, v1
	v_mul_f32_e32 v4, v4, v1
	v_mul_f32_e32 v4, v163, v4
	v_bfe_u32 v10, v4, 16, 1
	v_add3_u32 v4, v4, v10, s68
	global_store_short_d16_hi v[6:7], v4, off offset:1024
	v_mul_f32_e32 v4, v5, v1
	v_mul_f32_e32 v4, v162, v4
	v_bfe_u32 v5, v4, 16, 1
	v_add3_u32 v4, v4, v5, s68
	global_store_short_d16_hi v[6:7], v4, off offset:1088
	v_mul_f32_e32 v4, v9, v1
	v_mul_f32_e32 v4, v161, v4
	v_bfe_u32 v5, v4, 16, 1
	v_add3_u32 v4, v4, v5, s68
	global_store_short_d16_hi v[6:7], v4, off offset:1152
	v_mul_f32_e32 v4, 0x4b800000, v0
	v_cmp_gt_f32_e32 vcc, s67, v0
	v_mul_f32_e32 v1, v8, v1
	v_mul_f32_e32 v1, v130, v1
	v_cndmask_b32_e32 v0, v0, v4, vcc
	v_rsq_f32_e32 v0, v0
	v_bfe_u32 v4, v1, 16, 1
	v_add3_u32 v1, v1, v4, s68
	global_store_short_d16_hi v[6:7], v1, off offset:1216
	v_mul_f32_e32 v1, 0x45800000, v0
	v_cndmask_b32_e32 v0, v0, v1, vcc
	v_mul_f32_e32 v4, 0x3f4ccccd, v0
	v_mul_f32_e32 v5, v14, v4
	v_mul_f32_e32 v5, v163, v5
	v_bfe_u32 v6, v5, 16, 1
	v_lshl_add_u64 v[0:1], v[32:33], 0, v[16:17]
	v_add3_u32 v5, v5, v6, s68
	global_store_short_d16_hi v[0:1], v5, off offset:1024
	v_mul_f32_e32 v5, v15, v4
	v_mul_f32_e32 v5, v162, v5
	v_bfe_u32 v6, v5, 16, 1
	v_mul_f32_e32 v3, v3, v4
	v_add3_u32 v5, v5, v6, s68
	v_mul_f32_e32 v3, v161, v3
	global_store_short_d16_hi v[0:1], v5, off offset:1088
	v_bfe_u32 v5, v3, 16, 1
	v_mul_f32_e32 v2, v2, v4
	v_add3_u32 v3, v3, v5, s68
	v_mul_f32_e32 v2, v130, v2
	global_store_short_d16_hi v[0:1], v3, off offset:1152
	v_bfe_u32 v3, v2, 16, 1
	v_add3_u32 v2, v2, v3, s68
	global_store_short_d16_hi v[0:1], v2, off offset:1216
	s_waitcnt vmcnt(63) expcnt(7) lgkmcnt(15)
	s_barrier

; #define LAS __attribute__((address_space(3)))
; DI void expsum(f32x16& p, float& l_reg, bf16x8& pa0, bf16x8& pa1) {
; #pragma unroll
;     for (int r = 0; r < 16; ++r) p[r] = __builtin_amdgcn_exp2f(p[r]);
;     float ps = 0.f;
; #pragma unroll
;     for (int r = 0; r < 16; ++r) ps += p[r];
;     l_reg += ps; asm volatile("" : "+v"(l_reg));
;     ...
;     ATT_PK4(p, 0, pa0); ATT_PK4(p, 8, pa1);
;     ...
; }
; DI int v_rd_base(int lane) { return ((lane & 3) << 3) | (((lane >> 2) & 3) << 6) | (((lane >> 4) & 1) << 5) | (((lane >> 5) & 1) << 8); }
; template <int OFF> DI s16x4 tr_read(int vb) { s16x4 r; asm volatile("ds_read_b64_tr_b16 %0, %1 offset:%2" : "=&v"(r) : "v"(vb), "i"(OFF) : "memory"); return r; }
; template <int H> DI void v_reads(s16x4* vf, int vb) {
;     vf[0] = tr_read<v_rd_off(0, 2 * H, 0)>(vb); vf[1] = tr_read<v_rd_off(0, 2 * H, 1)>(vb); vf[2] = tr_read<v_rd_off(0, 2 * H + 1, 0)>(vb); vf[3] = tr_read<v_rd_off(0, 2 * H + 1, 1)>(vb);
;     vf[4] = tr_read<v_rd_off(1, 2 * H, 0)>(vb); vf[5] = tr_read<v_rd_off(1, 2 * H, 1)>(vb); vf[6] = tr_read<v_rd_off(1, 2 * H + 1, 0)>(vb); vf[7] = tr_read<v_rd_off(1, 2 * H + 1, 1)>(vb);
;     vf[8] = tr_read<v_rd_off(2, 2 * H, 0)>(vb); vf[9] = tr_read<v_rd_off(2, 2 * H, 1)>(vb); vf[10] = tr_read<v_rd_off(2, 2 * H + 1, 0)>(vb); vf[11] = tr_read<v_rd_off(2, 2 * H + 1, 1)>(vb);
;     vf[12] = tr_read<v_rd_off(3, 2 * H, 0)>(vb); vf[13] = tr_read<v_rd_off(3, 2 * H, 1)>(vb); vf[14] = tr_read<v_rd_off(3, 2 * H + 1, 0)>(vb); vf[15] = tr_read<v_rd_off(3, 2 * H + 1, 1)>(vb);
; }
; DI void pv_mma(f32x16* o, const s16x4* vf, bf16x8 pa0, bf16x8 pa1) {
;     ...
; #pragma unroll
;     for (int d0 = 0; d0 < 4; ++d0) {
;         o[d0] = __builtin_amdgcn_mfma_f32_32x32x16_bf16(pa0, ATT_PK(vf[4 * d0], vf[4 * d0 + 1]), o[d0], 0, 0, 0);
;         o[d0] = __builtin_amdgcn_mfma_f32_32x32x16_bf16(pa1, ATT_PK(vf[4 * d0 + 2], vf[4 * d0 + 3]), o[d0], 0, 0, 0); }
;     ...
; }
; template <int DQK, int D0A, int D0B> DI void k_reads(bf16x8* kf, const LAS unsigned char* Ks, int half, int r32, int hi) {
; #pragma unroll
;     for (int d0 = D0A; d0 < D0B; ++d0) kf[d0 - D0A] = *(const LAS bf16x8*)(Ks + half * (32 * DQK * 2) + kswz<DQK>(r32, (d0 * 16 + hi * 8) * 2));
; }
; template <int D0A, int D0B> DI void qk_mma(f32x16& p, const bf16x8* kf, const bf16x8* qr) {
; #pragma unroll
;     for (int d0 = D0A; d0 < D0B; ++d0) {
.Lstg_mla_top_2:
	s_setprio 0
	s_mov_b32 m0, s1
	s_mov_b32 s0, s5
	s_mov_b32 s5, s44
	s_mov_b32 s44, s4
	s_lshl_b32 s4, s4, 14
	global_load_lds_dwordx4 v136, s[34:35]
	s_add_i32 m0, s1, 0x2000
	s_add_i32 s4, s52, s4
	global_load_lds_dwordx4 v138, s[34:35]
	s_add_i32 m0, s1, 0x4000
	s_add_i32 s6, s4, 0x400
	global_load_lds_dwordx4 v140, s[34:35]
	s_mov_b32 m0, s4
	s_add_i32 s1, s43, -3
	global_load_lds_dwordx4 v144, s[34:35]
	s_mov_b32 m0, s6
	s_nop 0
	global_load_lds_dwordx4 v142, s[34:35]
	s_and_b32 s1, s1, 3
	s_mulk_i32 s1, 0x6000
	v_add_u32_e32 v246, s1, v158
	v_add_u32_e32 v174, v246, v151
	v_add_u32_e32 v178, v246, v149
	v_add_u32_e32 v182, v246, v148
	v_add_u32_e32 v186, v246, v147
	s_lshl_b32 s1, s0, 14
	ds_read_b128 v[190:193], v174 offset:12416
	ds_read_b128 v[194:197], v178 offset:12416
	ds_read_b128 v[174:177], v174 offset:12288
	ds_read_b128 v[178:181], v178 offset:12288
	ds_read_b128 v[182:185], v182 offset:12288
	ds_read_b128 v[186:189], v186 offset:12288
	v_add_u32_e32 v254, s1, v130
	ds_read_b64_tr_b16 v[198:199], v254 offset:0
	ds_read_b64_tr_b16 v[200:201], v254 offset:0x800
	ds_read_b64_tr_b16 v[202:203], v254 offset:0x1000
	ds_read_b64_tr_b16 v[204:205], v254 offset:0x1800
	ds_read_b64_tr_b16 v[206:207], v254 offset:0x200
	ds_read_b64_tr_b16 v[208:209], v254 offset:0xa00
	ds_read_b64_tr_b16 v[210:211], v254 offset:0x1200
	ds_read_b64_tr_b16 v[212:213], v254 offset:0x1a00
	ds_read_b64_tr_b16 v[214:215], v254 offset:0x400
	ds_read_b64_tr_b16 v[216:217], v254 offset:0xc00
	ds_read_b64_tr_b16 v[218:219], v254 offset:0x1400
	ds_read_b64_tr_b16 v[220:221], v254 offset:0x1c00
	ds_read_b64_tr_b16 v[222:223], v254 offset:0x600
	ds_read_b64_tr_b16 v[224:225], v254 offset:0xe00
	ds_read_b64_tr_b16 v[226:227], v254 offset:0x1600
	ds_read_b64_tr_b16 v[228:229], v254 offset:0x1e00
	v_exp_f32_e32 v64, v64
	v_exp_f32_e32 v65, v65
	v_exp_f32_e32 v66, v66
	v_exp_f32_e32 v67, v67
	v_exp_f32_e32 v68, v68
	v_exp_f32_e32 v69, v69
	v_add_f32_e32 v230, v65, v64
	v_exp_f32_e32 v70, v70
	v_add_f32_e32 v230, v66, v230
	v_exp_f32_e32 v71, v71
	v_add_f32_e32 v230, v67, v230
	v_exp_f32_e32 v72, v72
	v_add_f32_e32 v230, v68, v230
	v_exp_f32_e32 v73, v73
	v_add_f32_e32 v230, v69, v230
	v_exp_f32_e32 v74, v74
	v_add_f32_e32 v230, v70, v230
	v_exp_f32_e32 v75, v75
	v_add_f32_e32 v230, v71, v230
	v_exp_f32_e32 v76, v76
	v_add_f32_e32 v230, v72, v230
	v_exp_f32_e32 v77, v77
	v_add_f32_e32 v230, v73, v230
	v_exp_f32_e32 v78, v78
	v_add_f32_e32 v230, v74, v230
	v_exp_f32_e32 v79, v79
	v_add_f32_e32 v230, v75, v230
	v_add_f32_e32 v230, v76, v230
	v_add_f32_e32 v230, v77, v230
	v_add_f32_e32 v230, v78, v230
	v_add_f32_e32 v230, v79, v230
	v_add_f32_e32 v173, v173, v230
	s_setprio 2
	v_cvt_pk_bf16_f32 v64, v64, v65
	v_cvt_pk_bf16_f32 v65, v66, v67
	v_cvt_pk_bf16_f32 v66, v68, v69
	v_cvt_pk_bf16_f32 v67, v70, v71
	v_cvt_pk_bf16_f32 v68, v72, v73
	v_cvt_pk_bf16_f32 v69, v74, v75
	v_cvt_pk_bf16_f32 v70, v76, v77
	v_cvt_pk_bf16_f32 v71, v78, v79
	s_nop 0
	v_permlane32_swap_b32_e32 v64, v66
	v_permlane32_swap_b32_e32 v65, v67
	v_permlane32_swap_b32_e32 v68, v70
	v_permlane32_swap_b32_e32 v69, v71
	s_waitcnt lgkmcnt(0)
	v_add_u32_e32 v72, v246, v151
	v_add_u32_e32 v73, v246, v149
	v_add_u32_e32 v74, v246, v148
	v_add_u32_e32 v75, v246, v147
	ds_read_b128 v[230:233], v74 offset:12416
	ds_read_b128 v[234:237], v75 offset:12416
	ds_read_b128 v[238:241], v72 offset:12544
	ds_read_b128 v[242:245], v73 offset:12544
	ds_read_b128 v[246:249], v74 offset:12544
	ds_read_b128 v[250:253], v75 offset:12544
	s_setprio 1
	v_mfma_f32_32x32x16_bf16 v[48:63], v[64:67], v[198:201], v[48:63]
	v_mfma_f32_32x32x16_bf16 v[32:47], v[64:67], v[206:209], v[32:47]
	v_mfma_f32_32x32x16_bf16 v[16:31], v[64:67], v[214:217], v[16:31]
	v_mfma_f32_32x32x16_bf16 v[0:15], v[64:67], v[222:225], v[0:15]
	v_mfma_f32_32x32x16_bf16 v[48:63], v[68:71], v[202:205], v[48:63]
	v_mfma_f32_32x32x16_bf16 v[32:47], v[68:71], v[210:213], v[32:47]
	v_mfma_f32_32x32x16_bf16 v[16:31], v[68:71], v[218:221], v[16:31]
	v_mfma_f32_32x32x16_bf16 v[0:15], v[68:71], v[226:229], v[0:15]
	s_waitcnt lgkmcnt(0)
; #define LAS __attribute__((address_space(3)))
; DI void expsum(f32x16& p, float& l_reg, bf16x8& pa0, bf16x8& pa1) {
; #pragma unroll
;     for (int r = 0; r < 16; ++r) p[r] = __builtin_amdgcn_exp2f(p[r]);
;     float ps = 0.f;
; #pragma unroll
;     for (int r = 0; r < 16; ++r) ps += p[r];
;     l_reg += ps; asm volatile("" : "+v"(l_reg));
;     ...
;     ATT_PK4(p, 0, pa0); ATT_PK4(p, 8, pa1);
;     ...
; }
; DI int v_rd_base(int lane) { return ((lane & 3) << 3) | (((lane >> 2) & 3) << 6) | (((lane >> 4) & 1) << 5) | (((lane >> 5) & 1) << 8); }
; template <int OFF> DI s16x4 tr_read(int vb) { s16x4 r; asm volatile("ds_read_b64_tr_b16 %0, %1 offset:%2" : "=&v"(r) : "v"(vb), "i"(OFF) : "memory"); return r; }
; template <int H> DI void v_reads(s16x4* vf, int vb) {
;     vf[0] = tr_read<v_rd_off(0, 2 * H, 0)>(vb); vf[1] = tr_read<v_rd_off(0, 2 * H, 1)>(vb); vf[2] = tr_read<v_rd_off(0, 2 * H + 1, 0)>(vb); vf[3] = tr_read<v_rd_off(0, 2 * H + 1, 1)>(vb);
;     vf[4] = tr_read<v_rd_off(1, 2 * H, 0)>(vb); vf[5] = tr_read<v_rd_off(1, 2 * H, 1)>(vb); vf[6] = tr_read<v_rd_off(1, 2 * H + 1, 0)>(vb); vf[7] = tr_read<v_rd_off(1, 2 * H + 1, 1)>(vb);
;     vf[8] = tr_read<v_rd_off(2, 2 * H, 0)>(vb); vf[9] = tr_read<v_rd_off(2, 2 * H, 1)>(vb); vf[10] = tr_read<v_rd_off(2, 2 * H + 1, 0)>(vb); vf[11] = tr_read<v_rd_off(2, 2 * H + 1, 1)>(vb);
;     vf[12] = tr_read<v_rd_off(3, 2 * H, 0)>(vb); vf[13] = tr_read<v_rd_off(3, 2 * H, 1)>(vb); vf[14] = tr_read<v_rd_off(3, 2 * H + 1, 0)>(vb); vf[15] = tr_read<v_rd_off(3, 2 * H + 1, 1)>(vb);
; }
; DI void pv_mma(f32x16* o, const s16x4* vf, bf16x8 pa0, bf16x8 pa1) {
;     ...
; #pragma unroll
;     for (int d0 = 0; d0 < 4; ++d0) {
;         o[d0] = __builtin_amdgcn_mfma_f32_32x32x16_bf16(pa0, ATT_PK(vf[4 * d0], vf[4 * d0 + 1]), o[d0], 0, 0, 0);
;         o[d0] = __builtin_amdgcn_mfma_f32_32x32x16_bf16(pa1, ATT_PK(vf[4 * d0 + 2], vf[4 * d0 + 3]), o[d0], 0, 0, 0); }
;     ...
; }
; template <int DQK, int D0A, int D0B> DI void k_reads(bf16x8* kf, const LAS unsigned char* Ks, int half, int r32, int hi) {
; #pragma unroll
;     for (int d0 = D0A; d0 < D0B; ++d0) kf[d0 - D0A] = *(const LAS bf16x8*)(Ks + half * (32 * DQK * 2) + kswz<DQK>(r32, (d0 * 16 + hi * 8) * 2));
; }
; template <int D0A, int D0B> DI void qk_mma(f32x16& p, const bf16x8* kf, const bf16x8* qr) {
; #pragma unroll
;     for (int d0 = D0A; d0 < D0B; ++d0) {
	v_mfma_f32_32x32x16_bf16 v[64:79], v[174:177], v[80:83], 0
	v_mfma_f32_32x32x16_bf16 v[64:79], v[178:181], v[84:87], v[64:79]
	v_mfma_f32_32x32x16_bf16 v[64:79], v[182:185], v[88:91], v[64:79]
	v_mfma_f32_32x32x16_bf16 v[64:79], v[186:189], v[92:95], v[64:79]
	v_mfma_f32_32x32x16_bf16 v[64:79], v[190:193], v[96:99], v[64:79]
	v_mfma_f32_32x32x16_bf16 v[64:79], v[194:197], v[100:103], v[64:79]
	v_mfma_f32_32x32x16_bf16 v[64:79], v[230:233], v[104:107], v[64:79]
	v_mfma_f32_32x32x16_bf16 v[64:79], v[234:237], v[108:111], v[64:79]
	v_mfma_f32_32x32x16_bf16 v[64:79], v[238:241], v[112:115], v[64:79]
	v_mfma_f32_32x32x16_bf16 v[64:79], v[242:245], v[116:119], v[64:79]
	v_mfma_f32_32x32x16_bf16 v[64:79], v[246:249], v[120:123], v[64:79]
	v_mfma_f32_32x32x16_bf16 v[64:79], v[250:253], v[124:127], v[64:79]
	s_setprio 0
	s_add_i32 s4, s43, -2
	s_and_b32 s4, s4, 3
	s_mulk_i32 s4, 0x6000
	v_add_u32_e32 v246, s4, v158
	v_add_u32_e32 v174, v246, v151
	v_add_u32_e32 v178, v246, v149
	v_add_u32_e32 v182, v246, v148
	v_add_u32_e32 v186, v246, v147
	ds_read_b128 v[190:193], v174 offset:128
	ds_read_b128 v[194:197], v178 offset:128
	ds_read_b128 v[174:177], v174
	ds_read_b128 v[178:181], v178
	ds_read_b128 v[182:185], v182
	ds_read_b128 v[186:189], v186
	ds_read_b64_tr_b16 v[198:199], v254 offset:0x2000
	ds_read_b64_tr_b16 v[200:201], v254 offset:0x2800
	ds_read_b64_tr_b16 v[202:203], v254 offset:0x3000
	ds_read_b64_tr_b16 v[204:205], v254 offset:0x3800
	ds_read_b64_tr_b16 v[206:207], v254 offset:0x2200
	ds_read_b64_tr_b16 v[208:209], v254 offset:0x2a00
	ds_read_b64_tr_b16 v[210:211], v254 offset:0x3200
	ds_read_b64_tr_b16 v[212:213], v254 offset:0x3a00
	ds_read_b64_tr_b16 v[214:215], v254 offset:0x2400
	ds_read_b64_tr_b16 v[216:217], v254 offset:0x2c00
	ds_read_b64_tr_b16 v[218:219], v254 offset:0x3400
	ds_read_b64_tr_b16 v[220:221], v254 offset:0x3c00
	ds_read_b64_tr_b16 v[222:223], v254 offset:0x2600
	ds_read_b64_tr_b16 v[224:225], v254 offset:0x2e00
	ds_read_b64_tr_b16 v[226:227], v254 offset:0x3600
	ds_read_b64_tr_b16 v[228:229], v254 offset:0x3e00
	v_exp_f32_e32 v64, v64
	v_exp_f32_e32 v65, v65
	v_exp_f32_e32 v66, v66
	v_exp_f32_e32 v67, v67
	v_exp_f32_e32 v68, v68
	v_exp_f32_e32 v69, v69
	v_add_f32_e32 v230, v65, v64
	v_exp_f32_e32 v70, v70
	v_add_f32_e32 v230, v66, v230
	v_exp_f32_e32 v71, v71
	v_add_f32_e32 v230, v67, v230
	v_exp_f32_e32 v72, v72
	v_add_f32_e32 v230, v68, v230
	v_exp_f32_e32 v73, v73
	v_add_f32_e32 v230, v69, v230
	v_exp_f32_e32 v74, v74
	v_add_f32_e32 v230, v70, v230
	v_exp_f32_e32 v75, v75
	v_add_f32_e32 v230, v71, v230
	v_exp_f32_e32 v76, v76
	v_add_f32_e32 v230, v72, v230
	v_exp_f32_e32 v77, v77
	v_add_f32_e32 v230, v73, v230
	v_exp_f32_e32 v78, v78
	v_add_f32_e32 v230, v74, v230
	v_exp_f32_e32 v79, v79
	v_add_f32_e32 v230, v75, v230
	v_add_f32_e32 v230, v76, v230
	v_add_f32_e32 v230, v77, v230
	v_add_f32_e32 v230, v78, v230
	v_add_f32_e32 v230, v79, v230
	v_add_f32_e32 v173, v173, v230
	s_setprio 2
	v_cvt_pk_bf16_f32 v64, v64, v65
	v_cvt_pk_bf16_f32 v65, v66, v67
	v_cvt_pk_bf16_f32 v66, v68, v69
	v_cvt_pk_bf16_f32 v67, v70, v71
	v_cvt_pk_bf16_f32 v68, v72, v73
	v_cvt_pk_bf16_f32 v69, v74, v75
	v_cvt_pk_bf16_f32 v70, v76, v77
	v_cvt_pk_bf16_f32 v71, v78, v79
	s_nop 0
	v_permlane32_swap_b32_e32 v64, v66
	v_permlane32_swap_b32_e32 v65, v67
	v_permlane32_swap_b32_e32 v68, v70
	v_permlane32_swap_b32_e32 v69, v71
	s_waitcnt lgkmcnt(0)
	v_add_u32_e32 v72, v246, v151
	v_add_u32_e32 v73, v246, v149
	v_add_u32_e32 v74, v246, v148
	v_add_u32_e32 v75, v246, v147
	ds_read_b128 v[230:233], v74 offset:128
	ds_read_b128 v[234:237], v75 offset:128
	ds_read_b128 v[238:241], v72 offset:256
	ds_read_b128 v[242:245], v73 offset:256
	ds_read_b128 v[246:249], v74 offset:256
	ds_read_b128 v[250:253], v75 offset:256
	s_setprio 1
	s_cmp_lt_u32 s33, 0x100
	s_cbranch_scc1 .Lstg_mla_mid_3
	s_waitcnt vmcnt(5)
	s_barrier

; #define LAS __attribute__((address_space(3)))
; DI void expsum(f32x16& p, float& l_reg, bf16x8& pa0, bf16x8& pa1) {
; #pragma unroll
;     for (int r = 0; r < 16; ++r) p[r] = __builtin_amdgcn_exp2f(p[r]);
;     float ps = 0.f;
; #pragma unroll
;     for (int r = 0; r < 16; ++r) ps += p[r];
;     l_reg += ps; asm volatile("" : "+v"(l_reg));
;     ...
;     ATT_PK4(p, 0, pa0); ATT_PK4(p, 8, pa1);
;     ...
; }
; DI int v_rd_base(int lane) { return ((lane & 3) << 3) | (((lane >> 2) & 3) << 6) | (((lane >> 4) & 1) << 5) | (((lane >> 5) & 1) << 8); }
; template <int OFF> DI s16x4 tr_read(int vb) { s16x4 r; asm volatile("ds_read_b64_tr_b16 %0, %1 offset:%2" : "=&v"(r) : "v"(vb), "i"(OFF) : "memory"); return r; }
; template <int H> DI void v_reads(s16x4* vf, int vb) {
;     vf[0] = tr_read<v_rd_off(0, 2 * H, 0)>(vb); vf[1] = tr_read<v_rd_off(0, 2 * H, 1)>(vb); vf[2] = tr_read<v_rd_off(0, 2 * H + 1, 0)>(vb); vf[3] = tr_read<v_rd_off(0, 2 * H + 1, 1)>(vb);
;     vf[4] = tr_read<v_rd_off(1, 2 * H, 0)>(vb); vf[5] = tr_read<v_rd_off(1, 2 * H, 1)>(vb); vf[6] = tr_read<v_rd_off(1, 2 * H + 1, 0)>(vb); vf[7] = tr_read<v_rd_off(1, 2 * H + 1, 1)>(vb);
;     vf[8] = tr_read<v_rd_off(2, 2 * H, 0)>(vb); vf[9] = tr_read<v_rd_off(2, 2 * H, 1)>(vb); vf[10] = tr_read<v_rd_off(2, 2 * H + 1, 0)>(vb); vf[11] = tr_read<v_rd_off(2, 2 * H + 1, 1)>(vb);
;     vf[12] = tr_read<v_rd_off(3, 2 * H, 0)>(vb); vf[13] = tr_read<v_rd_off(3, 2 * H, 1)>(vb); vf[14] = tr_read<v_rd_off(3, 2 * H + 1, 0)>(vb); vf[15] = tr_read<v_rd_off(3, 2 * H + 1, 1)>(vb);
; }
; DI void pv_mma(f32x16* o, const s16x4* vf, bf16x8 pa0, bf16x8 pa1) {
;     ...
; #pragma unroll
;     for (int d0 = 0; d0 < 4; ++d0) {
;         o[d0] = __builtin_amdgcn_mfma_f32_32x32x16_bf16(pa0, ATT_PK(vf[4 * d0], vf[4 * d0 + 1]), o[d0], 0, 0, 0);
;         o[d0] = __builtin_amdgcn_mfma_f32_32x32x16_bf16(pa1, ATT_PK(vf[4 * d0 + 2], vf[4 * d0 + 3]), o[d0], 0, 0, 0); }
;     ...
; }
; template <int DQK, int D0A, int D0B> DI void k_reads(bf16x8* kf, const LAS unsigned char* Ks, int half, int r32, int hi) {
; #pragma unroll
;     for (int d0 = D0A; d0 < D0B; ++d0) kf[d0 - D0A] = *(const LAS bf16x8*)(Ks + half * (32 * DQK * 2) + kswz<DQK>(r32, (d0 * 16 + hi * 8) * 2));
; }
; template <int D0A, int D0B> DI void qk_mma(f32x16& p, const bf16x8* kf, const bf16x8* qr) {
; #pragma unroll
;     for (int d0 = D0A; d0 < D0B; ++d0) {
.Lstg_mla_t61_4:
	s_setprio 0
	v_lshl_add_u64 v[132:133], v[132:133], 1, s[0:1]
	s_mov_b32 m0, s6
	v_lshl_add_u64 v[134:135], v[134:135], 1, s[0:1]
	global_load_lds_dwordx4 v[132:133], off
	s_mov_b32 m0, s7
	s_nop 0
	global_load_lds_dwordx4 v[134:135], off
	ds_read_b128 v[132:135], v161 offset:36864
	ds_read_b128 v[136:139], v162 offset:36864
	ds_read_b128 v[140:143], v163 offset:36864
	ds_read_b128 v[174:177], v164 offset:36864
	ds_read_b128 v[178:181], v165 offset:36864
	ds_read_b128 v[182:185], v166 offset:36864
	v_lshl_add_u32 v144, s5, 14, v130
	ds_read_b64_tr_b16 v[186:187], v144 offset:0
	ds_read_b64_tr_b16 v[188:189], v144 offset:0x800
	ds_read_b64_tr_b16 v[190:191], v144 offset:0x1000
	ds_read_b64_tr_b16 v[192:193], v144 offset:0x1800
	ds_read_b64_tr_b16 v[194:195], v144 offset:0x200
	ds_read_b64_tr_b16 v[196:197], v144 offset:0xa00
	ds_read_b64_tr_b16 v[198:199], v144 offset:0x1200
	ds_read_b64_tr_b16 v[200:201], v144 offset:0x1a00
	ds_read_b64_tr_b16 v[202:203], v144 offset:0x400
	ds_read_b64_tr_b16 v[204:205], v144 offset:0xc00
	ds_read_b64_tr_b16 v[206:207], v144 offset:0x1400
	ds_read_b64_tr_b16 v[208:209], v144 offset:0x1c00
	ds_read_b64_tr_b16 v[210:211], v144 offset:0x600
	ds_read_b64_tr_b16 v[212:213], v144 offset:0xe00
	ds_read_b64_tr_b16 v[214:215], v144 offset:0x1600
	ds_read_b64_tr_b16 v[216:217], v144 offset:0x1e00
	v_exp_f32_e32 v64, v64
	v_exp_f32_e32 v65, v65
	v_exp_f32_e32 v66, v66
	v_exp_f32_e32 v67, v67
	v_exp_f32_e32 v68, v68
	v_exp_f32_e32 v69, v69
	v_add_f32_e32 v145, v65, v64
	v_exp_f32_e32 v70, v70
	v_add_f32_e32 v145, v66, v145
	v_exp_f32_e32 v71, v71
	v_add_f32_e32 v145, v67, v145
	v_exp_f32_e32 v72, v72
	v_add_f32_e32 v145, v68, v145
	v_exp_f32_e32 v73, v73
	v_add_f32_e32 v145, v69, v145
	v_exp_f32_e32 v74, v74
	v_add_f32_e32 v145, v70, v145
	v_exp_f32_e32 v75, v75
	v_add_f32_e32 v145, v71, v145
	v_exp_f32_e32 v76, v76
	v_add_f32_e32 v145, v72, v145
	v_exp_f32_e32 v77, v77
	v_add_f32_e32 v145, v73, v145
	v_exp_f32_e32 v78, v78
	v_add_f32_e32 v145, v74, v145
	v_exp_f32_e32 v79, v79
	v_add_f32_e32 v145, v75, v145
	v_add_f32_e32 v145, v76, v145
	v_add_f32_e32 v145, v77, v145
	v_add_f32_e32 v145, v78, v145
	v_add_f32_e32 v145, v79, v145
	v_add_f32_e32 v145, v173, v145
	s_setprio 2
	v_cvt_pk_bf16_f32 v64, v64, v65
	v_cvt_pk_bf16_f32 v65, v66, v67
	v_cvt_pk_bf16_f32 v66, v68, v69
	v_cvt_pk_bf16_f32 v67, v70, v71
	v_cvt_pk_bf16_f32 v68, v72, v73
	v_cvt_pk_bf16_f32 v69, v74, v75
	v_cvt_pk_bf16_f32 v70, v76, v77
	v_cvt_pk_bf16_f32 v71, v78, v79
	s_nop 0
	v_permlane32_swap_b32_e32 v64, v66
	v_permlane32_swap_b32_e32 v65, v67
	v_permlane32_swap_b32_e32 v68, v70
	v_permlane32_swap_b32_e32 v69, v71
	s_waitcnt lgkmcnt(0)
	ds_read_b128 v[218:221], v167 offset:36864
	ds_read_b128 v[222:225], v168 offset:36864
	ds_read_b128 v[226:229], v169 offset:36864
	ds_read_b128 v[230:233], v170 offset:36864
	ds_read_b128 v[234:237], v171 offset:36864
	ds_read_b128 v[238:241], v172 offset:36864
	s_setprio 1
	v_mfma_f32_32x32x16_bf16 v[48:63], v[64:67], v[186:189], v[48:63]
	v_mfma_f32_32x32x16_bf16 v[32:47], v[64:67], v[194:197], v[32:47]
	v_mfma_f32_32x32x16_bf16 v[16:31], v[64:67], v[202:205], v[16:31]
	v_mfma_f32_32x32x16_bf16 v[0:15], v[64:67], v[210:213], v[0:15]
	v_mfma_f32_32x32x16_bf16 v[48:63], v[68:71], v[190:193], v[48:63]
	v_mfma_f32_32x32x16_bf16 v[32:47], v[68:71], v[198:201], v[32:47]
	v_mfma_f32_32x32x16_bf16 v[16:31], v[68:71], v[206:209], v[16:31]
	v_mfma_f32_32x32x16_bf16 v[0:15], v[68:71], v[214:217], v[0:15]
	s_waitcnt lgkmcnt(0)
; #define LAS __attribute__((address_space(3)))
; DI void expsum(f32x16& p, float& l_reg, bf16x8& pa0, bf16x8& pa1) {
; #pragma unroll
;     for (int r = 0; r < 16; ++r) p[r] = __builtin_amdgcn_exp2f(p[r]);
;     float ps = 0.f;
; #pragma unroll
;     for (int r = 0; r < 16; ++r) ps += p[r];
;     l_reg += ps; asm volatile("" : "+v"(l_reg));
;     ...
;     ATT_PK4(p, 0, pa0); ATT_PK4(p, 8, pa1);
;     ...
; }
; DI int v_rd_base(int lane) { return ((lane & 3) << 3) | (((lane >> 2) & 3) << 6) | (((lane >> 4) & 1) << 5) | (((lane >> 5) & 1) << 8); }
; template <int OFF> DI s16x4 tr_read(int vb) { s16x4 r; asm volatile("ds_read_b64_tr_b16 %0, %1 offset:%2" : "=&v"(r) : "v"(vb), "i"(OFF) : "memory"); return r; }
; template <int H> DI void v_reads(s16x4* vf, int vb) {
;     vf[0] = tr_read<v_rd_off(0, 2 * H, 0)>(vb); vf[1] = tr_read<v_rd_off(0, 2 * H, 1)>(vb); vf[2] = tr_read<v_rd_off(0, 2 * H + 1, 0)>(vb); vf[3] = tr_read<v_rd_off(0, 2 * H + 1, 1)>(vb);
;     vf[4] = tr_read<v_rd_off(1, 2 * H, 0)>(vb); vf[5] = tr_read<v_rd_off(1, 2 * H, 1)>(vb); vf[6] = tr_read<v_rd_off(1, 2 * H + 1, 0)>(vb); vf[7] = tr_read<v_rd_off(1, 2 * H + 1, 1)>(vb);
;     vf[8] = tr_read<v_rd_off(2, 2 * H, 0)>(vb); vf[9] = tr_read<v_rd_off(2, 2 * H, 1)>(vb); vf[10] = tr_read<v_rd_off(2, 2 * H + 1, 0)>(vb); vf[11] = tr_read<v_rd_off(2, 2 * H + 1, 1)>(vb);
;     vf[12] = tr_read<v_rd_off(3, 2 * H, 0)>(vb); vf[13] = tr_read<v_rd_off(3, 2 * H, 1)>(vb); vf[14] = tr_read<v_rd_off(3, 2 * H + 1, 0)>(vb); vf[15] = tr_read<v_rd_off(3, 2 * H + 1, 1)>(vb);
; }
; DI void pv_mma(f32x16* o, const s16x4* vf, bf16x8 pa0, bf16x8 pa1) {
;     ...
; #pragma unroll
;     for (int d0 = 0; d0 < 4; ++d0) {
;         o[d0] = __builtin_amdgcn_mfma_f32_32x32x16_bf16(pa0, ATT_PK(vf[4 * d0], vf[4 * d0 + 1]), o[d0], 0, 0, 0);
;         o[d0] = __builtin_amdgcn_mfma_f32_32x32x16_bf16(pa1, ATT_PK(vf[4 * d0 + 2], vf[4 * d0 + 3]), o[d0], 0, 0, 0); }
;     ...
; }
; template <int DQK, int D0A, int D0B> DI void k_reads(bf16x8* kf, const LAS unsigned char* Ks, int half, int r32, int hi) {
; #pragma unroll
;     for (int d0 = D0A; d0 < D0B; ++d0) kf[d0 - D0A] = *(const LAS bf16x8*)(Ks + half * (32 * DQK * 2) + kswz<DQK>(r32, (d0 * 16 + hi * 8) * 2));
; }
; template <int D0A, int D0B> DI void qk_mma(f32x16& p, const bf16x8* kf, const bf16x8* qr) {
; #pragma unroll
;     for (int d0 = D0A; d0 < D0B; ++d0) {
	v_mfma_f32_32x32x16_bf16 v[64:79], v[132:135], v[80:83], 0
	v_mfma_f32_32x32x16_bf16 v[64:79], v[136:139], v[84:87], v[64:79]
	v_mfma_f32_32x32x16_bf16 v[64:79], v[140:143], v[88:91], v[64:79]
	v_mfma_f32_32x32x16_bf16 v[64:79], v[174:177], v[92:95], v[64:79]
	v_mfma_f32_32x32x16_bf16 v[64:79], v[178:181], v[96:99], v[64:79]
	v_mfma_f32_32x32x16_bf16 v[64:79], v[182:185], v[100:103], v[64:79]
	s_waitcnt lgkmcnt(0)
	v_mfma_f32_32x32x16_bf16 v[64:79], v[218:221], v[104:107], v[64:79]
	v_mfma_f32_32x32x16_bf16 v[64:79], v[222:225], v[108:111], v[64:79]
	v_mfma_f32_32x32x16_bf16 v[64:79], v[226:229], v[112:115], v[64:79]
	v_mfma_f32_32x32x16_bf16 v[64:79], v[230:233], v[116:119], v[64:79]
	v_mfma_f32_32x32x16_bf16 v[64:79], v[234:237], v[120:123], v[64:79]
	v_mfma_f32_32x32x16_bf16 v[64:79], v[238:241], v[124:127], v[64:79]
	s_setprio 0
	ds_read_b128 v[132:135], v161 offset:49152
	ds_read_b128 v[136:139], v162 offset:49152
	ds_read_b128 v[140:143], v163 offset:49152
	ds_read_b128 v[174:177], v164 offset:49152
	ds_read_b128 v[178:181], v165 offset:49152
	ds_read_b128 v[182:185], v166 offset:49152
	ds_read_b64_tr_b16 v[186:187], v144 offset:0x2000
	ds_read_b64_tr_b16 v[188:189], v144 offset:0x2800
	ds_read_b64_tr_b16 v[190:191], v144 offset:0x3000
	ds_read_b64_tr_b16 v[192:193], v144 offset:0x3800
	ds_read_b64_tr_b16 v[194:195], v144 offset:0x2200
	ds_read_b64_tr_b16 v[196:197], v144 offset:0x2a00
	ds_read_b64_tr_b16 v[198:199], v144 offset:0x3200
	ds_read_b64_tr_b16 v[200:201], v144 offset:0x3a00
	ds_read_b64_tr_b16 v[202:203], v144 offset:0x2400
	ds_read_b64_tr_b16 v[204:205], v144 offset:0x2c00
	ds_read_b64_tr_b16 v[206:207], v144 offset:0x3400
	ds_read_b64_tr_b16 v[208:209], v144 offset:0x3c00
	ds_read_b64_tr_b16 v[210:211], v144 offset:0x2600
	ds_read_b64_tr_b16 v[212:213], v144 offset:0x2e00
	ds_read_b64_tr_b16 v[214:215], v144 offset:0x3600
	ds_read_b64_tr_b16 v[216:217], v144 offset:0x3e00
	s_nop 5
	v_exp_f32_e32 v64, v64
	v_exp_f32_e32 v65, v65
	v_exp_f32_e32 v66, v66
	v_exp_f32_e32 v67, v67
	v_exp_f32_e32 v68, v68
	v_exp_f32_e32 v69, v69
	v_add_f32_e32 v144, v65, v64
	v_exp_f32_e32 v70, v70
	v_add_f32_e32 v144, v66, v144
	v_exp_f32_e32 v71, v71
	v_add_f32_e32 v144, v67, v144
	v_exp_f32_e32 v72, v72
	v_add_f32_e32 v144, v68, v144
	v_exp_f32_e32 v73, v73
	v_add_f32_e32 v144, v69, v144
	v_exp_f32_e32 v74, v74
	v_add_f32_e32 v144, v70, v144
	v_exp_f32_e32 v75, v75
	v_add_f32_e32 v144, v71, v144
	v_exp_f32_e32 v76, v76
	v_add_f32_e32 v144, v72, v144
	v_exp_f32_e32 v77, v77
	v_add_f32_e32 v144, v73, v144
	v_exp_f32_e32 v78, v78
	v_add_f32_e32 v144, v74, v144
	v_exp_f32_e32 v79, v79
	v_add_f32_e32 v144, v75, v144
	v_add_f32_e32 v144, v76, v144
	v_add_f32_e32 v144, v77, v144
	v_add_f32_e32 v144, v78, v144
	v_add_f32_e32 v144, v79, v144
	v_add_f32_e32 v144, v145, v144
	s_setprio 2
	v_cvt_pk_bf16_f32 v64, v64, v65
	v_cvt_pk_bf16_f32 v65, v66, v67
	v_cvt_pk_bf16_f32 v66, v68, v69
	v_cvt_pk_bf16_f32 v67, v70, v71
	v_cvt_pk_bf16_f32 v68, v72, v73
	v_cvt_pk_bf16_f32 v69, v74, v75
	v_cvt_pk_bf16_f32 v70, v76, v77
	v_cvt_pk_bf16_f32 v71, v78, v79
	s_nop 0
	v_permlane32_swap_b32_e32 v64, v66
	v_permlane32_swap_b32_e32 v65, v67
	v_permlane32_swap_b32_e32 v68, v70
	v_permlane32_swap_b32_e32 v69, v71
	s_waitcnt lgkmcnt(0)
	ds_read_b128 v[218:221], v167 offset:49152
	ds_read_b128 v[222:225], v168 offset:49152
	ds_read_b128 v[226:229], v169 offset:49152
	ds_read_b128 v[230:233], v170 offset:49152
	ds_read_b128 v[234:237], v171 offset:49152
	ds_read_b128 v[238:241], v172 offset:49152
	s_setprio 1
	s_cmp_lt_u32 s33, 0x100
	s_cbranch_scc1 .Lstg_mla_m61_5
	s_waitcnt vmcnt(0)
	s_barrier

; #define LAS __attribute__((address_space(3)))
; DI void expsum(f32x16& p, float& l_reg, bf16x8& pa0, bf16x8& pa1) {
; #pragma unroll
;     for (int r = 0; r < 16; ++r) p[r] = __builtin_amdgcn_exp2f(p[r]);
;     float ps = 0.f;
; #pragma unroll
;     for (int r = 0; r < 16; ++r) ps += p[r];
;     l_reg += ps; asm volatile("" : "+v"(l_reg));
;     ...
;     ATT_PK4(p, 0, pa0); ATT_PK4(p, 8, pa1);
;     ...
; }
; DI int v_rd_base(int lane) { return ((lane & 3) << 3) | (((lane >> 2) & 3) << 6) | (((lane >> 4) & 1) << 5) | (((lane >> 5) & 1) << 8); }
; template <int OFF> DI s16x4 tr_read(int vb) { s16x4 r; asm volatile("ds_read_b64_tr_b16 %0, %1 offset:%2" : "=&v"(r) : "v"(vb), "i"(OFF) : "memory"); return r; }
; template <int H> DI void v_reads(s16x4* vf, int vb) {
;     vf[0] = tr_read<v_rd_off(0, 2 * H, 0)>(vb); vf[1] = tr_read<v_rd_off(0, 2 * H, 1)>(vb); vf[2] = tr_read<v_rd_off(0, 2 * H + 1, 0)>(vb); vf[3] = tr_read<v_rd_off(0, 2 * H + 1, 1)>(vb);
;     vf[4] = tr_read<v_rd_off(1, 2 * H, 0)>(vb); vf[5] = tr_read<v_rd_off(1, 2 * H, 1)>(vb); vf[6] = tr_read<v_rd_off(1, 2 * H + 1, 0)>(vb); vf[7] = tr_read<v_rd_off(1, 2 * H + 1, 1)>(vb);
;     vf[8] = tr_read<v_rd_off(2, 2 * H, 0)>(vb); vf[9] = tr_read<v_rd_off(2, 2 * H, 1)>(vb); vf[10] = tr_read<v_rd_off(2, 2 * H + 1, 0)>(vb); vf[11] = tr_read<v_rd_off(2, 2 * H + 1, 1)>(vb);
;     vf[12] = tr_read<v_rd_off(3, 2 * H, 0)>(vb); vf[13] = tr_read<v_rd_off(3, 2 * H, 1)>(vb); vf[14] = tr_read<v_rd_off(3, 2 * H + 1, 0)>(vb); vf[15] = tr_read<v_rd_off(3, 2 * H + 1, 1)>(vb);
; }
; DI void pv_mma(f32x16* o, const s16x4* vf, bf16x8 pa0, bf16x8 pa1) {
;     ...
; #pragma unroll
;     for (int d0 = 0; d0 < 4; ++d0) {
;         o[d0] = __builtin_amdgcn_mfma_f32_32x32x16_bf16(pa0, ATT_PK(vf[4 * d0], vf[4 * d0 + 1]), o[d0], 0, 0, 0);
;         o[d0] = __builtin_amdgcn_mfma_f32_32x32x16_bf16(pa1, ATT_PK(vf[4 * d0 + 2], vf[4 * d0 + 3]), o[d0], 0, 0, 0); }
;     ...
; }
; template <int DQK, int D0A, int D0B> DI void k_reads(bf16x8* kf, const LAS unsigned char* Ks, int half, int r32, int hi) {
; #pragma unroll
;     for (int d0 = D0A; d0 < D0B; ++d0) kf[d0 - D0A] = *(const LAS bf16x8*)(Ks + half * (32 * DQK * 2) + kswz<DQK>(r32, (d0 * 16 + hi * 8) * 2));
; }
; template <int D0A, int D0B> DI void qk_mma(f32x16& p, const bf16x8* kf, const bf16x8* qr) {
; #pragma unroll
;     for (int d0 = D0A; d0 < D0B; ++d0) {
.Lstg_mla_t62_6:
	s_setprio 0
	ds_read_b128 v[132:135], v161 offset:61440
	ds_read_b128 v[136:139], v162 offset:61440
	ds_read_b128 v[140:143], v163 offset:61440
	ds_read_b128 v[174:177], v164 offset:61440
	ds_read_b128 v[162:165], v165 offset:61440
	ds_read_b128 v[178:181], v166 offset:61440
	v_add_u32_e32 v145, 0x8000, v130
	ds_read_b64_tr_b16 v[182:183], v145 offset:0
	ds_read_b64_tr_b16 v[184:185], v145 offset:0x800
	ds_read_b64_tr_b16 v[186:187], v145 offset:0x1000
	ds_read_b64_tr_b16 v[188:189], v145 offset:0x1800
	ds_read_b64_tr_b16 v[190:191], v145 offset:0x200
	ds_read_b64_tr_b16 v[192:193], v145 offset:0xa00
	ds_read_b64_tr_b16 v[194:195], v145 offset:0x1200
	ds_read_b64_tr_b16 v[196:197], v145 offset:0x1a00
	ds_read_b64_tr_b16 v[198:199], v145 offset:0x400
	ds_read_b64_tr_b16 v[200:201], v145 offset:0xc00
	ds_read_b64_tr_b16 v[202:203], v145 offset:0x1400
	ds_read_b64_tr_b16 v[204:205], v145 offset:0x1c00
	ds_read_b64_tr_b16 v[206:207], v145 offset:0x600
	ds_read_b64_tr_b16 v[208:209], v145 offset:0xe00
	ds_read_b64_tr_b16 v[210:211], v145 offset:0x1600
	ds_read_b64_tr_b16 v[212:213], v145 offset:0x1e00
	s_nop 3
	v_exp_f32_e32 v64, v64
	v_exp_f32_e32 v65, v65
	v_exp_f32_e32 v66, v66
	v_exp_f32_e32 v67, v67
	v_exp_f32_e32 v68, v68
	v_exp_f32_e32 v69, v69
	v_add_f32_e32 v161, v65, v64
	v_exp_f32_e32 v70, v70
	v_add_f32_e32 v161, v66, v161
	v_exp_f32_e32 v71, v71
	v_add_f32_e32 v161, v67, v161
	v_exp_f32_e32 v72, v72
	v_add_f32_e32 v161, v68, v161
	v_exp_f32_e32 v73, v73
	v_add_f32_e32 v161, v69, v161
	v_exp_f32_e32 v74, v74
	v_add_f32_e32 v161, v70, v161
	v_exp_f32_e32 v75, v75
	v_add_f32_e32 v161, v71, v161
	v_exp_f32_e32 v76, v76
	v_add_f32_e32 v161, v72, v161
	v_exp_f32_e32 v77, v77
	v_add_f32_e32 v161, v73, v161
	v_exp_f32_e32 v78, v78
	v_add_f32_e32 v161, v74, v161
	v_exp_f32_e32 v79, v79
	v_add_f32_e32 v161, v75, v161
	v_add_f32_e32 v161, v76, v161
	v_add_f32_e32 v161, v77, v161
	v_add_f32_e32 v161, v78, v161
	v_add_f32_e32 v161, v79, v161
	v_add_f32_e32 v144, v144, v161
	s_setprio 2
	v_cvt_pk_bf16_f32 v64, v64, v65
	v_cvt_pk_bf16_f32 v65, v66, v67
	v_cvt_pk_bf16_f32 v66, v68, v69
	v_cvt_pk_bf16_f32 v67, v70, v71
	v_cvt_pk_bf16_f32 v68, v72, v73
	v_cvt_pk_bf16_f32 v69, v74, v75
	v_cvt_pk_bf16_f32 v70, v76, v77
	v_cvt_pk_bf16_f32 v71, v78, v79
	s_nop 0
	v_permlane32_swap_b32_e32 v64, v66
	v_permlane32_swap_b32_e32 v65, v67
	v_permlane32_swap_b32_e32 v68, v70
	v_permlane32_swap_b32_e32 v69, v71
	s_waitcnt lgkmcnt(0)
	ds_read_b128 v[214:217], v167 offset:61440
	ds_read_b128 v[218:221], v168 offset:61440
	ds_read_b128 v[166:169], v169 offset:61440
	ds_read_b128 v[222:225], v170 offset:61440
	ds_read_b128 v[226:229], v171 offset:61440
	ds_read_b128 v[170:173], v172 offset:61440
	s_setprio 1
	v_mfma_f32_32x32x16_bf16 v[48:63], v[64:67], v[182:185], v[48:63]
	v_mfma_f32_32x32x16_bf16 v[32:47], v[64:67], v[190:193], v[32:47]
	v_mfma_f32_32x32x16_bf16 v[16:31], v[64:67], v[198:201], v[16:31]
	v_mfma_f32_32x32x16_bf16 v[0:15], v[64:67], v[206:209], v[0:15]
	v_mfma_f32_32x32x16_bf16 v[48:63], v[68:71], v[186:189], v[48:63]
	v_mfma_f32_32x32x16_bf16 v[32:47], v[68:71], v[194:197], v[32:47]
	v_mfma_f32_32x32x16_bf16 v[16:31], v[68:71], v[202:205], v[16:31]
	v_mfma_f32_32x32x16_bf16 v[0:15], v[68:71], v[210:213], v[0:15]
	s_waitcnt lgkmcnt(0)
	v_mfma_f32_32x32x16_bf16 v[64:79], v[132:135], v[80:83], 0
	v_mfma_f32_32x32x16_bf16 v[64:79], v[136:139], v[84:87], v[64:79]
	v_mfma_f32_32x32x16_bf16 v[64:79], v[140:143], v[88:91], v[64:79]
	v_mfma_f32_32x32x16_bf16 v[64:79], v[174:177], v[92:95], v[64:79]
	v_mfma_f32_32x32x16_bf16 v[64:79], v[162:165], v[96:99], v[64:79]
	v_mfma_f32_32x32x16_bf16 v[64:79], v[178:181], v[100:103], v[64:79]
	s_waitcnt lgkmcnt(0)
; #define LAS __attribute__((address_space(3)))
; DI void expsum(f32x16& p, float& l_reg, bf16x8& pa0, bf16x8& pa1) {
; #pragma unroll
;     for (int r = 0; r < 16; ++r) p[r] = __builtin_amdgcn_exp2f(p[r]);
;     float ps = 0.f;
; #pragma unroll
;     for (int r = 0; r < 16; ++r) ps += p[r];
;     l_reg += ps; asm volatile("" : "+v"(l_reg));
;     ...
;     ATT_PK4(p, 0, pa0); ATT_PK4(p, 8, pa1);
;     ...
; }
; DI int v_rd_base(int lane) { return ((lane & 3) << 3) | (((lane >> 2) & 3) << 6) | (((lane >> 4) & 1) << 5) | (((lane >> 5) & 1) << 8); }
; template <int OFF> DI s16x4 tr_read(int vb) { s16x4 r; asm volatile("ds_read_b64_tr_b16 %0, %1 offset:%2" : "=&v"(r) : "v"(vb), "i"(OFF) : "memory"); return r; }
; template <int H> DI void v_reads(s16x4* vf, int vb) {
;     vf[0] = tr_read<v_rd_off(0, 2 * H, 0)>(vb); vf[1] = tr_read<v_rd_off(0, 2 * H, 1)>(vb); vf[2] = tr_read<v_rd_off(0, 2 * H + 1, 0)>(vb); vf[3] = tr_read<v_rd_off(0, 2 * H + 1, 1)>(vb);
;     vf[4] = tr_read<v_rd_off(1, 2 * H, 0)>(vb); vf[5] = tr_read<v_rd_off(1, 2 * H, 1)>(vb); vf[6] = tr_read<v_rd_off(1, 2 * H + 1, 0)>(vb); vf[7] = tr_read<v_rd_off(1, 2 * H + 1, 1)>(vb);
;     vf[8] = tr_read<v_rd_off(2, 2 * H, 0)>(vb); vf[9] = tr_read<v_rd_off(2, 2 * H, 1)>(vb); vf[10] = tr_read<v_rd_off(2, 2 * H + 1, 0)>(vb); vf[11] = tr_read<v_rd_off(2, 2 * H + 1, 1)>(vb);
;     vf[12] = tr_read<v_rd_off(3, 2 * H, 0)>(vb); vf[13] = tr_read<v_rd_off(3, 2 * H, 1)>(vb); vf[14] = tr_read<v_rd_off(3, 2 * H + 1, 0)>(vb); vf[15] = tr_read<v_rd_off(3, 2 * H + 1, 1)>(vb);
; }
; DI void pv_mma(f32x16* o, const s16x4* vf, bf16x8 pa0, bf16x8 pa1) {
;     ...
; #pragma unroll
;     for (int d0 = 0; d0 < 4; ++d0) {
;         o[d0] = __builtin_amdgcn_mfma_f32_32x32x16_bf16(pa0, ATT_PK(vf[4 * d0], vf[4 * d0 + 1]), o[d0], 0, 0, 0);
;         o[d0] = __builtin_amdgcn_mfma_f32_32x32x16_bf16(pa1, ATT_PK(vf[4 * d0 + 2], vf[4 * d0 + 3]), o[d0], 0, 0, 0); }
;     ...
; }
; template <int DQK, int D0A, int D0B> DI void k_reads(bf16x8* kf, const LAS unsigned char* Ks, int half, int r32, int hi) {
; #pragma unroll
;     for (int d0 = D0A; d0 < D0B; ++d0) kf[d0 - D0A] = *(const LAS bf16x8*)(Ks + half * (32 * DQK * 2) + kswz<DQK>(r32, (d0 * 16 + hi * 8) * 2));
; }
; template <int D0A, int D0B> DI void qk_mma(f32x16& p, const bf16x8* kf, const bf16x8* qr) {
; #pragma unroll
;     for (int d0 = D0A; d0 < D0B; ++d0) {
	v_mfma_f32_32x32x16_bf16 v[64:79], v[214:217], v[104:107], v[64:79]
	v_mfma_f32_32x32x16_bf16 v[64:79], v[218:221], v[108:111], v[64:79]
	v_mfma_f32_32x32x16_bf16 v[64:79], v[166:169], v[112:115], v[64:79]
	v_mfma_f32_32x32x16_bf16 v[64:79], v[222:225], v[116:119], v[64:79]
	v_mfma_f32_32x32x16_bf16 v[64:79], v[226:229], v[120:123], v[64:79]
	v_mfma_f32_32x32x16_bf16 v[64:79], v[170:173], v[124:127], v[64:79]
	s_setprio 0
	v_add_u32_e32 v158, 0x12000, v158
	v_add_u32_e32 v132, v158, v151
	v_add_u32_e32 v136, v158, v149
	v_add_u32_e32 v140, v158, v148
	v_add_u32_e32 v161, v158, v147
	ds_read_b128 v[132:135], v132
	ds_read_b128 v[136:139], v136
	ds_read_b128 v[140:143], v140
	ds_read_b128 v[162:165], v161
	v_add_u32_e32 v161, v158, v146
	v_add_u32_e32 v170, v158, v150
	ds_read_b128 v[166:169], v161
	ds_read_b128 v[170:173], v170
	ds_read_b64_tr_b16 v[174:175], v145 offset:0x2000
	ds_read_b64_tr_b16 v[176:177], v145 offset:0x2800
	ds_read_b64_tr_b16 v[178:179], v145 offset:0x3000
	ds_read_b64_tr_b16 v[180:181], v145 offset:0x3800
	ds_read_b64_tr_b16 v[182:183], v145 offset:0x2200
	ds_read_b64_tr_b16 v[184:185], v145 offset:0x2a00
	ds_read_b64_tr_b16 v[186:187], v145 offset:0x3200
	ds_read_b64_tr_b16 v[188:189], v145 offset:0x3a00
	ds_read_b64_tr_b16 v[190:191], v145 offset:0x2400
	ds_read_b64_tr_b16 v[192:193], v145 offset:0x2c00
	ds_read_b64_tr_b16 v[194:195], v145 offset:0x3400
	ds_read_b64_tr_b16 v[196:197], v145 offset:0x3c00
	ds_read_b64_tr_b16 v[198:199], v145 offset:0x2600
	ds_read_b64_tr_b16 v[200:201], v145 offset:0x2e00
	ds_read_b64_tr_b16 v[202:203], v145 offset:0x3600
	ds_read_b64_tr_b16 v[204:205], v145 offset:0x3e00
	v_exp_f32_e32 v64, v64
	v_exp_f32_e32 v65, v65
	v_exp_f32_e32 v66, v66
	v_exp_f32_e32 v67, v67
	v_exp_f32_e32 v68, v68
	v_exp_f32_e32 v69, v69
	v_add_f32_e32 v145, v65, v64
	v_exp_f32_e32 v70, v70
	v_add_f32_e32 v145, v66, v145
	v_exp_f32_e32 v71, v71
	v_add_f32_e32 v145, v67, v145
	v_exp_f32_e32 v72, v72
	v_add_f32_e32 v145, v68, v145
	v_exp_f32_e32 v73, v73
	v_add_f32_e32 v145, v69, v145
	v_exp_f32_e32 v74, v74
	v_add_f32_e32 v145, v70, v145
	v_exp_f32_e32 v75, v75
	v_add_f32_e32 v145, v71, v145
	v_exp_f32_e32 v76, v76
	v_add_f32_e32 v145, v72, v145
	v_exp_f32_e32 v77, v77
	v_add_f32_e32 v145, v73, v145
	v_exp_f32_e32 v78, v78
	v_add_f32_e32 v145, v74, v145
	v_exp_f32_e32 v79, v79
	v_add_f32_e32 v145, v75, v145
	v_add_f32_e32 v145, v76, v145
	v_add_f32_e32 v145, v77, v145
	v_add_f32_e32 v145, v78, v145
	v_add_f32_e32 v145, v79, v145
	v_add_f32_e32 v161, v144, v145
	s_setprio 2
	v_cvt_pk_bf16_f32 v64, v64, v65
	v_cvt_pk_bf16_f32 v65, v66, v67
	v_cvt_pk_bf16_f32 v66, v68, v69
	v_cvt_pk_bf16_f32 v67, v70, v71
	v_cvt_pk_bf16_f32 v68, v72, v73
	v_cvt_pk_bf16_f32 v69, v74, v75
	v_cvt_pk_bf16_f32 v70, v76, v77
	v_cvt_pk_bf16_f32 v71, v78, v79
	s_nop 0
	v_permlane32_swap_b32_e32 v64, v66
	v_permlane32_swap_b32_e32 v65, v67
	v_permlane32_swap_b32_e32 v68, v70
	v_permlane32_swap_b32_e32 v69, v71
	s_waitcnt lgkmcnt(0)
	v_add_u32_e32 v72, v158, v152
	v_add_u32_e32 v73, v158, v153
	ds_read_b128 v[206:209], v72
	ds_read_b128 v[210:213], v73
	v_add_u32_e32 v72, v158, v154
	v_add_u32_e32 v73, v158, v155
	ds_read_b128 v[214:217], v72
	ds_read_b128 v[218:221], v73
	v_add_u32_e32 v72, v158, v156
	v_add_u32_e32 v73, v158, v157
	ds_read_b128 v[222:225], v72
	ds_read_b128 v[226:229], v73
	s_setprio 1
	s_cmp_lt_u32 s33, 0x100
	s_cbranch_scc1 .Lstg_mla_m62_7
	s_waitcnt vmcnt(0)
	s_barrier

; #define LAS __attribute__((address_space(3)))
; DI void expsum(f32x16& p, float& l_reg, bf16x8& pa0, bf16x8& pa1) {
; #pragma unroll
;     for (int r = 0; r < 16; ++r) p[r] = __builtin_amdgcn_exp2f(p[r]);
;     float ps = 0.f;
; #pragma unroll
;     for (int r = 0; r < 16; ++r) ps += p[r];
;     l_reg += ps; asm volatile("" : "+v"(l_reg));
;     ...
;     ATT_PK4(p, 0, pa0); ATT_PK4(p, 8, pa1);
;     ...
; }
; DI int v_rd_base(int lane) { return ((lane & 3) << 3) | (((lane >> 2) & 3) << 6) | (((lane >> 4) & 1) << 5) | (((lane >> 5) & 1) << 8); }
; template <int OFF> DI s16x4 tr_read(int vb) { s16x4 r; asm volatile("ds_read_b64_tr_b16 %0, %1 offset:%2" : "=&v"(r) : "v"(vb), "i"(OFF) : "memory"); return r; }
; template <int H> DI void v_reads(s16x4* vf, int vb) {
;     vf[0] = tr_read<v_rd_off(0, 2 * H, 0)>(vb); vf[1] = tr_read<v_rd_off(0, 2 * H, 1)>(vb); vf[2] = tr_read<v_rd_off(0, 2 * H + 1, 0)>(vb); vf[3] = tr_read<v_rd_off(0, 2 * H + 1, 1)>(vb);
;     vf[4] = tr_read<v_rd_off(1, 2 * H, 0)>(vb); vf[5] = tr_read<v_rd_off(1, 2 * H, 1)>(vb); vf[6] = tr_read<v_rd_off(1, 2 * H + 1, 0)>(vb); vf[7] = tr_read<v_rd_off(1, 2 * H + 1, 1)>(vb);
;     vf[8] = tr_read<v_rd_off(2, 2 * H, 0)>(vb); vf[9] = tr_read<v_rd_off(2, 2 * H, 1)>(vb); vf[10] = tr_read<v_rd_off(2, 2 * H + 1, 0)>(vb); vf[11] = tr_read<v_rd_off(2, 2 * H + 1, 1)>(vb);
;     vf[12] = tr_read<v_rd_off(3, 2 * H, 0)>(vb); vf[13] = tr_read<v_rd_off(3, 2 * H, 1)>(vb); vf[14] = tr_read<v_rd_off(3, 2 * H + 1, 0)>(vb); vf[15] = tr_read<v_rd_off(3, 2 * H + 1, 1)>(vb);
; }
; DI void pv_mma(f32x16* o, const s16x4* vf, bf16x8 pa0, bf16x8 pa1) {
;     ...
; #pragma unroll
;     for (int d0 = 0; d0 < 4; ++d0) {
;         o[d0] = __builtin_amdgcn_mfma_f32_32x32x16_bf16(pa0, ATT_PK(vf[4 * d0], vf[4 * d0 + 1]), o[d0], 0, 0, 0);
;         o[d0] = __builtin_amdgcn_mfma_f32_32x32x16_bf16(pa1, ATT_PK(vf[4 * d0 + 2], vf[4 * d0 + 3]), o[d0], 0, 0, 0); }
;     ...
; }
; template <int DQK, int D0A, int D0B> DI void k_reads(bf16x8* kf, const LAS unsigned char* Ks, int half, int r32, int hi) {
; #pragma unroll
;     for (int d0 = D0A; d0 < D0B; ++d0) kf[d0 - D0A] = *(const LAS bf16x8*)(Ks + half * (32 * DQK * 2) + kswz<DQK>(r32, (d0 * 16 + hi * 8) * 2));
; }
; template <int D0A, int D0B> DI void qk_mma(f32x16& p, const bf16x8* kf, const bf16x8* qr) {
; #pragma unroll
;     for (int d0 = D0A; d0 < D0B; ++d0) {
.Lstg_mla_t63_8:
	s_setprio 0
	v_add_u32_e32 v158, s82, v159
	v_add_u32_e32 v132, v158, v151
	v_add_u32_e32 v136, v158, v149
	v_add_u32_e32 v140, v158, v148
	v_add_u32_e32 v144, v158, v147
	ds_read_b128 v[132:135], v132
	ds_read_b128 v[136:139], v136
	ds_read_b128 v[140:143], v140
	ds_read_b128 v[162:165], v144
	v_add_u32_e32 v144, v158, v146
	v_add_u32_e32 v148, v158, v150
	ds_read_b128 v[144:147], v144
	ds_read_b128 v[148:151], v148
	ds_read_b64_tr_b16 v[166:167], v130 offset:0
	ds_read_b64_tr_b16 v[168:169], v130 offset:0x800
	ds_read_b64_tr_b16 v[170:171], v130 offset:0x1000
	ds_read_b64_tr_b16 v[172:173], v130 offset:0x1800
	ds_read_b64_tr_b16 v[174:175], v130 offset:0x200
	ds_read_b64_tr_b16 v[176:177], v130 offset:0xa00
	ds_read_b64_tr_b16 v[178:179], v130 offset:0x1200
	ds_read_b64_tr_b16 v[180:181], v130 offset:0x1a00
	ds_read_b64_tr_b16 v[182:183], v130 offset:0x400
	ds_read_b64_tr_b16 v[184:185], v130 offset:0xc00
	ds_read_b64_tr_b16 v[186:187], v130 offset:0x1400
	ds_read_b64_tr_b16 v[188:189], v130 offset:0x1c00
	ds_read_b64_tr_b16 v[190:191], v130 offset:0x600
	ds_read_b64_tr_b16 v[192:193], v130 offset:0xe00
	ds_read_b64_tr_b16 v[194:195], v130 offset:0x1600
	ds_read_b64_tr_b16 v[196:197], v130 offset:0x1e00
	v_exp_f32_e32 v64, v64
	v_exp_f32_e32 v65, v65
	v_exp_f32_e32 v66, v66
	v_exp_f32_e32 v67, v67
	v_exp_f32_e32 v68, v68
	v_exp_f32_e32 v69, v69
	v_add_f32_e32 v159, v65, v64
	v_exp_f32_e32 v70, v70
	v_add_f32_e32 v159, v66, v159
	v_exp_f32_e32 v71, v71
	v_add_f32_e32 v159, v67, v159
	v_exp_f32_e32 v72, v72
	v_add_f32_e32 v159, v68, v159
	v_exp_f32_e32 v73, v73
	v_add_f32_e32 v159, v69, v159
	v_exp_f32_e32 v74, v74
	v_add_f32_e32 v159, v70, v159
	v_exp_f32_e32 v75, v75
	v_add_f32_e32 v159, v71, v159
	v_exp_f32_e32 v76, v76
	v_add_f32_e32 v159, v72, v159
	v_exp_f32_e32 v77, v77
	v_add_f32_e32 v159, v73, v159
	v_exp_f32_e32 v78, v78
	v_add_f32_e32 v159, v74, v159
	v_exp_f32_e32 v79, v79
	v_add_f32_e32 v159, v75, v159
	v_add_f32_e32 v159, v76, v159
	v_add_f32_e32 v159, v77, v159
	v_add_f32_e32 v159, v78, v159
	v_add_f32_e32 v159, v79, v159
	v_add_f32_e32 v161, v161, v159
	s_setprio 2
	v_cvt_pk_bf16_f32 v64, v64, v65
	v_cvt_pk_bf16_f32 v65, v66, v67
	v_cvt_pk_bf16_f32 v66, v68, v69
	v_cvt_pk_bf16_f32 v67, v70, v71
	v_cvt_pk_bf16_f32 v68, v72, v73
	v_cvt_pk_bf16_f32 v69, v74, v75
	v_cvt_pk_bf16_f32 v70, v76, v77
	v_cvt_pk_bf16_f32 v71, v78, v79
	s_nop 0
	v_permlane32_swap_b32_e32 v64, v66
	v_permlane32_swap_b32_e32 v65, v67
	v_permlane32_swap_b32_e32 v68, v70
	v_permlane32_swap_b32_e32 v69, v71
	s_waitcnt lgkmcnt(0)
	v_add_u32_e32 v72, v158, v152
	v_add_u32_e32 v73, v158, v153
	ds_read_b128 v[198:201], v72
	ds_read_b128 v[202:205], v73
	v_add_u32_e32 v72, v158, v154
	v_add_u32_e32 v73, v158, v155
	ds_read_b128 v[152:155], v72
	ds_read_b128 v[206:209], v73
	v_add_u32_e32 v72, v158, v156
	v_add_u32_e32 v73, v158, v157
	ds_read_b128 v[156:159], v72
	ds_read_b128 v[210:213], v73
	s_setprio 1
	v_mfma_f32_32x32x16_bf16 v[48:63], v[64:67], v[166:169], v[48:63]
	v_mfma_f32_32x32x16_bf16 v[32:47], v[64:67], v[174:177], v[32:47]
	v_mfma_f32_32x32x16_bf16 v[16:31], v[64:67], v[182:185], v[16:31]
	v_mfma_f32_32x32x16_bf16 v[0:15], v[64:67], v[190:193], v[0:15]
	v_mfma_f32_32x32x16_bf16 v[48:63], v[68:71], v[170:173], v[48:63]
	v_mfma_f32_32x32x16_bf16 v[32:47], v[68:71], v[178:181], v[32:47]
	v_mfma_f32_32x32x16_bf16 v[16:31], v[68:71], v[186:189], v[16:31]
	v_mfma_f32_32x32x16_bf16 v[0:15], v[68:71], v[194:197], v[0:15]
	s_waitcnt lgkmcnt(0)
; DI void expsum(f32x16& p, float& l_reg, bf16x8& pa0, bf16x8& pa1) {
; #pragma unroll
;     for (int r = 0; r < 16; ++r) p[r] = __builtin_amdgcn_exp2f(p[r]);
;     float ps = 0.f;
; #pragma unroll
;     for (int r = 0; r < 16; ++r) ps += p[r];
;     l_reg += ps; asm volatile("" : "+v"(l_reg));
;     ...
;     ATT_PK4(p, 0, pa0); ATT_PK4(p, 8, pa1);
;     ...
; }
; DI int v_rd_base(int lane) { return ((lane & 3) << 3) | (((lane >> 2) & 3) << 6) | (((lane >> 4) & 1) << 5) | (((lane >> 5) & 1) << 8); }
; template <int OFF> DI s16x4 tr_read(int vb) { s16x4 r; asm volatile("ds_read_b64_tr_b16 %0, %1 offset:%2" : "=&v"(r) : "v"(vb), "i"(OFF) : "memory"); return r; }
; template <int H> DI void v_reads(s16x4* vf, int vb) {
;     vf[0] = tr_read<v_rd_off(0, 2 * H, 0)>(vb); vf[1] = tr_read<v_rd_off(0, 2 * H, 1)>(vb); vf[2] = tr_read<v_rd_off(0, 2 * H + 1, 0)>(vb); vf[3] = tr_read<v_rd_off(0, 2 * H + 1, 1)>(vb);
;     vf[4] = tr_read<v_rd_off(1, 2 * H, 0)>(vb); vf[5] = tr_read<v_rd_off(1, 2 * H, 1)>(vb); vf[6] = tr_read<v_rd_off(1, 2 * H + 1, 0)>(vb); vf[7] = tr_read<v_rd_off(1, 2 * H + 1, 1)>(vb);
;     vf[8] = tr_read<v_rd_off(2, 2 * H, 0)>(vb); vf[9] = tr_read<v_rd_off(2, 2 * H, 1)>(vb); vf[10] = tr_read<v_rd_off(2, 2 * H + 1, 0)>(vb); vf[11] = tr_read<v_rd_off(2, 2 * H + 1, 1)>(vb);
;     vf[12] = tr_read<v_rd_off(3, 2 * H, 0)>(vb); vf[13] = tr_read<v_rd_off(3, 2 * H, 1)>(vb); vf[14] = tr_read<v_rd_off(3, 2 * H + 1, 0)>(vb); vf[15] = tr_read<v_rd_off(3, 2 * H + 1, 1)>(vb);
; }
; DI void pv_mma(f32x16* o, const s16x4* vf, bf16x8 pa0, bf16x8 pa1) {
;     ...
; #pragma unroll
;     for (int d0 = 0; d0 < 4; ++d0) {
;         o[d0] = __builtin_amdgcn_mfma_f32_32x32x16_bf16(pa0, ATT_PK(vf[4 * d0], vf[4 * d0 + 1]), o[d0], 0, 0, 0);
;         o[d0] = __builtin_amdgcn_mfma_f32_32x32x16_bf16(pa1, ATT_PK(vf[4 * d0 + 2], vf[4 * d0 + 3]), o[d0], 0, 0, 0); }
;     ...
; }
; template <int DQK, int MODE, int LDQ, int LDK, int LDV> ...
;     ...
;     f32x16 pA, pB; bf16x8 pa0, pa1;
;     int v0 = 0, v1 = 1, v2 = 2;
;     ATT_TOP(NKP + 2);
;     { bf16x8 kf[NDA]; k_reads<DQK, 0, NDA>(kf, lds, 0, r32, hi); ATT_LGKM0(); qk_mma<0, NDA>(pA, kf, qr);
;       if constexpr (ND0 > NDA) { bf16x8 kg[ND0 - NDA]; k_reads<DQK, NDA, ND0>(kg, lds, 0, r32, hi); ATT_LGKM0(); qk_mma<NDA, ND0>(pA, kg, qr); }
;       ATT_BIAS(pA, 0, 0); }
;     if (wid >= 4) __builtin_amdgcn_s_setprio(1);
;     for (int j = 0; j < NT; ++j) {
	v_mfma_f32_32x32x16_bf16 v[64:79], v[132:135], v[80:83], 0
	v_mfma_f32_32x32x16_bf16 v[64:79], v[136:139], v[84:87], v[64:79]
	v_mfma_f32_32x32x16_bf16 v[64:79], v[140:143], v[88:91], v[64:79]
	v_mfma_f32_32x32x16_bf16 v[64:79], v[162:165], v[92:95], v[64:79]
	v_mfma_f32_32x32x16_bf16 v[64:79], v[144:147], v[96:99], v[64:79]
	v_mfma_f32_32x32x16_bf16 v[64:79], v[148:151], v[100:103], v[64:79]
	s_waitcnt lgkmcnt(0)
	v_mfma_f32_32x32x16_bf16 v[64:79], v[198:201], v[104:107], v[64:79]
	v_mfma_f32_32x32x16_bf16 v[64:79], v[202:205], v[108:111], v[64:79]
	v_mfma_f32_32x32x16_bf16 v[64:79], v[152:155], v[112:115], v[64:79]
	v_mfma_f32_32x32x16_bf16 v[64:79], v[206:209], v[116:119], v[64:79]
	v_mfma_f32_32x32x16_bf16 v[64:79], v[156:159], v[120:123], v[64:79]
	v_mfma_f32_32x32x16_bf16 v[64:79], v[210:213], v[124:127], v[64:79]
	s_setprio 0
	ds_read_b64_tr_b16 v[80:81], v130 offset:0x2000
	ds_read_b64_tr_b16 v[82:83], v130 offset:0x2800
	ds_read_b64_tr_b16 v[84:85], v130 offset:0x3000
	ds_read_b64_tr_b16 v[86:87], v130 offset:0x3800
	ds_read_b64_tr_b16 v[88:89], v130 offset:0x2200
	ds_read_b64_tr_b16 v[90:91], v130 offset:0x2a00
	ds_read_b64_tr_b16 v[92:93], v130 offset:0x3200
	ds_read_b64_tr_b16 v[94:95], v130 offset:0x3a00
	ds_read_b64_tr_b16 v[96:97], v130 offset:0x2400
	ds_read_b64_tr_b16 v[98:99], v130 offset:0x2c00
	ds_read_b64_tr_b16 v[100:101], v130 offset:0x3400
	ds_read_b64_tr_b16 v[102:103], v130 offset:0x3c00
	ds_read_b64_tr_b16 v[104:105], v130 offset:0x2600
	ds_read_b64_tr_b16 v[106:107], v130 offset:0x2e00
	ds_read_b64_tr_b16 v[108:109], v130 offset:0x3600
	ds_read_b64_tr_b16 v[110:111], v130 offset:0x3e00
	s_nop 11
	v_exp_f32_e32 v112, v64
	v_exp_f32_e32 v65, v65
	v_exp_f32_e32 v113, v66
	v_exp_f32_e32 v67, v67
	v_exp_f32_e32 v68, v68
	v_exp_f32_e32 v69, v69
	v_add_f32_e32 v64, v65, v112
	v_exp_f32_e32 v70, v70
	v_add_f32_e32 v64, v113, v64
	v_exp_f32_e32 v71, v71
	v_add_f32_e32 v64, v67, v64
	v_exp_f32_e32 v72, v72
	v_add_f32_e32 v64, v68, v64
	v_exp_f32_e32 v73, v73
	v_add_f32_e32 v64, v69, v64
	v_exp_f32_e32 v74, v74
	v_add_f32_e32 v64, v70, v64
	v_exp_f32_e32 v75, v75
	v_add_f32_e32 v64, v71, v64
	v_exp_f32_e32 v76, v76
	v_add_f32_e32 v64, v72, v64
	v_exp_f32_e32 v77, v77
	v_add_f32_e32 v64, v73, v64
	v_exp_f32_e32 v78, v78
	v_add_f32_e32 v64, v74, v64
	v_exp_f32_e32 v79, v79
	v_add_f32_e32 v64, v75, v64
	v_add_f32_e32 v64, v76, v64
	v_add_f32_e32 v64, v77, v64
	v_add_f32_e32 v64, v78, v64
	v_add_f32_e32 v64, v79, v64
	v_add_f32_e32 v64, v161, v64
	s_setprio 2
	v_cvt_pk_bf16_f32 v66, v112, v65
	v_cvt_pk_bf16_f32 v67, v113, v67
	v_cvt_pk_bf16_f32 v68, v68, v69
	v_cvt_pk_bf16_f32 v69, v70, v71
	v_cvt_pk_bf16_f32 v70, v72, v73
	v_cvt_pk_bf16_f32 v71, v74, v75
	v_cvt_pk_bf16_f32 v72, v76, v77
	v_cvt_pk_bf16_f32 v73, v78, v79
	s_nop 0
	v_permlane32_swap_b32_e32 v66, v68
	v_permlane32_swap_b32_e32 v67, v69
	v_permlane32_swap_b32_e32 v70, v72
	v_permlane32_swap_b32_e32 v71, v73
	s_waitcnt lgkmcnt(0)
	s_setprio 1
	v_mfma_f32_32x32x16_bf16 v[48:63], v[66:69], v[80:83], v[48:63]
	v_mfma_f32_32x32x16_bf16 v[32:47], v[66:69], v[88:91], v[32:47]
	v_mfma_f32_32x32x16_bf16 v[16:31], v[66:69], v[96:99], v[16:31]
	v_mfma_f32_32x32x16_bf16 v[0:15], v[66:69], v[104:107], v[0:15]
	v_mfma_f32_32x32x16_bf16 v[48:63], v[70:73], v[84:87], v[48:63]
	v_mfma_f32_32x32x16_bf16 v[32:47], v[70:73], v[92:95], v[32:47]
	v_mfma_f32_32x32x16_bf16 v[16:31], v[70:73], v[100:103], v[16:31]
	v_mfma_f32_32x32x16_bf16 v[0:15], v[70:73], v[108:111], v[0:15]
	s_setprio 0
	v_mbcnt_lo_u32_b32 v66, -1, 0
	v_mbcnt_hi_u32_b32 v66, -1, v66
	v_mov_b32_e32 v67, v64
	v_and_b32_e32 v65, 31, v66
	v_bfe_u32 v66, v66, 5, 1
	v_permlane32_swap_b32_e32 v64, v67
	v_cmp_eq_u32_e32 vcc, 0, v66
	s_and_saveexec_b64 s[2:3], vcc
	s_cbranch_execz .LBB0_1910
	v_lshl_add_u32 v68, v65, 2, s4
	v_add_f32_e32 v64, v64, v67
	ds_write_b32 v68, v64
	s_branch .LBB0_1910
